# setprio-shift
# speedup vs baseline: 1.0169x; 1.0011x over previous
; #define PG8_STAGE(bufoff, gbase, voff) do { _Pragma("unroll") for (int _i = 0; _i < 2; ++_i) \
;         __builtin_amdgcn_global_load_lds((const unsigned*)((const char*)(gbase) + (voff)[_i]), (LAS unsigned*)(lds + (bufoff) + ldsw + _i * 8192), 16, 0, 0); } while (0)
; #define PG8_LDA(dst, b, h) do { _Pragma("unroll") for (int m = 0; m < 4; ++m) _Pragma("unroll") for (int k = 0; k < 2; ++k) dst[m][k] = *(const LAS bf16x8*)(lds + PG8_SA(b, h) + aoff + m * 2048 + k * 1024); } while (0)
; #define PG8_LDB(dst, b, h) do { _Pragma("unroll") for (int n = 0; n < 2; ++n) _Pragma("unroll") for (int k = 0; k < 2; ++k) dst[n][k] = *(const LAS bf16x8*)(lds + PG8_SB(b, h) + boff + n * 2048 + k * 1024); } while (0)
; #define PG8_MMA(ai, bj, At, Bt) do { __builtin_amdgcn_s_setprio(1); _Pragma("unroll") for (int m = 0; m < 4; ++m) _Pragma("unroll") for (int n = 0; n < 2; ++n) _Pragma("unroll") for (int k = 0; k < 2; ++k) \
;         acc[ai][bj][m][n] = __builtin_amdgcn_mfma_f32_16x16x32_bf16(Bt[n][k], At[m][k], acc[ai][bj][m][n], 0, 0, 0); __builtin_amdgcn_s_setprio(0); } while (0)
; #define PG8_WAIT_L(n) asm volatile("s_waitcnt lgkmcnt(" #n ")" ::: "memory")
; #define PG8_BAR __builtin_amdgcn_s_barrier()
; #define PG8_SCHED __builtin_amdgcn_sched_barrier(0)
; template <class Epi, class Sched, bool ATILE = false>
; __device__ __forceinline__ void gemm_phase(LAS unsigned char* lds, const Gemm g, const Sched& S, const Epi& E) {
;     ...
;         for (int t = 0; t < nt; t += 2) {
;             const bool last = (t == nt - 2);
;             const char* a1 = cA + (size_t)(t + 1) * kstepA;
;             const char* a2 = last ? nA : cA + (size_t)(t + 2) * kstepA; const char* b2 = last ? nB : cB + (size_t)(t + 2) * kstep;
;             const char* a3 = a2 + kstepA; const char* b3 = b2 + kstep;
;             PG8_LDB(B0, 0, 0); PG8_SCHED; PG8_LDA(At, 0, 0); PG8_STAGE(PG8_SA(1, 1), a1 + hstepA, voffA);
;             PG8_WAIT_L(8); PG8_BAR; PG8_WAIT_L(0); PG8_MMA(0, 0, At, B0); PG8_BAR; PG8_SCHED;
;             PG8_LDB(B1, 0, 1); PG8_STAGE(PG8_SB(0, 0), b2, voffB);
;             PG8_BAR; PG8_WAIT_L(0); PG8_MMA(0, 1, At, B1); PG8_BAR;
;             PG8_LDA(At, 0, 1); PG8_STAGE(PG8_SA(0, 0), a2, voffA);
;             PG8_BAR; PG8_WAIT_L(0); PG8_MMA(1, 0, At, B0); PG8_BAR; PG8_SCHED;
.LBB0_625:
	ds_read_b128 v[182:185], v139
	ds_read_b128 v[186:189], v139 offset:1024
	ds_read_b128 v[190:193], v139 offset:2048
	ds_read_b128 v[194:197], v139 offset:3072
	s_add_i32 s62, s28, 2
	s_add_u32 s29, s26, 0xfff80080
	s_addc_u32 s30, s27, -1
	s_cmp_eq_u32 s59, s28
	s_cselect_b32 s28, s58, s60
	s_cselect_b32 s31, s13, s30
	s_cselect_b32 s30, s56, s29
	s_cselect_b32 s29, s57, s61
	v_lshl_add_u64 v[230:231], s[26:27], 0, v[172:173]
	s_add_i32 m0, s35, 0xc000
	ds_read_b128 v[198:201], v163
	ds_read_b128 v[202:205], v163 offset:1024
	ds_read_b128 v[206:209], v163 offset:2048
	ds_read_b128 v[210:213], v163 offset:3072
	ds_read_b128 v[214:217], v163 offset:4096
	ds_read_b128 v[218:221], v163 offset:5120
	ds_read_b128 v[222:225], v163 offset:6144
	ds_read_b128 v[226:229], v163 offset:7168
	global_load_lds_dwordx4 v[230:231], off
	v_lshl_add_u64 v[230:231], s[26:27], 0, v[174:175]
	s_add_i32 m0, s35, 0xe000
	s_nop 0
	global_load_lds_dwordx4 v[230:231], off
	s_waitcnt lgkmcnt(8)
	s_setprio 1
	s_barrier
	s_waitcnt lgkmcnt(0)
	v_mfma_f32_16x16x32_bf16 v[120:123], v[182:185], v[198:201], v[120:123]
	v_mfma_f32_16x16x32_bf16 v[112:115], v[190:193], v[198:201], v[112:115]
	v_mfma_f32_16x16x32_bf16 v[104:107], v[182:185], v[206:209], v[104:107]
	v_mfma_f32_16x16x32_bf16 v[96:99], v[190:193], v[206:209], v[96:99]
	v_mfma_f32_16x16x32_bf16 v[88:91], v[182:185], v[214:217], v[88:91]
	v_mfma_f32_16x16x32_bf16 v[80:83], v[190:193], v[214:217], v[80:83]
	v_mfma_f32_16x16x32_bf16 v[72:75], v[182:185], v[222:225], v[72:75]
	v_mfma_f32_16x16x32_bf16 v[64:67], v[190:193], v[222:225], v[64:67]
	v_mfma_f32_16x16x32_bf16 v[120:123], v[186:189], v[202:205], v[120:123]
	v_mfma_f32_16x16x32_bf16 v[112:115], v[194:197], v[202:205], v[112:115]
	v_mfma_f32_16x16x32_bf16 v[104:107], v[186:189], v[210:213], v[104:107]
	v_mfma_f32_16x16x32_bf16 v[96:99], v[194:197], v[210:213], v[96:99]
	v_mfma_f32_16x16x32_bf16 v[88:91], v[186:189], v[218:221], v[88:91]
	v_mfma_f32_16x16x32_bf16 v[80:83], v[194:197], v[218:221], v[80:83]
	v_mfma_f32_16x16x32_bf16 v[72:75], v[186:189], v[226:229], v[72:75]
	v_mfma_f32_16x16x32_bf16 v[64:67], v[194:197], v[226:229], v[64:67]
	s_barrier
	s_setprio 0
	s_add_i32 s63, s53, s34
	v_lshl_add_u64 v[246:247], s[28:29], 0, v[130:131]
	s_mov_b32 m0, s63
	ds_read_b128 v[230:233], v167
	ds_read_b128 v[234:237], v167 offset:1024
	ds_read_b128 v[238:241], v167 offset:2048
	ds_read_b128 v[242:245], v167 offset:3072
	global_load_lds_dwordx4 v[246:247], off
	v_lshl_add_u64 v[248:249], s[28:29], 0, v[134:135]
	s_add_i32 m0, s63, 0x2000
	s_nop 0
	global_load_lds_dwordx4 v[248:249], off
	s_setprio 1
	s_barrier
	s_waitcnt lgkmcnt(0)
	v_mfma_f32_16x16x32_bf16 v[124:127], v[230:233], v[198:201], v[124:127]
	v_mfma_f32_16x16x32_bf16 v[116:119], v[238:241], v[198:201], v[116:119]
	v_mfma_f32_16x16x32_bf16 v[108:111], v[230:233], v[206:209], v[108:111]
	v_mfma_f32_16x16x32_bf16 v[100:103], v[238:241], v[206:209], v[100:103]
	v_mfma_f32_16x16x32_bf16 v[92:95], v[230:233], v[214:217], v[92:95]
	v_mfma_f32_16x16x32_bf16 v[84:87], v[238:241], v[214:217], v[84:87]
	v_mfma_f32_16x16x32_bf16 v[76:79], v[230:233], v[222:225], v[76:79]
	v_mfma_f32_16x16x32_bf16 v[68:71], v[238:241], v[222:225], v[68:71]
	v_mfma_f32_16x16x32_bf16 v[124:127], v[234:237], v[202:205], v[124:127]
	v_mfma_f32_16x16x32_bf16 v[116:119], v[242:245], v[202:205], v[116:119]
	v_mfma_f32_16x16x32_bf16 v[108:111], v[234:237], v[210:213], v[108:111]
	v_mfma_f32_16x16x32_bf16 v[100:103], v[242:245], v[210:213], v[100:103]
	v_mfma_f32_16x16x32_bf16 v[92:95], v[234:237], v[218:221], v[92:95]
	v_mfma_f32_16x16x32_bf16 v[84:87], v[242:245], v[218:221], v[84:87]
	v_mfma_f32_16x16x32_bf16 v[76:79], v[234:237], v[226:229], v[76:79]
	v_mfma_f32_16x16x32_bf16 v[68:71], v[242:245], v[226:229], v[68:71]
	s_barrier
	s_setprio 0
	s_mov_b32 m0, s35
	v_lshl_add_u64 v[250:251], s[30:31], 0, v[128:129]
	ds_read_b128 v[198:201], v163 offset:16384
	ds_read_b128 v[202:205], v163 offset:17408
	ds_read_b128 v[206:209], v163 offset:18432
	ds_read_b128 v[210:213], v163 offset:19456
	ds_read_b128 v[214:217], v163 offset:20480
	ds_read_b128 v[218:221], v163 offset:21504
	ds_read_b128 v[222:225], v163 offset:22528
	ds_read_b128 v[226:229], v163 offset:23552
	global_load_lds_dwordx4 v[250:251], off
	v_lshl_add_u64 v[252:253], s[30:31], 0, v[132:133]
	s_mov_b32 m0, s36
	s_nop 0
	global_load_lds_dwordx4 v[252:253], off
	s_setprio 1
	s_barrier
	s_waitcnt lgkmcnt(0)
	v_mfma_f32_16x16x32_bf16 v[56:59], v[182:185], v[198:201], v[56:59]
	v_mfma_f32_16x16x32_bf16 v[48:51], v[190:193], v[198:201], v[48:51]
	v_mfma_f32_16x16x32_bf16 v[40:43], v[182:185], v[206:209], v[40:43]
	v_mfma_f32_16x16x32_bf16 v[32:35], v[190:193], v[206:209], v[32:35]
	v_mfma_f32_16x16x32_bf16 v[24:27], v[182:185], v[214:217], v[24:27]
	v_mfma_f32_16x16x32_bf16 v[16:19], v[190:193], v[214:217], v[16:19]
	v_mfma_f32_16x16x32_bf16 v[8:11], v[182:185], v[222:225], v[8:11]
	v_mfma_f32_16x16x32_bf16 v[4:7], v[190:193], v[222:225], v[4:7]
	v_mfma_f32_16x16x32_bf16 v[56:59], v[186:189], v[202:205], v[56:59]
	v_mfma_f32_16x16x32_bf16 v[48:51], v[194:197], v[202:205], v[48:51]
	v_mfma_f32_16x16x32_bf16 v[40:43], v[186:189], v[210:213], v[40:43]
	v_mfma_f32_16x16x32_bf16 v[32:35], v[194:197], v[210:213], v[32:35]
	v_mfma_f32_16x16x32_bf16 v[24:27], v[186:189], v[218:221], v[24:27]
	v_mfma_f32_16x16x32_bf16 v[16:19], v[194:197], v[218:221], v[16:19]
	v_mfma_f32_16x16x32_bf16 v[8:11], v[186:189], v[226:229], v[8:11]
	v_mfma_f32_16x16x32_bf16 v[4:7], v[194:197], v[226:229], v[4:7]
	s_barrier
; #define PG8_STAGE(bufoff, gbase, voff) do { _Pragma("unroll") for (int _i = 0; _i < 2; ++_i) \
;         __builtin_amdgcn_global_load_lds((const unsigned*)((const char*)(gbase) + (voff)[_i]), (LAS unsigned*)(lds + (bufoff) + ldsw + _i * 8192), 16, 0, 0); } while (0)
; #define PG8_LDA(dst, b, h) do { _Pragma("unroll") for (int m = 0; m < 4; ++m) _Pragma("unroll") for (int k = 0; k < 2; ++k) dst[m][k] = *(const LAS bf16x8*)(lds + PG8_SA(b, h) + aoff + m * 2048 + k * 1024); } while (0)
; #define PG8_LDB(dst, b, h) do { _Pragma("unroll") for (int n = 0; n < 2; ++n) _Pragma("unroll") for (int k = 0; k < 2; ++k) dst[n][k] = *(const LAS bf16x8*)(lds + PG8_SB(b, h) + boff + n * 2048 + k * 1024); } while (0)
; #define PG8_MMA(ai, bj, At, Bt) do { __builtin_amdgcn_s_setprio(1); _Pragma("unroll") for (int m = 0; m < 4; ++m) _Pragma("unroll") for (int n = 0; n < 2; ++n) _Pragma("unroll") for (int k = 0; k < 2; ++k) \
;         acc[ai][bj][m][n] = __builtin_amdgcn_mfma_f32_16x16x32_bf16(Bt[n][k], At[m][k], acc[ai][bj][m][n], 0, 0, 0); __builtin_amdgcn_s_setprio(0); } while (0)
; #define PG8_WAIT_V(n) asm volatile("s_waitcnt vmcnt(" #n ")" ::: "memory")
; #define PG8_WAIT_L(n) asm volatile("s_waitcnt lgkmcnt(" #n ")" ::: "memory")
; #define PG8_BAR __builtin_amdgcn_s_barrier()
; #define PG8_SCHED __builtin_amdgcn_sched_barrier(0)
; template <class Epi, class Sched, bool ATILE = false>
; __device__ __forceinline__ void gemm_phase(LAS unsigned char* lds, const Gemm g, const Sched& S, const Epi& E) {
;     ...
;             PG8_BAR; PG8_WAIT_L(0); PG8_MMA(1, 0, At, B0); PG8_BAR; PG8_SCHED;
;             PG8_STAGE(PG8_SB(0, 1), b2 + hstepB, voffB);
;             PG8_WAIT_V(6); PG8_BAR; PG8_MMA(1, 1, At, B1); PG8_BAR;
;             PG8_LDB(B0, 1, 0); PG8_SCHED; PG8_LDA(At, 1, 0); PG8_STAGE(PG8_SA(0, 1), a2 + hstepA, voffA);
;             PG8_WAIT_L(8); PG8_BAR; PG8_WAIT_L(0); PG8_MMA(0, 0, At, B0); PG8_BAR; PG8_SCHED;
;             PG8_LDB(B1, 1, 1); PG8_STAGE(PG8_SB(1, 0), b3, voffB);
;             PG8_BAR; PG8_WAIT_L(0); PG8_MMA(0, 1, At, B1); PG8_BAR;
	s_setprio 0
	s_add_u32 s64, s28, 0x80000
	s_addc_u32 s65, s29, 0
	s_add_i32 s63, s54, s34
	v_lshl_add_u64 v[182:183], s[64:65], 0, v[130:131]
	s_mov_b32 m0, s63
	s_nop 0
	global_load_lds_dwordx4 v[182:183], off
	v_lshl_add_u64 v[182:183], s[64:65], 0, v[134:135]
	s_add_i32 m0, s63, 0x2000
	s_nop 0
	global_load_lds_dwordx4 v[182:183], off
	s_waitcnt vmcnt(6)
	s_setprio 1
	s_barrier
	v_mfma_f32_16x16x32_bf16 v[60:63], v[230:233], v[198:201], v[60:63]
	v_mfma_f32_16x16x32_bf16 v[52:55], v[238:241], v[198:201], v[52:55]
	v_mfma_f32_16x16x32_bf16 v[44:47], v[230:233], v[206:209], v[44:47]
	v_mfma_f32_16x16x32_bf16 v[36:39], v[238:241], v[206:209], v[36:39]
	v_mfma_f32_16x16x32_bf16 v[28:31], v[230:233], v[214:217], v[28:31]
	v_mfma_f32_16x16x32_bf16 v[20:23], v[238:241], v[214:217], v[20:23]
	v_mfma_f32_16x16x32_bf16 v[12:15], v[230:233], v[222:225], v[12:15]
	v_mfma_f32_16x16x32_bf16 v[0:3], v[238:241], v[222:225], v[0:3]
	v_mfma_f32_16x16x32_bf16 v[60:63], v[234:237], v[202:205], v[60:63]
	v_mfma_f32_16x16x32_bf16 v[52:55], v[242:245], v[202:205], v[52:55]
	v_mfma_f32_16x16x32_bf16 v[44:47], v[234:237], v[210:213], v[44:47]
	v_mfma_f32_16x16x32_bf16 v[36:39], v[242:245], v[210:213], v[36:39]
	v_mfma_f32_16x16x32_bf16 v[28:31], v[234:237], v[218:221], v[28:31]
	v_mfma_f32_16x16x32_bf16 v[20:23], v[242:245], v[218:221], v[20:23]
	v_mfma_f32_16x16x32_bf16 v[12:15], v[234:237], v[226:229], v[12:15]
	v_mfma_f32_16x16x32_bf16 v[0:3], v[242:245], v[226:229], v[0:3]
	s_barrier
	s_setprio 0
	s_add_i32 s63, 0, 0x18000
	v_add_u32_e32 v176, s63, v161
	ds_read_b128 v[182:185], v176
	ds_read_b128 v[186:189], v176 offset:1024
	ds_read_b128 v[190:193], v176 offset:2048
	ds_read_b128 v[194:197], v176 offset:3072
	s_add_u32 s30, s30, 0x80000
	s_addc_u32 s31, s31, 0
	s_mov_b32 m0, s37
	v_lshl_add_u64 v[230:231], s[30:31], 0, v[128:129]
	ds_read_b128 v[198:201], v163 offset:32768
	ds_read_b128 v[202:205], v163 offset:33792
	ds_read_b128 v[206:209], v163 offset:34816
	ds_read_b128 v[210:213], v163 offset:35840
	ds_read_b128 v[214:217], v163 offset:36864
	ds_read_b128 v[218:221], v163 offset:37888
	ds_read_b128 v[222:225], v163 offset:38912
	ds_read_b128 v[226:229], v163 offset:39936
	global_load_lds_dwordx4 v[230:231], off
	v_lshl_add_u64 v[230:231], s[30:31], 0, v[132:133]
	s_mov_b32 m0, s38
	s_nop 0
	global_load_lds_dwordx4 v[230:231], off
	s_waitcnt lgkmcnt(8)
	s_setprio 1
	s_barrier
	s_waitcnt lgkmcnt(0)
	v_mfma_f32_16x16x32_bf16 v[120:123], v[182:185], v[198:201], v[120:123]
	v_mfma_f32_16x16x32_bf16 v[112:115], v[190:193], v[198:201], v[112:115]
	v_mfma_f32_16x16x32_bf16 v[104:107], v[182:185], v[206:209], v[104:107]
	v_mfma_f32_16x16x32_bf16 v[96:99], v[190:193], v[206:209], v[96:99]
	v_mfma_f32_16x16x32_bf16 v[88:91], v[182:185], v[214:217], v[88:91]
	v_mfma_f32_16x16x32_bf16 v[80:83], v[190:193], v[214:217], v[80:83]
	v_mfma_f32_16x16x32_bf16 v[72:75], v[182:185], v[222:225], v[72:75]
	v_mfma_f32_16x16x32_bf16 v[64:67], v[190:193], v[222:225], v[64:67]
	v_mfma_f32_16x16x32_bf16 v[120:123], v[186:189], v[202:205], v[120:123]
	v_mfma_f32_16x16x32_bf16 v[112:115], v[194:197], v[202:205], v[112:115]
	v_mfma_f32_16x16x32_bf16 v[104:107], v[186:189], v[210:213], v[104:107]
	v_mfma_f32_16x16x32_bf16 v[96:99], v[194:197], v[210:213], v[96:99]
	v_mfma_f32_16x16x32_bf16 v[88:91], v[186:189], v[218:221], v[88:91]
	v_mfma_f32_16x16x32_bf16 v[80:83], v[194:197], v[218:221], v[80:83]
	v_mfma_f32_16x16x32_bf16 v[72:75], v[186:189], v[226:229], v[72:75]
	v_mfma_f32_16x16x32_bf16 v[64:67], v[194:197], v[226:229], v[64:67]
	s_barrier
	s_setprio 0
	s_add_i32 s30, 0, 0x1c000
	s_add_i32 s31, s63, s34
	v_add_u32_e32 v176, s30, v161
	v_lshl_add_u64 v[246:247], v[246:247], 0, s[0:1]
	s_mov_b32 m0, s31
	ds_read_b128 v[230:233], v176
	ds_read_b128 v[234:237], v176 offset:1024
	ds_read_b128 v[238:241], v176 offset:2048
	ds_read_b128 v[242:245], v176 offset:3072
	global_load_lds_dwordx4 v[246:247], off
	v_lshl_add_u64 v[246:247], v[248:249], 0, s[0:1]
	s_add_i32 m0, s31, 0x2000
	s_nop 0
	global_load_lds_dwordx4 v[246:247], off
	s_setprio 1
	s_barrier
; #define PG8_STAGE(bufoff, gbase, voff) do { _Pragma("unroll") for (int _i = 0; _i < 2; ++_i) \
;         __builtin_amdgcn_global_load_lds((const unsigned*)((const char*)(gbase) + (voff)[_i]), (LAS unsigned*)(lds + (bufoff) + ldsw + _i * 8192), 16, 0, 0); } while (0)
; #define PG8_LDA(dst, b, h) do { _Pragma("unroll") for (int m = 0; m < 4; ++m) _Pragma("unroll") for (int k = 0; k < 2; ++k) dst[m][k] = *(const LAS bf16x8*)(lds + PG8_SA(b, h) + aoff + m * 2048 + k * 1024); } while (0)
; #define PG8_MMA(ai, bj, At, Bt) do { __builtin_amdgcn_s_setprio(1); _Pragma("unroll") for (int m = 0; m < 4; ++m) _Pragma("unroll") for (int n = 0; n < 2; ++n) _Pragma("unroll") for (int k = 0; k < 2; ++k) \
;         acc[ai][bj][m][n] = __builtin_amdgcn_mfma_f32_16x16x32_bf16(Bt[n][k], At[m][k], acc[ai][bj][m][n], 0, 0, 0); __builtin_amdgcn_s_setprio(0); } while (0)
; #define PG8_WAIT_V(n) asm volatile("s_waitcnt vmcnt(" #n ")" ::: "memory")
; #define PG8_WAIT_L(n) asm volatile("s_waitcnt lgkmcnt(" #n ")" ::: "memory")
; #define PG8_BAR __builtin_amdgcn_s_barrier()
; #define PG8_SCHED __builtin_amdgcn_sched_barrier(0)
; template <class Epi, class Sched, bool ATILE = false>
; __device__ __forceinline__ void gemm_phase(LAS unsigned char* lds, const Gemm g, const Sched& S, const Epi& E) {
;     ...
;             PG8_BAR; PG8_WAIT_L(0); PG8_MMA(0, 1, At, B1); PG8_BAR;
;             PG8_LDA(At, 1, 1); PG8_STAGE(PG8_SA(1, 0), a3, voffA);
;             PG8_BAR; PG8_WAIT_L(0); PG8_MMA(1, 0, At, B0); PG8_BAR; PG8_SCHED;
;             PG8_STAGE(PG8_SB(1, 1), b3 + hstepB, voffB);
;             PG8_WAIT_V(6); PG8_BAR; PG8_MMA(1, 1, At, B1); PG8_BAR;
	s_waitcnt lgkmcnt(0)
	v_mfma_f32_16x16x32_bf16 v[124:127], v[230:233], v[198:201], v[124:127]
	v_mfma_f32_16x16x32_bf16 v[116:119], v[238:241], v[198:201], v[116:119]
	v_mfma_f32_16x16x32_bf16 v[108:111], v[230:233], v[206:209], v[108:111]
	v_mfma_f32_16x16x32_bf16 v[100:103], v[238:241], v[206:209], v[100:103]
	v_mfma_f32_16x16x32_bf16 v[92:95], v[230:233], v[214:217], v[92:95]
	v_mfma_f32_16x16x32_bf16 v[84:87], v[238:241], v[214:217], v[84:87]
	v_mfma_f32_16x16x32_bf16 v[76:79], v[230:233], v[222:225], v[76:79]
	v_mfma_f32_16x16x32_bf16 v[68:71], v[238:241], v[222:225], v[68:71]
	v_mfma_f32_16x16x32_bf16 v[124:127], v[234:237], v[202:205], v[124:127]
	v_mfma_f32_16x16x32_bf16 v[116:119], v[242:245], v[202:205], v[116:119]
	v_mfma_f32_16x16x32_bf16 v[108:111], v[234:237], v[210:213], v[108:111]
	v_mfma_f32_16x16x32_bf16 v[100:103], v[242:245], v[210:213], v[100:103]
	v_mfma_f32_16x16x32_bf16 v[92:95], v[234:237], v[218:221], v[92:95]
	v_mfma_f32_16x16x32_bf16 v[84:87], v[242:245], v[218:221], v[84:87]
	v_mfma_f32_16x16x32_bf16 v[76:79], v[234:237], v[226:229], v[76:79]
	v_mfma_f32_16x16x32_bf16 v[68:71], v[242:245], v[226:229], v[68:71]
	s_barrier
	s_setprio 0
	s_mov_b32 m0, s41
	v_lshl_add_u64 v[246:247], v[250:251], 0, s[0:1]
	ds_read_b128 v[198:201], v163 offset:49152
	ds_read_b128 v[202:205], v163 offset:50176
	ds_read_b128 v[206:209], v163 offset:51200
	ds_read_b128 v[210:213], v163 offset:52224
	ds_read_b128 v[214:217], v163 offset:53248
	ds_read_b128 v[218:221], v163 offset:54272
	ds_read_b128 v[222:225], v163 offset:55296
	ds_read_b128 v[226:229], v163 offset:56320
	global_load_lds_dwordx4 v[246:247], off
	v_lshl_add_u64 v[246:247], v[252:253], 0, s[0:1]
	s_mov_b32 m0, s42
	s_nop 0
	global_load_lds_dwordx4 v[246:247], off
	s_setprio 1
	s_barrier
	s_waitcnt lgkmcnt(0)
	v_mfma_f32_16x16x32_bf16 v[56:59], v[182:185], v[198:201], v[56:59]
	v_mfma_f32_16x16x32_bf16 v[48:51], v[190:193], v[198:201], v[48:51]
	v_mfma_f32_16x16x32_bf16 v[40:43], v[182:185], v[206:209], v[40:43]
	v_mfma_f32_16x16x32_bf16 v[32:35], v[190:193], v[206:209], v[32:35]
	v_mfma_f32_16x16x32_bf16 v[24:27], v[182:185], v[214:217], v[24:27]
	v_mfma_f32_16x16x32_bf16 v[16:19], v[190:193], v[214:217], v[16:19]
	v_mfma_f32_16x16x32_bf16 v[8:11], v[182:185], v[222:225], v[8:11]
	v_mfma_f32_16x16x32_bf16 v[4:7], v[190:193], v[222:225], v[4:7]
	v_mfma_f32_16x16x32_bf16 v[56:59], v[186:189], v[202:205], v[56:59]
	v_mfma_f32_16x16x32_bf16 v[48:51], v[194:197], v[202:205], v[48:51]
	v_mfma_f32_16x16x32_bf16 v[40:43], v[186:189], v[210:213], v[40:43]
	v_mfma_f32_16x16x32_bf16 v[32:35], v[194:197], v[210:213], v[32:35]
	v_mfma_f32_16x16x32_bf16 v[24:27], v[186:189], v[218:221], v[24:27]
	v_mfma_f32_16x16x32_bf16 v[16:19], v[194:197], v[218:221], v[16:19]
	v_mfma_f32_16x16x32_bf16 v[8:11], v[186:189], v[226:229], v[8:11]
	v_mfma_f32_16x16x32_bf16 v[4:7], v[194:197], v[226:229], v[4:7]
	s_barrier
	s_setprio 0
	s_add_u32 s28, s28, 0x80080
	s_addc_u32 s29, s29, 0
	s_add_i32 s30, s30, s34
	v_lshl_add_u64 v[182:183], s[28:29], 0, v[130:131]
	s_mov_b32 m0, s30
	s_nop 0
	global_load_lds_dwordx4 v[182:183], off
	v_lshl_add_u64 v[182:183], s[28:29], 0, v[134:135]
	s_add_i32 m0, s30, 0x2000
	s_nop 0
	global_load_lds_dwordx4 v[182:183], off
	s_waitcnt vmcnt(6)
	s_setprio 1
	s_barrier
	v_mfma_f32_16x16x32_bf16 v[60:63], v[230:233], v[198:201], v[60:63]
	v_mfma_f32_16x16x32_bf16 v[52:55], v[238:241], v[198:201], v[52:55]
	v_mfma_f32_16x16x32_bf16 v[44:47], v[230:233], v[206:209], v[44:47]
	v_mfma_f32_16x16x32_bf16 v[36:39], v[238:241], v[206:209], v[36:39]
	v_mfma_f32_16x16x32_bf16 v[28:31], v[230:233], v[214:217], v[28:31]
	v_mfma_f32_16x16x32_bf16 v[20:23], v[238:241], v[214:217], v[20:23]
	v_mfma_f32_16x16x32_bf16 v[12:15], v[230:233], v[222:225], v[12:15]
	v_mfma_f32_16x16x32_bf16 v[0:3], v[238:241], v[222:225], v[0:3]
	v_mfma_f32_16x16x32_bf16 v[60:63], v[234:237], v[202:205], v[60:63]
	v_mfma_f32_16x16x32_bf16 v[52:55], v[242:245], v[202:205], v[52:55]
	v_mfma_f32_16x16x32_bf16 v[44:47], v[234:237], v[210:213], v[44:47]
	v_mfma_f32_16x16x32_bf16 v[36:39], v[242:245], v[210:213], v[36:39]
	v_mfma_f32_16x16x32_bf16 v[28:31], v[234:237], v[218:221], v[28:31]
	v_mfma_f32_16x16x32_bf16 v[20:23], v[242:245], v[218:221], v[20:23]
	v_mfma_f32_16x16x32_bf16 v[12:15], v[234:237], v[226:229], v[12:15]
	v_mfma_f32_16x16x32_bf16 v[0:3], v[242:245], v[226:229], v[0:3]
	s_barrier
	s_setprio 0
	s_add_u32 s26, s26, 0x100
	s_addc_u32 s27, s27, 0
	s_add_u32 s60, s60, 0x100
	s_addc_u32 s61, s61, 0
	s_cmp_ge_i32 s62, s11
	s_mov_b32 s28, s62
	s_cbranch_scc0 .LBB0_625
	s_branch .LBB0_616

; #define PG8_STAGE(bufoff, gbase, voff) do { _Pragma("unroll") for (int _i = 0; _i < 2; ++_i) \
;         __builtin_amdgcn_global_load_lds((const unsigned*)((const char*)(gbase) + (voff)[_i]), (LAS unsigned*)(lds + (bufoff) + ldsw + _i * 8192), 16, 0, 0); } while (0)
; #define PG8_LDA(dst, b, h) do { _Pragma("unroll") for (int m = 0; m < 4; ++m) _Pragma("unroll") for (int k = 0; k < 2; ++k) dst[m][k] = *(const LAS bf16x8*)(lds + PG8_SA(b, h) + aoff + m * 2048 + k * 1024); } while (0)
; #define PG8_LDB(dst, b, h) do { _Pragma("unroll") for (int n = 0; n < 2; ++n) _Pragma("unroll") for (int k = 0; k < 2; ++k) dst[n][k] = *(const LAS bf16x8*)(lds + PG8_SB(b, h) + boff + n * 2048 + k * 1024); } while (0)
; #define PG8_MMA(ai, bj, At, Bt) do { __builtin_amdgcn_s_setprio(1); _Pragma("unroll") for (int m = 0; m < 4; ++m) _Pragma("unroll") for (int n = 0; n < 2; ++n) _Pragma("unroll") for (int k = 0; k < 2; ++k) \
;         acc[ai][bj][m][n] = __builtin_amdgcn_mfma_f32_16x16x32_bf16(Bt[n][k], At[m][k], acc[ai][bj][m][n], 0, 0, 0); __builtin_amdgcn_s_setprio(0); } while (0)
; #define PG8_WAIT_L(n) asm volatile("s_waitcnt lgkmcnt(" #n ")" ::: "memory")
; #define PG8_BAR __builtin_amdgcn_s_barrier()
; #define PG8_SCHED __builtin_amdgcn_sched_barrier(0)
; template <class Epi, class Sched, bool ATILE = false>
; __device__ __forceinline__ void gemm_phase(LAS unsigned char* lds, const Gemm g, const Sched& S, const Epi& E) {
;     ...
;         for (int t = 0; t < nt; t += 2) {
;             const bool last = (t == nt - 2);
;             const char* a1 = cA + (size_t)(t + 1) * kstepA;
;             const char* a2 = last ? nA : cA + (size_t)(t + 2) * kstepA; const char* b2 = last ? nB : cB + (size_t)(t + 2) * kstep;
;             const char* a3 = a2 + kstepA; const char* b3 = b2 + kstep;
;             PG8_LDB(B0, 0, 0); PG8_SCHED; PG8_LDA(At, 0, 0); PG8_STAGE(PG8_SA(1, 1), a1 + hstepA, voffA);
;             PG8_WAIT_L(8); PG8_BAR; PG8_WAIT_L(0); PG8_MMA(0, 0, At, B0); PG8_BAR; PG8_SCHED;
;             PG8_LDB(B1, 0, 1); PG8_STAGE(PG8_SB(0, 0), b2, voffB);
;             PG8_BAR; PG8_WAIT_L(0); PG8_MMA(0, 1, At, B1); PG8_BAR;
;             PG8_LDA(At, 0, 1); PG8_STAGE(PG8_SA(0, 0), a2, voffA);
;             PG8_BAR; PG8_WAIT_L(0); PG8_MMA(1, 0, At, B0); PG8_BAR; PG8_SCHED;
.LBB0_739:
	ds_read_b128 v[20:23], v165
	ds_read_b128 v[28:31], v165 offset:1024
	ds_read_b128 v[136:139], v165 offset:2048
	ds_read_b128 v[140:143], v165 offset:3072
	s_add_i32 s62, s26, 2
	s_add_u32 s27, s24, 0x4000
	s_addc_u32 s28, s25, 0
	s_cmp_eq_u32 s11, s26
	s_cselect_b32 s30, s20, s27
	s_cselect_b32 s31, s21, s28
	s_cselect_b32 s26, s22, s60
	s_cselect_b32 s27, s23, s61
	s_add_u32 s28, s30, 0x8000
	s_addc_u32 s29, s31, 0
	v_lshl_add_u64 v[216:217], s[24:25], 0, v[194:195]
	s_add_i32 m0, s34, 0xc000
	ds_read_b128 v[144:147], v167
	ds_read_b128 v[148:151], v167 offset:1024
	ds_read_b128 v[200:203], v167 offset:2048
	ds_read_b128 v[204:207], v167 offset:3072
	ds_read_b128 v[208:211], v167 offset:4096
	ds_read_b128 v[212:215], v167 offset:5120
	ds_read_b128 v[220:223], v167 offset:6144
	ds_read_b128 v[224:227], v167 offset:7168
	global_load_lds_dwordx4 v[216:217], off
	v_lshl_add_u64 v[216:217], s[24:25], 0, v[196:197]
	s_add_i32 m0, s34, 0xe000
	s_nop 0
	global_load_lds_dwordx4 v[216:217], off
	s_waitcnt lgkmcnt(8)
	s_setprio 1
	s_barrier
	s_waitcnt lgkmcnt(0)
	v_mfma_f32_16x16x32_bf16 v[0:3], v[20:23], v[144:147], v[0:3]
	v_mfma_f32_16x16x32_bf16 v[4:7], v[136:139], v[144:147], v[4:7]
	v_mfma_f32_16x16x32_bf16 v[44:47], v[20:23], v[200:203], v[44:47]
	v_mfma_f32_16x16x32_bf16 v[36:39], v[136:139], v[200:203], v[36:39]
	v_mfma_f32_16x16x32_bf16 v[52:55], v[20:23], v[208:211], v[52:55]
	v_mfma_f32_16x16x32_bf16 v[48:51], v[136:139], v[208:211], v[48:51]
	v_mfma_f32_16x16x32_bf16 v[92:95], v[20:23], v[220:223], v[92:95]
	v_mfma_f32_16x16x32_bf16 v[84:87], v[136:139], v[220:223], v[84:87]
	v_mfma_f32_16x16x32_bf16 v[0:3], v[28:31], v[148:151], v[0:3]
	v_mfma_f32_16x16x32_bf16 v[4:7], v[140:143], v[148:151], v[4:7]
	v_mfma_f32_16x16x32_bf16 v[44:47], v[28:31], v[204:207], v[44:47]
	v_mfma_f32_16x16x32_bf16 v[36:39], v[140:143], v[204:207], v[36:39]
	v_mfma_f32_16x16x32_bf16 v[52:55], v[28:31], v[212:215], v[52:55]
	v_mfma_f32_16x16x32_bf16 v[48:51], v[140:143], v[212:215], v[48:51]
	v_mfma_f32_16x16x32_bf16 v[92:95], v[28:31], v[224:227], v[92:95]
	v_mfma_f32_16x16x32_bf16 v[84:87], v[140:143], v[224:227], v[84:87]
	s_barrier
	s_setprio 0
	s_add_i32 s63, s52, s33
	v_lshl_add_u64 v[216:217], s[26:27], 0, v[170:171]
	s_mov_b32 m0, s63
	ds_read_b128 v[228:231], v177
	ds_read_b128 v[232:235], v177 offset:1024
	ds_read_b128 v[236:239], v177 offset:2048
	ds_read_b128 v[240:243], v177 offset:3072
	global_load_lds_dwordx4 v[216:217], off
	v_lshl_add_u64 v[244:245], s[26:27], 0, v[174:175]
	s_add_i32 m0, s63, 0x2000
	s_nop 0
	global_load_lds_dwordx4 v[244:245], off
	s_setprio 1
	s_barrier
	s_waitcnt lgkmcnt(0)
	v_mfma_f32_16x16x32_bf16 v[12:15], v[228:231], v[144:147], v[12:15]
	v_mfma_f32_16x16x32_bf16 v[8:11], v[236:239], v[144:147], v[8:11]
	v_mfma_f32_16x16x32_bf16 v[24:27], v[228:231], v[200:203], v[24:27]
	v_mfma_f32_16x16x32_bf16 v[16:19], v[236:239], v[200:203], v[16:19]
	v_mfma_f32_16x16x32_bf16 v[40:43], v[228:231], v[208:211], v[40:43]
	v_mfma_f32_16x16x32_bf16 v[32:35], v[236:239], v[208:211], v[32:35]
	v_mfma_f32_16x16x32_bf16 v[56:59], v[228:231], v[220:223], v[56:59]
	v_mfma_f32_16x16x32_bf16 v[60:63], v[236:239], v[220:223], v[60:63]
	v_mfma_f32_16x16x32_bf16 v[12:15], v[232:235], v[148:151], v[12:15]
	v_mfma_f32_16x16x32_bf16 v[8:11], v[240:243], v[148:151], v[8:11]
	v_mfma_f32_16x16x32_bf16 v[24:27], v[232:235], v[204:207], v[24:27]
	v_mfma_f32_16x16x32_bf16 v[16:19], v[240:243], v[204:207], v[16:19]
	v_mfma_f32_16x16x32_bf16 v[40:43], v[232:235], v[212:215], v[40:43]
	v_mfma_f32_16x16x32_bf16 v[32:35], v[240:243], v[212:215], v[32:35]
	v_mfma_f32_16x16x32_bf16 v[56:59], v[232:235], v[224:227], v[56:59]
	v_mfma_f32_16x16x32_bf16 v[60:63], v[240:243], v[224:227], v[60:63]
	s_barrier
	s_setprio 0
	s_mov_b32 m0, s34
	v_lshl_add_u64 v[246:247], s[30:31], 0, v[168:169]
	ds_read_b128 v[144:147], v167 offset:16384
	ds_read_b128 v[148:151], v167 offset:17408
	ds_read_b128 v[200:203], v167 offset:18432
	ds_read_b128 v[204:207], v167 offset:19456
	ds_read_b128 v[208:211], v167 offset:20480
	ds_read_b128 v[212:215], v167 offset:21504
	ds_read_b128 v[220:223], v167 offset:22528
	ds_read_b128 v[224:227], v167 offset:23552
	global_load_lds_dwordx4 v[246:247], off
	v_lshl_add_u64 v[246:247], s[30:31], 0, v[172:173]
	s_mov_b32 m0, s35
	s_nop 0
	global_load_lds_dwordx4 v[246:247], off
	s_setprio 1
	s_barrier
	s_waitcnt lgkmcnt(0)
	v_mfma_f32_16x16x32_bf16 v[64:67], v[20:23], v[144:147], v[64:67]
	v_mfma_f32_16x16x32_bf16 v[68:71], v[136:139], v[144:147], v[68:71]
	v_mfma_f32_16x16x32_bf16 v[108:111], v[20:23], v[200:203], v[108:111]
	v_mfma_f32_16x16x32_bf16 v[100:103], v[136:139], v[200:203], v[100:103]
	v_mfma_f32_16x16x32_bf16 v[116:119], v[20:23], v[208:211], v[116:119]
	v_mfma_f32_16x16x32_bf16 v[112:115], v[136:139], v[208:211], v[112:115]
	v_mfma_f32_16x16x32_bf16 v[20:23], v[20:23], v[220:223], v[132:135]
	v_mfma_f32_16x16x32_bf16 v[64:67], v[28:31], v[148:151], v[64:67]
	v_mfma_f32_16x16x32_bf16 v[68:71], v[140:143], v[148:151], v[68:71]
	v_mfma_f32_16x16x32_bf16 v[108:111], v[28:31], v[204:207], v[108:111]
	v_mfma_f32_16x16x32_bf16 v[100:103], v[140:143], v[204:207], v[100:103]
	v_mfma_f32_16x16x32_bf16 v[116:119], v[28:31], v[212:215], v[116:119]
	v_mfma_f32_16x16x32_bf16 v[112:115], v[140:143], v[212:215], v[112:115]
	v_mfma_f32_16x16x32_bf16 v[20:23], v[28:31], v[224:227], v[20:23]
	v_mfma_f32_16x16x32_bf16 v[28:31], v[136:139], v[220:223], v[128:131]
	v_mfma_f32_16x16x32_bf16 v[28:31], v[140:143], v[224:227], v[28:31]
	s_barrier
; #define PG8_STAGE(bufoff, gbase, voff) do { _Pragma("unroll") for (int _i = 0; _i < 2; ++_i) \
;         __builtin_amdgcn_global_load_lds((const unsigned*)((const char*)(gbase) + (voff)[_i]), (LAS unsigned*)(lds + (bufoff) + ldsw + _i * 8192), 16, 0, 0); } while (0)
; #define PG8_LDA(dst, b, h) do { _Pragma("unroll") for (int m = 0; m < 4; ++m) _Pragma("unroll") for (int k = 0; k < 2; ++k) dst[m][k] = *(const LAS bf16x8*)(lds + PG8_SA(b, h) + aoff + m * 2048 + k * 1024); } while (0)
; #define PG8_LDB(dst, b, h) do { _Pragma("unroll") for (int n = 0; n < 2; ++n) _Pragma("unroll") for (int k = 0; k < 2; ++k) dst[n][k] = *(const LAS bf16x8*)(lds + PG8_SB(b, h) + boff + n * 2048 + k * 1024); } while (0)
; #define PG8_MMA(ai, bj, At, Bt) do { __builtin_amdgcn_s_setprio(1); _Pragma("unroll") for (int m = 0; m < 4; ++m) _Pragma("unroll") for (int n = 0; n < 2; ++n) _Pragma("unroll") for (int k = 0; k < 2; ++k) \
;         acc[ai][bj][m][n] = __builtin_amdgcn_mfma_f32_16x16x32_bf16(Bt[n][k], At[m][k], acc[ai][bj][m][n], 0, 0, 0); __builtin_amdgcn_s_setprio(0); } while (0)
; #define PG8_WAIT_V(n) asm volatile("s_waitcnt vmcnt(" #n ")" ::: "memory")
; #define PG8_WAIT_L(n) asm volatile("s_waitcnt lgkmcnt(" #n ")" ::: "memory")
; #define PG8_BAR __builtin_amdgcn_s_barrier()
; #define PG8_SCHED __builtin_amdgcn_sched_barrier(0)
; template <class Epi, class Sched, bool ATILE = false>
; __device__ __forceinline__ void gemm_phase(LAS unsigned char* lds, const Gemm g, const Sched& S, const Epi& E) {
;     ...
;             PG8_BAR; PG8_WAIT_L(0); PG8_MMA(1, 0, At, B0); PG8_BAR; PG8_SCHED;
;             PG8_STAGE(PG8_SB(0, 1), b2 + hstepB, voffB);
;             PG8_WAIT_V(6); PG8_BAR; PG8_MMA(1, 1, At, B1); PG8_BAR;
;             PG8_LDB(B0, 1, 0); PG8_SCHED; PG8_LDA(At, 1, 0); PG8_STAGE(PG8_SA(0, 1), a2 + hstepA, voffA);
;             PG8_WAIT_L(8); PG8_BAR; PG8_WAIT_L(0); PG8_MMA(0, 0, At, B0); PG8_BAR; PG8_SCHED;
;             PG8_LDB(B1, 1, 1); PG8_STAGE(PG8_SB(1, 0), b3, voffB);
;             PG8_BAR; PG8_WAIT_L(0); PG8_MMA(0, 1, At, B1); PG8_BAR;
	s_setprio 0
	s_add_u32 s64, s26, 0x158000
	s_addc_u32 s65, s27, 0
	s_add_i32 s63, s53, s33
	v_lshl_add_u64 v[128:129], s[64:65], 0, v[170:171]
	s_mov_b32 m0, s63
	s_nop 0
	global_load_lds_dwordx4 v[128:129], off
	v_lshl_add_u64 v[128:129], s[64:65], 0, v[174:175]
	s_add_i32 m0, s63, 0x2000
	s_nop 0
	global_load_lds_dwordx4 v[128:129], off
	s_waitcnt vmcnt(6)
	s_setprio 1
	s_barrier
	v_mfma_f32_16x16x32_bf16 v[76:79], v[228:231], v[144:147], v[76:79]
	v_mfma_f32_16x16x32_bf16 v[72:75], v[236:239], v[144:147], v[72:75]
	v_mfma_f32_16x16x32_bf16 v[88:91], v[228:231], v[200:203], v[88:91]
	v_mfma_f32_16x16x32_bf16 v[80:83], v[236:239], v[200:203], v[80:83]
	v_mfma_f32_16x16x32_bf16 v[104:107], v[228:231], v[208:211], v[104:107]
	v_mfma_f32_16x16x32_bf16 v[96:99], v[236:239], v[208:211], v[96:99]
	v_mfma_f32_16x16x32_bf16 v[120:123], v[228:231], v[220:223], v[120:123]
	v_mfma_f32_16x16x32_bf16 v[124:127], v[236:239], v[220:223], v[124:127]
	v_mfma_f32_16x16x32_bf16 v[76:79], v[232:235], v[148:151], v[76:79]
	v_mfma_f32_16x16x32_bf16 v[72:75], v[240:243], v[148:151], v[72:75]
	v_mfma_f32_16x16x32_bf16 v[88:91], v[232:235], v[204:207], v[88:91]
	v_mfma_f32_16x16x32_bf16 v[80:83], v[240:243], v[204:207], v[80:83]
	v_mfma_f32_16x16x32_bf16 v[104:107], v[232:235], v[212:215], v[104:107]
	v_mfma_f32_16x16x32_bf16 v[96:99], v[240:243], v[212:215], v[96:99]
	v_mfma_f32_16x16x32_bf16 v[120:123], v[232:235], v[224:227], v[120:123]
	v_mfma_f32_16x16x32_bf16 v[124:127], v[240:243], v[224:227], v[124:127]
	s_barrier
	s_setprio 0
	s_add_i32 s63, 0, 0x18000
	v_add_u32_e32 v140, s63, v161
	ds_read_b128 v[128:131], v140
	ds_read_b128 v[132:135], v140 offset:1024
	ds_read_b128 v[136:139], v140 offset:2048
	ds_read_b128 v[140:143], v140 offset:3072
	s_add_u32 s30, s30, 0x4000
	s_addc_u32 s31, s31, 0
	s_mov_b32 m0, s36
	v_lshl_add_u64 v[228:229], s[30:31], 0, v[168:169]
	ds_read_b128 v[144:147], v167 offset:32768
	ds_read_b128 v[148:151], v167 offset:33792
	ds_read_b128 v[200:203], v167 offset:34816
	ds_read_b128 v[204:207], v167 offset:35840
	ds_read_b128 v[208:211], v167 offset:36864
	ds_read_b128 v[212:215], v167 offset:37888
	ds_read_b128 v[220:223], v167 offset:38912
	ds_read_b128 v[224:227], v167 offset:39936
	global_load_lds_dwordx4 v[228:229], off
	v_lshl_add_u64 v[228:229], s[30:31], 0, v[172:173]
	s_mov_b32 m0, s37
	s_nop 0
	global_load_lds_dwordx4 v[228:229], off
	s_waitcnt lgkmcnt(8)
	s_setprio 1
	s_barrier
	s_waitcnt lgkmcnt(0)
	v_mfma_f32_16x16x32_bf16 v[0:3], v[128:131], v[144:147], v[0:3]
	v_mfma_f32_16x16x32_bf16 v[4:7], v[136:139], v[144:147], v[4:7]
	v_mfma_f32_16x16x32_bf16 v[44:47], v[128:131], v[200:203], v[44:47]
	v_mfma_f32_16x16x32_bf16 v[36:39], v[136:139], v[200:203], v[36:39]
	v_mfma_f32_16x16x32_bf16 v[52:55], v[128:131], v[208:211], v[52:55]
	v_mfma_f32_16x16x32_bf16 v[48:51], v[136:139], v[208:211], v[48:51]
	v_mfma_f32_16x16x32_bf16 v[92:95], v[128:131], v[220:223], v[92:95]
	v_mfma_f32_16x16x32_bf16 v[84:87], v[136:139], v[220:223], v[84:87]
	v_mfma_f32_16x16x32_bf16 v[0:3], v[132:135], v[148:151], v[0:3]
	v_mfma_f32_16x16x32_bf16 v[4:7], v[140:143], v[148:151], v[4:7]
	v_mfma_f32_16x16x32_bf16 v[44:47], v[132:135], v[204:207], v[44:47]
	v_mfma_f32_16x16x32_bf16 v[36:39], v[140:143], v[204:207], v[36:39]
	v_mfma_f32_16x16x32_bf16 v[52:55], v[132:135], v[212:215], v[52:55]
	v_mfma_f32_16x16x32_bf16 v[48:51], v[140:143], v[212:215], v[48:51]
	v_mfma_f32_16x16x32_bf16 v[92:95], v[132:135], v[224:227], v[92:95]
	v_mfma_f32_16x16x32_bf16 v[84:87], v[140:143], v[224:227], v[84:87]
	s_barrier
	s_setprio 0
	s_add_i32 s30, 0, 0x1c000
	s_add_i32 s31, s63, s33
	v_add_u32_e32 v219, s30, v161
	v_lshl_add_u64 v[216:217], v[216:217], 0, s[6:7]
	s_mov_b32 m0, s31
	ds_read_b128 v[228:231], v219
	ds_read_b128 v[232:235], v219 offset:1024
	ds_read_b128 v[236:239], v219 offset:2048
	ds_read_b128 v[240:243], v219 offset:3072
	global_load_lds_dwordx4 v[216:217], off
	v_lshl_add_u64 v[216:217], v[244:245], 0, s[6:7]
	s_add_i32 m0, s31, 0x2000
	s_nop 0
	global_load_lds_dwordx4 v[216:217], off
	s_setprio 1
	s_barrier
	s_waitcnt lgkmcnt(0)
	v_mfma_f32_16x16x32_bf16 v[12:15], v[228:231], v[144:147], v[12:15]
	v_mfma_f32_16x16x32_bf16 v[8:11], v[236:239], v[144:147], v[8:11]
	v_mfma_f32_16x16x32_bf16 v[24:27], v[228:231], v[200:203], v[24:27]
	v_mfma_f32_16x16x32_bf16 v[16:19], v[236:239], v[200:203], v[16:19]
	v_mfma_f32_16x16x32_bf16 v[40:43], v[228:231], v[208:211], v[40:43]
	v_mfma_f32_16x16x32_bf16 v[32:35], v[236:239], v[208:211], v[32:35]
	v_mfma_f32_16x16x32_bf16 v[56:59], v[228:231], v[220:223], v[56:59]
	v_mfma_f32_16x16x32_bf16 v[60:63], v[236:239], v[220:223], v[60:63]
	v_mfma_f32_16x16x32_bf16 v[12:15], v[232:235], v[148:151], v[12:15]
	v_mfma_f32_16x16x32_bf16 v[8:11], v[240:243], v[148:151], v[8:11]
	v_mfma_f32_16x16x32_bf16 v[24:27], v[232:235], v[204:207], v[24:27]
	v_mfma_f32_16x16x32_bf16 v[16:19], v[240:243], v[204:207], v[16:19]
	v_mfma_f32_16x16x32_bf16 v[40:43], v[232:235], v[212:215], v[40:43]
	v_mfma_f32_16x16x32_bf16 v[32:35], v[240:243], v[212:215], v[32:35]
	v_mfma_f32_16x16x32_bf16 v[56:59], v[232:235], v[224:227], v[56:59]
	v_mfma_f32_16x16x32_bf16 v[60:63], v[240:243], v[224:227], v[60:63]
	s_barrier
	s_setprio 0
	s_mov_b32 m0, s39
	v_lshl_add_u64 v[216:217], s[28:29], 0, v[168:169]
	ds_read_b128 v[144:147], v167 offset:49152
	ds_read_b128 v[148:151], v167 offset:50176
	ds_read_b128 v[200:203], v167 offset:51200
	ds_read_b128 v[204:207], v167 offset:52224
	ds_read_b128 v[208:211], v167 offset:53248
	ds_read_b128 v[212:215], v167 offset:54272
	ds_read_b128 v[220:223], v167 offset:55296
	ds_read_b128 v[224:227], v167 offset:56320
	global_load_lds_dwordx4 v[216:217], off
	v_lshl_add_u64 v[216:217], s[28:29], 0, v[172:173]
	s_mov_b32 m0, s40
	s_nop 0
	global_load_lds_dwordx4 v[216:217], off
	s_setprio 1
	s_barrier
; __device__ __forceinline__ float bflo(unsigned w) { return __uint_as_float(w << 16); }
; __device__ __forceinline__ float bfhi(unsigned w) { return __uint_as_float(w & 0xffff0000u); }
; #define PG8_STAGE(bufoff, gbase, voff) do { _Pragma("unroll") for (int _i = 0; _i < 2; ++_i) \
;         __builtin_amdgcn_global_load_lds((const unsigned*)((const char*)(gbase) + (voff)[_i]), (LAS unsigned*)(lds + (bufoff) + ldsw + _i * 8192), 16, 0, 0); } while (0)
; #define PG8_LDA(dst, b, h) do { _Pragma("unroll") for (int m = 0; m < 4; ++m) _Pragma("unroll") for (int k = 0; k < 2; ++k) dst[m][k] = *(const LAS bf16x8*)(lds + PG8_SA(b, h) + aoff + m * 2048 + k * 1024); } while (0)
; #define PG8_MMA(ai, bj, At, Bt) do { __builtin_amdgcn_s_setprio(1); _Pragma("unroll") for (int m = 0; m < 4; ++m) _Pragma("unroll") for (int n = 0; n < 2; ++n) _Pragma("unroll") for (int k = 0; k < 2; ++k) \
;         acc[ai][bj][m][n] = __builtin_amdgcn_mfma_f32_16x16x32_bf16(Bt[n][k], At[m][k], acc[ai][bj][m][n], 0, 0, 0); __builtin_amdgcn_s_setprio(0); } while (0)
; #define PG8_WAIT_V(n) asm volatile("s_waitcnt vmcnt(" #n ")" ::: "memory")
; #define PG8_WAIT_L(n) asm volatile("s_waitcnt lgkmcnt(" #n ")" ::: "memory")
; #define PG8_BAR __builtin_amdgcn_s_barrier()
; #define PG8_SCHED __builtin_amdgcn_sched_barrier(0)
; template <class Epi, class Sched, bool ATILE = false>
; __device__ __forceinline__ void gemm_phase(LAS unsigned char* lds, const Gemm g, const Sched& S, const Epi& E) {
;     ...
;             PG8_BAR; PG8_WAIT_L(0); PG8_MMA(0, 1, At, B1); PG8_BAR;
;             PG8_LDA(At, 1, 1); PG8_STAGE(PG8_SA(1, 0), a3, voffA);
;             PG8_BAR; PG8_WAIT_L(0); PG8_MMA(1, 0, At, B0); PG8_BAR; PG8_SCHED;
;             PG8_STAGE(PG8_SB(1, 1), b3 + hstepB, voffB);
;             PG8_WAIT_V(6); PG8_BAR; PG8_MMA(1, 1, At, B1); PG8_BAR;
;     __device__ __forceinline__ void operator()(const f32x4 (&acc)[2][2][4][2], const Unit& u, int wr, int wc, int fr, int fq) const {
;     ...
;                     const f32x4 v0 = (f32x4){bflo(x.x), bfhi(x.x), bflo(x.y), bfhi(x.y)} + alpha * acc[ai][bj][m][0];
;                     const f32x4 v1 = (f32x4){bflo(x.z), bfhi(x.z), bflo(x.w), bfhi(x.w)} + alpha * acc[ai][bj][m][1];
	s_waitcnt lgkmcnt(0)
	v_mfma_f32_16x16x32_bf16 v[64:67], v[128:131], v[144:147], v[64:67]
	v_mfma_f32_16x16x32_bf16 v[108:111], v[128:131], v[200:203], v[108:111]
	v_mfma_f32_16x16x32_bf16 v[116:119], v[128:131], v[208:211], v[116:119]
	v_mfma_f32_16x16x32_bf16 v[20:23], v[128:131], v[220:223], v[20:23]
	v_mfma_f32_16x16x32_bf16 v[64:67], v[132:135], v[148:151], v[64:67]
	v_mfma_f32_16x16x32_bf16 v[68:71], v[136:139], v[144:147], v[68:71]
	v_mfma_f32_16x16x32_bf16 v[108:111], v[132:135], v[204:207], v[108:111]
	v_mfma_f32_16x16x32_bf16 v[100:103], v[136:139], v[200:203], v[100:103]
	v_mfma_f32_16x16x32_bf16 v[116:119], v[132:135], v[212:215], v[116:119]
	v_mfma_f32_16x16x32_bf16 v[112:115], v[136:139], v[208:211], v[112:115]
	v_mfma_f32_16x16x32_bf16 v[132:135], v[132:135], v[224:227], v[20:23]
	v_mfma_f32_16x16x32_bf16 v[20:23], v[136:139], v[220:223], v[28:31]
	v_mfma_f32_16x16x32_bf16 v[68:71], v[140:143], v[148:151], v[68:71]
	v_mfma_f32_16x16x32_bf16 v[100:103], v[140:143], v[204:207], v[100:103]
	v_mfma_f32_16x16x32_bf16 v[112:115], v[140:143], v[212:215], v[112:115]
	v_mfma_f32_16x16x32_bf16 v[128:131], v[140:143], v[224:227], v[20:23]
	s_barrier
	s_setprio 0
	s_add_u32 s26, s26, 0x158080
	s_addc_u32 s27, s27, 0
	s_add_i32 s28, s30, s33
	v_lshl_add_u64 v[20:21], s[26:27], 0, v[170:171]
	s_mov_b32 m0, s28
	s_nop 0
	global_load_lds_dwordx4 v[20:21], off
	v_lshl_add_u64 v[20:21], s[26:27], 0, v[174:175]
	s_add_i32 m0, s28, 0x2000
	s_nop 0
	global_load_lds_dwordx4 v[20:21], off
	s_waitcnt vmcnt(6)
	s_setprio 1
	s_barrier
	v_mfma_f32_16x16x32_bf16 v[20:23], v[228:231], v[144:147], v[76:79]
	v_mfma_f32_16x16x32_bf16 v[76:79], v[232:235], v[148:151], v[20:23]
	v_mfma_f32_16x16x32_bf16 v[20:23], v[236:239], v[144:147], v[72:75]
	v_mfma_f32_16x16x32_bf16 v[72:75], v[240:243], v[148:151], v[20:23]
	v_mfma_f32_16x16x32_bf16 v[20:23], v[228:231], v[200:203], v[88:91]
	v_mfma_f32_16x16x32_bf16 v[88:91], v[232:235], v[204:207], v[20:23]
	v_mfma_f32_16x16x32_bf16 v[20:23], v[236:239], v[200:203], v[80:83]
	v_mfma_f32_16x16x32_bf16 v[80:83], v[240:243], v[204:207], v[20:23]
	v_mfma_f32_16x16x32_bf16 v[20:23], v[228:231], v[208:211], v[104:107]
	v_mfma_f32_16x16x32_bf16 v[104:107], v[232:235], v[212:215], v[20:23]
	v_mfma_f32_16x16x32_bf16 v[20:23], v[236:239], v[208:211], v[96:99]
	v_mfma_f32_16x16x32_bf16 v[96:99], v[240:243], v[212:215], v[20:23]
	v_mfma_f32_16x16x32_bf16 v[20:23], v[228:231], v[220:223], v[120:123]
	v_mfma_f32_16x16x32_bf16 v[120:123], v[232:235], v[224:227], v[20:23]
	v_mfma_f32_16x16x32_bf16 v[20:23], v[236:239], v[220:223], v[124:127]
	v_mfma_f32_16x16x32_bf16 v[124:127], v[240:243], v[224:227], v[20:23]
	s_barrier
	s_setprio 0
	s_add_u32 s60, s60, 0x100
	s_addc_u32 s61, s61, 0
	s_add_u32 s24, s24, 0x10000
	s_addc_u32 s25, s25, 0
	s_cmp_ge_i32 s62, s59
	s_mov_b32 s26, s62
	s_cbranch_scc0 .LBB0_739
	v_pk_mul_f32 v[2:3], v[2:3], 0.5 op_sel_hi:[1,0]
	v_pk_mul_f32 v[0:1], v[0:1], 0.5 op_sel_hi:[1,0]
	v_pk_mul_f32 v[6:7], v[6:7], 0.5 op_sel_hi:[1,0]
	v_pk_mul_f32 v[4:5], v[4:5], 0.5 op_sel_hi:[1,0]
	v_pk_mul_f32 v[22:23], v[14:15], 0.5 op_sel_hi:[1,0]
	v_pk_mul_f32 v[20:21], v[12:13], 0.5 op_sel_hi:[1,0]
	v_pk_mul_f32 v[30:31], v[10:11], 0.5 op_sel_hi:[1,0]
	v_pk_mul_f32 v[28:29], v[8:9], 0.5 op_sel_hi:[1,0]
	v_pk_mul_f32 v[10:11], v[46:47], 0.5 op_sel_hi:[1,0]
	v_pk_mul_f32 v[8:9], v[44:45], 0.5 op_sel_hi:[1,0]
	v_pk_mul_f32 v[14:15], v[38:39], 0.5 op_sel_hi:[1,0]
	v_pk_mul_f32 v[12:13], v[36:37], 0.5 op_sel_hi:[1,0]
	v_pk_mul_f32 v[38:39], v[26:27], 0.5 op_sel_hi:[1,0]
	v_pk_mul_f32 v[36:37], v[24:25], 0.5 op_sel_hi:[1,0]
	v_pk_mul_f32 v[46:47], v[18:19], 0.5 op_sel_hi:[1,0]
	v_pk_mul_f32 v[44:45], v[16:17], 0.5 op_sel_hi:[1,0]
	v_pk_mul_f32 v[18:19], v[54:55], 0.5 op_sel_hi:[1,0]
	v_pk_mul_f32 v[16:17], v[52:53], 0.5 op_sel_hi:[1,0]
	v_pk_mul_f32 v[26:27], v[50:51], 0.5 op_sel_hi:[1,0]
	v_pk_mul_f32 v[24:25], v[48:49], 0.5 op_sel_hi:[1,0]
	v_pk_mul_f32 v[50:51], v[42:43], 0.5 op_sel_hi:[1,0]
	v_pk_mul_f32 v[48:49], v[40:41], 0.5 op_sel_hi:[1,0]
	v_pk_mul_f32 v[54:55], v[34:35], 0.5 op_sel_hi:[1,0]
	v_pk_mul_f32 v[52:53], v[32:33], 0.5 op_sel_hi:[1,0]
	v_pk_mul_f32 v[34:35], v[94:95], 0.5 op_sel_hi:[1,0]
	v_pk_mul_f32 v[32:33], v[92:93], 0.5 op_sel_hi:[1,0]
	v_pk_mul_f32 v[42:43], v[86:87], 0.5 op_sel_hi:[1,0]
	v_pk_mul_f32 v[40:41], v[84:85], 0.5 op_sel_hi:[1,0]
	v_pk_mul_f32 v[58:59], v[58:59], 0.5 op_sel_hi:[1,0]
	v_pk_mul_f32 v[56:57], v[56:57], 0.5 op_sel_hi:[1,0]
	v_pk_mul_f32 v[62:63], v[62:63], 0.5 op_sel_hi:[1,0]
	v_pk_mul_f32 v[60:61], v[60:61], 0.5 op_sel_hi:[1,0]
	v_pk_mul_f32 v[66:67], v[66:67], 0.5 op_sel_hi:[1,0]
	v_pk_mul_f32 v[64:65], v[64:65], 0.5 op_sel_hi:[1,0]
	v_pk_mul_f32 v[70:71], v[70:71], 0.5 op_sel_hi:[1,0]
	v_pk_mul_f32 v[68:69], v[68:69], 0.5 op_sel_hi:[1,0]
	v_pk_mul_f32 v[86:87], v[78:79], 0.5 op_sel_hi:[1,0]
	v_pk_mul_f32 v[84:85], v[76:77], 0.5 op_sel_hi:[1,0]
	v_pk_mul_f32 v[94:95], v[74:75], 0.5 op_sel_hi:[1,0]
	v_pk_mul_f32 v[92:93], v[72:73], 0.5 op_sel_hi:[1,0]
	v_pk_mul_f32 v[74:75], v[110:111], 0.5 op_sel_hi:[1,0]
	v_pk_mul_f32 v[72:73], v[108:109], 0.5 op_sel_hi:[1,0]
	v_pk_mul_f32 v[78:79], v[102:103], 0.5 op_sel_hi:[1,0]
	v_pk_mul_f32 v[76:77], v[100:101], 0.5 op_sel_hi:[1,0]
	v_pk_mul_f32 v[102:103], v[90:91], 0.5 op_sel_hi:[1,0]
	v_pk_mul_f32 v[100:101], v[88:89], 0.5 op_sel_hi:[1,0]
	v_pk_mul_f32 v[110:111], v[82:83], 0.5 op_sel_hi:[1,0]
	v_pk_mul_f32 v[108:109], v[80:81], 0.5 op_sel_hi:[1,0]
	v_pk_mul_f32 v[82:83], v[118:119], 0.5 op_sel_hi:[1,0]
	v_pk_mul_f32 v[80:81], v[116:117], 0.5 op_sel_hi:[1,0]
	v_pk_mul_f32 v[90:91], v[114:115], 0.5 op_sel_hi:[1,0]
	v_pk_mul_f32 v[88:89], v[112:113], 0.5 op_sel_hi:[1,0]
	v_pk_mul_f32 v[114:115], v[106:107], 0.5 op_sel_hi:[1,0]
	v_pk_mul_f32 v[112:113], v[104:105], 0.5 op_sel_hi:[1,0]
	v_pk_mul_f32 v[118:119], v[98:99], 0.5 op_sel_hi:[1,0]
	v_pk_mul_f32 v[116:117], v[96:97], 0.5 op_sel_hi:[1,0]
	v_pk_mul_f32 v[98:99], v[134:135], 0.5 op_sel_hi:[1,0]
	v_pk_mul_f32 v[96:97], v[132:133], 0.5 op_sel_hi:[1,0]
	v_pk_mul_f32 v[106:107], v[130:131], 0.5 op_sel_hi:[1,0]
	v_pk_mul_f32 v[104:105], v[128:129], 0.5 op_sel_hi:[1,0]
	v_pk_mul_f32 v[122:123], v[122:123], 0.5 op_sel_hi:[1,0]
	v_pk_mul_f32 v[120:121], v[120:121], 0.5 op_sel_hi:[1,0]
	v_pk_mul_f32 v[126:127], v[126:127], 0.5 op_sel_hi:[1,0]
	v_pk_mul_f32 v[124:125], v[124:125], 0.5 op_sel_hi:[1,0]
	s_branch .LBB0_744

; #define PG8_STAGE(bufoff, gbase, voff) do { _Pragma("unroll") for (int _i = 0; _i < 2; ++_i) \
;         __builtin_amdgcn_global_load_lds((const unsigned*)((const char*)(gbase) + (voff)[_i]), (LAS unsigned*)(lds + (bufoff) + ldsw + _i * 8192), 16, 0, 0); } while (0)
; #define PG8_LDA(dst, b, h) do { _Pragma("unroll") for (int m = 0; m < 4; ++m) _Pragma("unroll") for (int k = 0; k < 2; ++k) dst[m][k] = *(const LAS bf16x8*)(lds + PG8_SA(b, h) + aoff + m * 2048 + k * 1024); } while (0)
; #define PG8_LDB(dst, b, h) do { _Pragma("unroll") for (int n = 0; n < 2; ++n) _Pragma("unroll") for (int k = 0; k < 2; ++k) dst[n][k] = *(const LAS bf16x8*)(lds + PG8_SB(b, h) + boff + n * 2048 + k * 1024); } while (0)
; #define PG8_MMA(ai, bj, At, Bt) do { __builtin_amdgcn_s_setprio(1); _Pragma("unroll") for (int m = 0; m < 4; ++m) _Pragma("unroll") for (int n = 0; n < 2; ++n) _Pragma("unroll") for (int k = 0; k < 2; ++k) \
;         acc[ai][bj][m][n] = __builtin_amdgcn_mfma_f32_16x16x32_bf16(Bt[n][k], At[m][k], acc[ai][bj][m][n], 0, 0, 0); __builtin_amdgcn_s_setprio(0); } while (0)
; #define PG8_WAIT_L(n) asm volatile("s_waitcnt lgkmcnt(" #n ")" ::: "memory")
; #define PG8_BAR __builtin_amdgcn_s_barrier()
; #define PG8_SCHED __builtin_amdgcn_sched_barrier(0)
; template <class Epi, class Sched, bool ATILE = false>
; __device__ __forceinline__ void gemm_phase(LAS unsigned char* lds, const Gemm g, const Sched& S, const Epi& E) {
;     ...
;         for (int t = 0; t < nt; t += 2) {
;             const bool last = (t == nt - 2);
;             const char* a1 = cA + (size_t)(t + 1) * kstepA;
;             const char* a2 = last ? nA : cA + (size_t)(t + 2) * kstepA; const char* b2 = last ? nB : cB + (size_t)(t + 2) * kstep;
;             const char* a3 = a2 + kstepA; const char* b3 = b2 + kstep;
;             PG8_LDB(B0, 0, 0); PG8_SCHED; PG8_LDA(At, 0, 0); PG8_STAGE(PG8_SA(1, 1), a1 + hstepA, voffA);
;             PG8_WAIT_L(8); PG8_BAR; PG8_WAIT_L(0); PG8_MMA(0, 0, At, B0); PG8_BAR; PG8_SCHED;
;             PG8_LDB(B1, 0, 1); PG8_STAGE(PG8_SB(0, 0), b2, voffB);
;             PG8_BAR; PG8_WAIT_L(0); PG8_MMA(0, 1, At, B1); PG8_BAR;
;             PG8_LDA(At, 0, 1); PG8_STAGE(PG8_SA(0, 0), a2, voffA);
;             PG8_BAR; PG8_WAIT_L(0); PG8_MMA(1, 0, At, B0); PG8_BAR; PG8_SCHED;
.LBB0_895:
	ds_read_b128 v[32:35], v165
	ds_read_b128 v[36:39], v165 offset:1024
	ds_read_b128 v[178:181], v165 offset:2048
	ds_read_b128 v[182:185], v165 offset:3072
	s_add_i32 s88, s73, 2
	s_add_u32 s84, s12, 0xfff80080
	s_addc_u32 s85, s13, -1
	s_cmp_eq_u32 s53, s73
	s_cselect_b32 s87, s11, s85
	s_cselect_b32 s86, s20, s84
	s_cselect_b32 s85, s41, s63
	s_cselect_b32 s84, s52, s62
	v_lshl_add_u64 v[224:225], s[12:13], 0, v[170:171]
	s_add_i32 m0, s35, 0xc000
	ds_read_b128 v[192:195], v167
	ds_read_b128 v[196:199], v167 offset:1024
	ds_read_b128 v[200:203], v167 offset:2048
	ds_read_b128 v[204:207], v167 offset:3072
	ds_read_b128 v[208:211], v167 offset:4096
	ds_read_b128 v[212:215], v167 offset:5120
	ds_read_b128 v[216:219], v167 offset:6144
	ds_read_b128 v[220:223], v167 offset:7168
	global_load_lds_dwordx4 v[224:225], off
	v_lshl_add_u64 v[224:225], s[12:13], 0, v[172:173]
	s_add_i32 m0, s35, 0xe000
	s_nop 0
	global_load_lds_dwordx4 v[224:225], off
	s_waitcnt lgkmcnt(8)
	s_setprio 1
	s_barrier
	s_waitcnt lgkmcnt(0)
	v_mfma_f32_16x16x32_bf16 v[132:135], v[32:35], v[192:195], v[132:135]
	v_mfma_f32_16x16x32_bf16 v[128:131], v[178:181], v[192:195], v[128:131]
	v_mfma_f32_16x16x32_bf16 v[116:119], v[32:35], v[200:203], v[116:119]
	v_mfma_f32_16x16x32_bf16 v[112:115], v[178:181], v[200:203], v[112:115]
	v_mfma_f32_16x16x32_bf16 v[100:103], v[32:35], v[208:211], v[100:103]
	v_mfma_f32_16x16x32_bf16 v[96:99], v[178:181], v[208:211], v[96:99]
	v_mfma_f32_16x16x32_bf16 v[84:87], v[32:35], v[216:219], v[84:87]
	v_mfma_f32_16x16x32_bf16 v[80:83], v[178:181], v[216:219], v[80:83]
	v_mfma_f32_16x16x32_bf16 v[132:135], v[36:39], v[196:199], v[132:135]
	v_mfma_f32_16x16x32_bf16 v[128:131], v[182:185], v[196:199], v[128:131]
	v_mfma_f32_16x16x32_bf16 v[116:119], v[36:39], v[204:207], v[116:119]
	v_mfma_f32_16x16x32_bf16 v[112:115], v[182:185], v[204:207], v[112:115]
	v_mfma_f32_16x16x32_bf16 v[100:103], v[36:39], v[212:215], v[100:103]
	v_mfma_f32_16x16x32_bf16 v[96:99], v[182:185], v[212:215], v[96:99]
	v_mfma_f32_16x16x32_bf16 v[84:87], v[36:39], v[220:223], v[84:87]
	v_mfma_f32_16x16x32_bf16 v[80:83], v[182:185], v[220:223], v[80:83]
	s_barrier
	s_setprio 0
	s_add_i32 s73, s43, s31
	v_lshl_add_u64 v[240:241], s[84:85], 0, v[138:139]
	s_mov_b32 m0, s73
	ds_read_b128 v[224:227], v186
	ds_read_b128 v[228:231], v186 offset:1024
	ds_read_b128 v[232:235], v186 offset:2048
	ds_read_b128 v[236:239], v186 offset:3072
	global_load_lds_dwordx4 v[240:241], off
	v_lshl_add_u64 v[242:243], s[84:85], 0, v[142:143]
	s_add_i32 m0, s73, 0x2000
	s_nop 0
	global_load_lds_dwordx4 v[242:243], off
	s_setprio 1
	s_barrier
	s_waitcnt lgkmcnt(0)
	v_mfma_f32_16x16x32_bf16 v[124:127], v[224:227], v[192:195], v[124:127]
	v_mfma_f32_16x16x32_bf16 v[120:123], v[232:235], v[192:195], v[120:123]
	v_mfma_f32_16x16x32_bf16 v[108:111], v[224:227], v[200:203], v[108:111]
	v_mfma_f32_16x16x32_bf16 v[104:107], v[232:235], v[200:203], v[104:107]
	v_mfma_f32_16x16x32_bf16 v[92:95], v[224:227], v[208:211], v[92:95]
	v_mfma_f32_16x16x32_bf16 v[88:91], v[232:235], v[208:211], v[88:91]
	v_mfma_f32_16x16x32_bf16 v[76:79], v[224:227], v[216:219], v[76:79]
	v_mfma_f32_16x16x32_bf16 v[72:75], v[232:235], v[216:219], v[72:75]
	v_mfma_f32_16x16x32_bf16 v[124:127], v[228:231], v[196:199], v[124:127]
	v_mfma_f32_16x16x32_bf16 v[120:123], v[236:239], v[196:199], v[120:123]
	v_mfma_f32_16x16x32_bf16 v[108:111], v[228:231], v[204:207], v[108:111]
	v_mfma_f32_16x16x32_bf16 v[104:107], v[236:239], v[204:207], v[104:107]
	v_mfma_f32_16x16x32_bf16 v[92:95], v[228:231], v[212:215], v[92:95]
	v_mfma_f32_16x16x32_bf16 v[88:91], v[236:239], v[212:215], v[88:91]
	v_mfma_f32_16x16x32_bf16 v[76:79], v[228:231], v[220:223], v[76:79]
	v_mfma_f32_16x16x32_bf16 v[72:75], v[236:239], v[220:223], v[72:75]
	s_barrier
	s_setprio 0
	s_mov_b32 m0, s35
	v_lshl_add_u64 v[244:245], s[86:87], 0, v[136:137]
	ds_read_b128 v[192:195], v167 offset:16384
	ds_read_b128 v[196:199], v167 offset:17408
	ds_read_b128 v[200:203], v167 offset:18432
	ds_read_b128 v[204:207], v167 offset:19456
	ds_read_b128 v[208:211], v167 offset:20480
	ds_read_b128 v[212:215], v167 offset:21504
	ds_read_b128 v[216:219], v167 offset:22528
	ds_read_b128 v[220:223], v167 offset:23552
	global_load_lds_dwordx4 v[244:245], off
	v_lshl_add_u64 v[246:247], s[86:87], 0, v[140:141]
	s_mov_b32 m0, s37
	s_nop 0
	global_load_lds_dwordx4 v[246:247], off
	s_setprio 1
	s_barrier
	s_waitcnt lgkmcnt(0)
	v_mfma_f32_16x16x32_bf16 v[68:71], v[32:35], v[192:195], v[68:71]
	v_mfma_f32_16x16x32_bf16 v[64:67], v[178:181], v[192:195], v[64:67]
	v_mfma_f32_16x16x32_bf16 v[52:55], v[32:35], v[200:203], v[52:55]
	v_mfma_f32_16x16x32_bf16 v[48:51], v[178:181], v[200:203], v[48:51]
	v_mfma_f32_16x16x32_bf16 v[28:31], v[32:35], v[208:211], v[28:31]
	v_mfma_f32_16x16x32_bf16 v[24:27], v[178:181], v[208:211], v[24:27]
	v_mfma_f32_16x16x32_bf16 v[12:15], v[32:35], v[216:219], v[12:15]
	v_mfma_f32_16x16x32_bf16 v[8:11], v[178:181], v[216:219], v[8:11]
	v_mfma_f32_16x16x32_bf16 v[68:71], v[36:39], v[196:199], v[68:71]
	v_mfma_f32_16x16x32_bf16 v[64:67], v[182:185], v[196:199], v[64:67]
	v_mfma_f32_16x16x32_bf16 v[52:55], v[36:39], v[204:207], v[52:55]
	v_mfma_f32_16x16x32_bf16 v[48:51], v[182:185], v[204:207], v[48:51]
	v_mfma_f32_16x16x32_bf16 v[28:31], v[36:39], v[212:215], v[28:31]
	v_mfma_f32_16x16x32_bf16 v[24:27], v[182:185], v[212:215], v[24:27]
	v_mfma_f32_16x16x32_bf16 v[12:15], v[36:39], v[220:223], v[12:15]
	v_mfma_f32_16x16x32_bf16 v[8:11], v[182:185], v[220:223], v[8:11]
	s_barrier
; #define PG8_STAGE(bufoff, gbase, voff) do { _Pragma("unroll") for (int _i = 0; _i < 2; ++_i) \
;         __builtin_amdgcn_global_load_lds((const unsigned*)((const char*)(gbase) + (voff)[_i]), (LAS unsigned*)(lds + (bufoff) + ldsw + _i * 8192), 16, 0, 0); } while (0)
; #define PG8_LDA(dst, b, h) do { _Pragma("unroll") for (int m = 0; m < 4; ++m) _Pragma("unroll") for (int k = 0; k < 2; ++k) dst[m][k] = *(const LAS bf16x8*)(lds + PG8_SA(b, h) + aoff + m * 2048 + k * 1024); } while (0)
; #define PG8_LDB(dst, b, h) do { _Pragma("unroll") for (int n = 0; n < 2; ++n) _Pragma("unroll") for (int k = 0; k < 2; ++k) dst[n][k] = *(const LAS bf16x8*)(lds + PG8_SB(b, h) + boff + n * 2048 + k * 1024); } while (0)
; #define PG8_MMA(ai, bj, At, Bt) do { __builtin_amdgcn_s_setprio(1); _Pragma("unroll") for (int m = 0; m < 4; ++m) _Pragma("unroll") for (int n = 0; n < 2; ++n) _Pragma("unroll") for (int k = 0; k < 2; ++k) \
;         acc[ai][bj][m][n] = __builtin_amdgcn_mfma_f32_16x16x32_bf16(Bt[n][k], At[m][k], acc[ai][bj][m][n], 0, 0, 0); __builtin_amdgcn_s_setprio(0); } while (0)
; #define PG8_WAIT_V(n) asm volatile("s_waitcnt vmcnt(" #n ")" ::: "memory")
; #define PG8_WAIT_L(n) asm volatile("s_waitcnt lgkmcnt(" #n ")" ::: "memory")
; #define PG8_BAR __builtin_amdgcn_s_barrier()
; #define PG8_SCHED __builtin_amdgcn_sched_barrier(0)
; template <class Epi, class Sched, bool ATILE = false>
; __device__ __forceinline__ void gemm_phase(LAS unsigned char* lds, const Gemm g, const Sched& S, const Epi& E) {
;     ...
;             PG8_BAR; PG8_WAIT_L(0); PG8_MMA(1, 0, At, B0); PG8_BAR; PG8_SCHED;
;             PG8_STAGE(PG8_SB(0, 1), b2 + hstepB, voffB);
;             PG8_WAIT_V(6); PG8_BAR; PG8_MMA(1, 1, At, B1); PG8_BAR;
;             PG8_LDB(B0, 1, 0); PG8_SCHED; PG8_LDA(At, 1, 0); PG8_STAGE(PG8_SA(0, 1), a2 + hstepA, voffA);
;             PG8_WAIT_L(8); PG8_BAR; PG8_WAIT_L(0); PG8_MMA(0, 0, At, B0); PG8_BAR; PG8_SCHED;
;             PG8_LDB(B1, 1, 1); PG8_STAGE(PG8_SB(1, 0), b3, voffB);
;             PG8_BAR; PG8_WAIT_L(0); PG8_MMA(0, 1, At, B1); PG8_BAR;
	s_setprio 0
	s_add_u32 vcc_lo, s84, 0x80000
	s_addc_u32 vcc_hi, s85, 0
	s_add_i32 s73, s56, s31
	v_lshl_add_u64 v[32:33], vcc, 0, v[138:139]
	s_mov_b32 m0, s73
	s_nop 0
	global_load_lds_dwordx4 v[32:33], off
	v_lshl_add_u64 v[32:33], vcc, 0, v[142:143]
	s_add_i32 m0, s73, 0x2000
	s_nop 0
	global_load_lds_dwordx4 v[32:33], off
	s_waitcnt vmcnt(6)
	s_setprio 1
	s_barrier
	v_mfma_f32_16x16x32_bf16 v[44:47], v[224:227], v[200:203], v[44:47]
	v_mfma_f32_16x16x32_bf16 v[40:43], v[232:235], v[200:203], v[40:43]
	v_mfma_f32_16x16x32_bf16 v[20:23], v[224:227], v[208:211], v[20:23]
	v_mfma_f32_16x16x32_bf16 v[16:19], v[232:235], v[208:211], v[16:19]
	v_mfma_f32_16x16x32_bf16 v[4:7], v[224:227], v[216:219], v[4:7]
	v_mfma_f32_16x16x32_bf16 v[0:3], v[232:235], v[216:219], v[0:3]
	v_mfma_f32_16x16x32_bf16 v[32:35], v[224:227], v[192:195], v[60:63]
	v_mfma_f32_16x16x32_bf16 v[36:39], v[232:235], v[192:195], v[56:59]
	v_mfma_f32_16x16x32_bf16 v[44:47], v[228:231], v[204:207], v[44:47]
	v_mfma_f32_16x16x32_bf16 v[40:43], v[236:239], v[204:207], v[40:43]
	v_mfma_f32_16x16x32_bf16 v[20:23], v[228:231], v[212:215], v[20:23]
	v_mfma_f32_16x16x32_bf16 v[16:19], v[236:239], v[212:215], v[16:19]
	v_mfma_f32_16x16x32_bf16 v[4:7], v[228:231], v[220:223], v[4:7]
	v_mfma_f32_16x16x32_bf16 v[0:3], v[236:239], v[220:223], v[0:3]
	v_mfma_f32_16x16x32_bf16 v[32:35], v[228:231], v[196:199], v[32:35]
	v_mfma_f32_16x16x32_bf16 v[36:39], v[236:239], v[196:199], v[36:39]
	s_barrier
	s_setprio 0
	s_add_i32 s73, 0, 0x18000
	v_add_u32_e32 v144, s73, v161
	ds_read_b128 v[56:59], v144
	ds_read_b128 v[60:63], v144 offset:1024
	ds_read_b128 v[178:181], v144 offset:2048
	ds_read_b128 v[182:185], v144 offset:3072
	s_add_u32 s86, s86, 0x80000
	s_addc_u32 s87, s87, 0
	s_mov_b32 m0, s39
	v_lshl_add_u64 v[224:225], s[86:87], 0, v[136:137]
	ds_read_b128 v[192:195], v167 offset:32768
	ds_read_b128 v[196:199], v167 offset:33792
	ds_read_b128 v[200:203], v167 offset:34816
	ds_read_b128 v[204:207], v167 offset:35840
	ds_read_b128 v[208:211], v167 offset:36864
	ds_read_b128 v[212:215], v167 offset:37888
	ds_read_b128 v[216:219], v167 offset:38912
	ds_read_b128 v[220:223], v167 offset:39936
	global_load_lds_dwordx4 v[224:225], off
	v_lshl_add_u64 v[224:225], s[86:87], 0, v[140:141]
	s_mov_b32 m0, s97
	s_nop 0
	global_load_lds_dwordx4 v[224:225], off
	s_waitcnt lgkmcnt(8)
	s_setprio 1
	s_barrier
	s_waitcnt lgkmcnt(0)
	v_mfma_f32_16x16x32_bf16 v[132:135], v[56:59], v[192:195], v[132:135]
	v_mfma_f32_16x16x32_bf16 v[128:131], v[178:181], v[192:195], v[128:131]
	v_mfma_f32_16x16x32_bf16 v[116:119], v[56:59], v[200:203], v[116:119]
	v_mfma_f32_16x16x32_bf16 v[112:115], v[178:181], v[200:203], v[112:115]
	v_mfma_f32_16x16x32_bf16 v[100:103], v[56:59], v[208:211], v[100:103]
	v_mfma_f32_16x16x32_bf16 v[96:99], v[178:181], v[208:211], v[96:99]
	v_mfma_f32_16x16x32_bf16 v[84:87], v[56:59], v[216:219], v[84:87]
	v_mfma_f32_16x16x32_bf16 v[80:83], v[178:181], v[216:219], v[80:83]
	v_mfma_f32_16x16x32_bf16 v[132:135], v[60:63], v[196:199], v[132:135]
	v_mfma_f32_16x16x32_bf16 v[128:131], v[182:185], v[196:199], v[128:131]
	v_mfma_f32_16x16x32_bf16 v[116:119], v[60:63], v[204:207], v[116:119]
	v_mfma_f32_16x16x32_bf16 v[112:115], v[182:185], v[204:207], v[112:115]
	v_mfma_f32_16x16x32_bf16 v[100:103], v[60:63], v[212:215], v[100:103]
	v_mfma_f32_16x16x32_bf16 v[96:99], v[182:185], v[212:215], v[96:99]
	v_mfma_f32_16x16x32_bf16 v[84:87], v[60:63], v[220:223], v[84:87]
	v_mfma_f32_16x16x32_bf16 v[80:83], v[182:185], v[220:223], v[80:83]
	s_barrier
	s_setprio 0
	s_add_i32 s86, 0, 0x1c000
	s_add_i32 s73, s73, s31
	v_add_u32_e32 v144, s86, v161
	v_lshl_add_u64 v[240:241], v[240:241], 0, s[22:23]
	s_mov_b32 m0, s73
	ds_read_b128 v[224:227], v144
	ds_read_b128 v[228:231], v144 offset:1024
	ds_read_b128 v[232:235], v144 offset:2048
	ds_read_b128 v[236:239], v144 offset:3072
	global_load_lds_dwordx4 v[240:241], off
	v_lshl_add_u64 v[240:241], v[242:243], 0, s[22:23]
	s_add_i32 m0, s73, 0x2000
	s_nop 0
	global_load_lds_dwordx4 v[240:241], off
	s_setprio 1
	s_barrier
; #define PG8_STAGE(bufoff, gbase, voff) do { _Pragma("unroll") for (int _i = 0; _i < 2; ++_i) \
;         __builtin_amdgcn_global_load_lds((const unsigned*)((const char*)(gbase) + (voff)[_i]), (LAS unsigned*)(lds + (bufoff) + ldsw + _i * 8192), 16, 0, 0); } while (0)
; #define PG8_LDA(dst, b, h) do { _Pragma("unroll") for (int m = 0; m < 4; ++m) _Pragma("unroll") for (int k = 0; k < 2; ++k) dst[m][k] = *(const LAS bf16x8*)(lds + PG8_SA(b, h) + aoff + m * 2048 + k * 1024); } while (0)
; #define PG8_MMA(ai, bj, At, Bt) do { __builtin_amdgcn_s_setprio(1); _Pragma("unroll") for (int m = 0; m < 4; ++m) _Pragma("unroll") for (int n = 0; n < 2; ++n) _Pragma("unroll") for (int k = 0; k < 2; ++k) \
;         acc[ai][bj][m][n] = __builtin_amdgcn_mfma_f32_16x16x32_bf16(Bt[n][k], At[m][k], acc[ai][bj][m][n], 0, 0, 0); __builtin_amdgcn_s_setprio(0); } while (0)
; #define PG8_WAIT_V(n) asm volatile("s_waitcnt vmcnt(" #n ")" ::: "memory")
; #define PG8_WAIT_L(n) asm volatile("s_waitcnt lgkmcnt(" #n ")" ::: "memory")
; #define PG8_BAR __builtin_amdgcn_s_barrier()
; #define PG8_SCHED __builtin_amdgcn_sched_barrier(0)
; template <class Epi, class Sched, bool ATILE = false>
; __device__ __forceinline__ void gemm_phase(LAS unsigned char* lds, const Gemm g, const Sched& S, const Epi& E) {
;     ...
;             PG8_BAR; PG8_WAIT_L(0); PG8_MMA(0, 1, At, B1); PG8_BAR;
;             PG8_LDA(At, 1, 1); PG8_STAGE(PG8_SA(1, 0), a3, voffA);
;             PG8_BAR; PG8_WAIT_L(0); PG8_MMA(1, 0, At, B0); PG8_BAR; PG8_SCHED;
;             PG8_STAGE(PG8_SB(1, 1), b3 + hstepB, voffB);
;             PG8_WAIT_V(6); PG8_BAR; PG8_MMA(1, 1, At, B1); PG8_BAR;
	s_waitcnt lgkmcnt(0)
	v_mfma_f32_16x16x32_bf16 v[124:127], v[224:227], v[192:195], v[124:127]
	v_mfma_f32_16x16x32_bf16 v[120:123], v[232:235], v[192:195], v[120:123]
	v_mfma_f32_16x16x32_bf16 v[108:111], v[224:227], v[200:203], v[108:111]
	v_mfma_f32_16x16x32_bf16 v[104:107], v[232:235], v[200:203], v[104:107]
	v_mfma_f32_16x16x32_bf16 v[92:95], v[224:227], v[208:211], v[92:95]
	v_mfma_f32_16x16x32_bf16 v[88:91], v[232:235], v[208:211], v[88:91]
	v_mfma_f32_16x16x32_bf16 v[76:79], v[224:227], v[216:219], v[76:79]
	v_mfma_f32_16x16x32_bf16 v[72:75], v[232:235], v[216:219], v[72:75]
	v_mfma_f32_16x16x32_bf16 v[124:127], v[228:231], v[196:199], v[124:127]
	v_mfma_f32_16x16x32_bf16 v[120:123], v[236:239], v[196:199], v[120:123]
	v_mfma_f32_16x16x32_bf16 v[108:111], v[228:231], v[204:207], v[108:111]
	v_mfma_f32_16x16x32_bf16 v[104:107], v[236:239], v[204:207], v[104:107]
	v_mfma_f32_16x16x32_bf16 v[92:95], v[228:231], v[212:215], v[92:95]
	v_mfma_f32_16x16x32_bf16 v[88:91], v[236:239], v[212:215], v[88:91]
	v_mfma_f32_16x16x32_bf16 v[76:79], v[228:231], v[220:223], v[76:79]
	v_mfma_f32_16x16x32_bf16 v[72:75], v[236:239], v[220:223], v[72:75]
	s_barrier
	s_setprio 0
	s_mov_b32 m0, s4
	v_lshl_add_u64 v[240:241], v[244:245], 0, s[22:23]
	ds_read_b128 v[192:195], v167 offset:49152
	ds_read_b128 v[196:199], v167 offset:50176
	ds_read_b128 v[200:203], v167 offset:51200
	ds_read_b128 v[204:207], v167 offset:52224
	ds_read_b128 v[208:211], v167 offset:53248
	ds_read_b128 v[212:215], v167 offset:54272
	ds_read_b128 v[216:219], v167 offset:55296
	ds_read_b128 v[220:223], v167 offset:56320
	global_load_lds_dwordx4 v[240:241], off
	v_lshl_add_u64 v[240:241], v[246:247], 0, s[22:23]
	s_mov_b32 m0, s5
	s_nop 0
	global_load_lds_dwordx4 v[240:241], off
	s_setprio 1
	s_barrier
	s_waitcnt lgkmcnt(0)
	v_mfma_f32_16x16x32_bf16 v[68:71], v[56:59], v[192:195], v[68:71]
	v_mfma_f32_16x16x32_bf16 v[64:67], v[178:181], v[192:195], v[64:67]
	v_mfma_f32_16x16x32_bf16 v[52:55], v[56:59], v[200:203], v[52:55]
	v_mfma_f32_16x16x32_bf16 v[48:51], v[178:181], v[200:203], v[48:51]
	v_mfma_f32_16x16x32_bf16 v[28:31], v[56:59], v[208:211], v[28:31]
	v_mfma_f32_16x16x32_bf16 v[24:27], v[178:181], v[208:211], v[24:27]
	v_mfma_f32_16x16x32_bf16 v[12:15], v[56:59], v[216:219], v[12:15]
	v_mfma_f32_16x16x32_bf16 v[8:11], v[178:181], v[216:219], v[8:11]
	v_mfma_f32_16x16x32_bf16 v[68:71], v[60:63], v[196:199], v[68:71]
	v_mfma_f32_16x16x32_bf16 v[64:67], v[182:185], v[196:199], v[64:67]
	v_mfma_f32_16x16x32_bf16 v[52:55], v[60:63], v[204:207], v[52:55]
	v_mfma_f32_16x16x32_bf16 v[48:51], v[182:185], v[204:207], v[48:51]
	v_mfma_f32_16x16x32_bf16 v[28:31], v[60:63], v[212:215], v[28:31]
	v_mfma_f32_16x16x32_bf16 v[24:27], v[182:185], v[212:215], v[24:27]
	v_mfma_f32_16x16x32_bf16 v[12:15], v[60:63], v[220:223], v[12:15]
	v_mfma_f32_16x16x32_bf16 v[8:11], v[182:185], v[220:223], v[8:11]
	s_barrier
	s_setprio 0
	s_add_u32 s84, s84, 0x80080
	s_addc_u32 s85, s85, 0
	s_add_i32 s73, s86, s31
	v_lshl_add_u64 v[56:57], s[84:85], 0, v[138:139]
	s_mov_b32 m0, s73
	s_nop 0
	global_load_lds_dwordx4 v[56:57], off
	v_lshl_add_u64 v[56:57], s[84:85], 0, v[142:143]
	s_add_i32 m0, s73, 0x2000
	s_nop 0
	global_load_lds_dwordx4 v[56:57], off
	s_waitcnt vmcnt(6)
	s_setprio 1
	s_barrier
	v_mfma_f32_16x16x32_bf16 v[32:35], v[224:227], v[192:195], v[32:35]
	v_mfma_f32_16x16x32_bf16 v[60:63], v[228:231], v[196:199], v[32:35]
	v_mfma_f32_16x16x32_bf16 v[32:35], v[232:235], v[192:195], v[36:39]
	v_mfma_f32_16x16x32_bf16 v[56:59], v[236:239], v[196:199], v[32:35]
	v_mfma_f32_16x16x32_bf16 v[32:35], v[224:227], v[200:203], v[44:47]
	v_mfma_f32_16x16x32_bf16 v[44:47], v[228:231], v[204:207], v[32:35]
	v_mfma_f32_16x16x32_bf16 v[32:35], v[232:235], v[200:203], v[40:43]
	v_mfma_f32_16x16x32_bf16 v[20:23], v[224:227], v[208:211], v[20:23]
	v_mfma_f32_16x16x32_bf16 v[16:19], v[232:235], v[208:211], v[16:19]
	v_mfma_f32_16x16x32_bf16 v[4:7], v[224:227], v[216:219], v[4:7]
	v_mfma_f32_16x16x32_bf16 v[0:3], v[232:235], v[216:219], v[0:3]
	v_mfma_f32_16x16x32_bf16 v[40:43], v[236:239], v[204:207], v[32:35]
	v_mfma_f32_16x16x32_bf16 v[20:23], v[228:231], v[212:215], v[20:23]
	v_mfma_f32_16x16x32_bf16 v[16:19], v[236:239], v[212:215], v[16:19]
	v_mfma_f32_16x16x32_bf16 v[4:7], v[228:231], v[220:223], v[4:7]
	v_mfma_f32_16x16x32_bf16 v[0:3], v[236:239], v[220:223], v[0:3]
	s_barrier
	s_setprio 0
	s_add_u32 s12, s12, 0x100
	s_addc_u32 s13, s13, 0
	s_add_u32 s62, s62, 0x100
	s_addc_u32 s63, s63, 0
	s_cmp_ge_i32 s88, s1
	s_mov_b32 s73, s88
	s_cbranch_scc0 .LBB0_895
	s_branch .LBB0_897

; #define PG8_STAGE(bufoff, gbase, voff) do { _Pragma("unroll") for (int _i = 0; _i < 2; ++_i) \
;         __builtin_amdgcn_global_load_lds((const unsigned*)((const char*)(gbase) + (voff)[_i]), (LAS unsigned*)(lds + (bufoff) + ldsw + _i * 8192), 16, 0, 0); } while (0)
; #define PG8_LDA(dst, b, h) do { _Pragma("unroll") for (int m = 0; m < 4; ++m) _Pragma("unroll") for (int k = 0; k < 2; ++k) dst[m][k] = *(const LAS bf16x8*)(lds + PG8_SA(b, h) + aoff + m * 2048 + k * 1024); } while (0)
; #define PG8_LDB(dst, b, h) do { _Pragma("unroll") for (int n = 0; n < 2; ++n) _Pragma("unroll") for (int k = 0; k < 2; ++k) dst[n][k] = *(const LAS bf16x8*)(lds + PG8_SB(b, h) + boff + n * 2048 + k * 1024); } while (0)
; #define PG8_MMA(ai, bj, At, Bt) do { __builtin_amdgcn_s_setprio(1); _Pragma("unroll") for (int m = 0; m < 4; ++m) _Pragma("unroll") for (int n = 0; n < 2; ++n) _Pragma("unroll") for (int k = 0; k < 2; ++k) \
;         acc[ai][bj][m][n] = __builtin_amdgcn_mfma_f32_16x16x32_bf16(Bt[n][k], At[m][k], acc[ai][bj][m][n], 0, 0, 0); __builtin_amdgcn_s_setprio(0); } while (0)
; #define PG8_WAIT_V(n) asm volatile("s_waitcnt vmcnt(" #n ")" ::: "memory")
; #define PG8_WAIT_L(n) asm volatile("s_waitcnt lgkmcnt(" #n ")" ::: "memory")
; template <class Epi, class Sched, bool ATILE = false>
; __device__ __forceinline__ void gemm_phase(LAS unsigned char* lds, const Gemm g, const Sched& S, const Epi& E) {
;     ...
;         for (int t = 0; t < nt; t += 2) {
;             const bool last = (t == nt - 2);
;             const char* a1 = cA + (size_t)(t + 1) * kstepA;
;             const char* a2 = last ? nA : cA + (size_t)(t + 2) * kstepA; const char* b2 = last ? nB : cB + (size_t)(t + 2) * kstep;
;             const char* a3 = a2 + kstepA; const char* b3 = b2 + kstep;
;             PG8_LDB(B0, 0, 0); PG8_SCHED; PG8_LDA(At, 0, 0); PG8_STAGE(PG8_SA(1, 1), a1 + hstepA, voffA);
;             PG8_WAIT_L(8); PG8_BAR; PG8_WAIT_L(0); PG8_MMA(0, 0, At, B0); PG8_BAR; PG8_SCHED;
;             PG8_LDB(B1, 0, 1); PG8_STAGE(PG8_SB(0, 0), b2, voffB);
;             PG8_BAR; PG8_WAIT_L(0); PG8_MMA(0, 1, At, B1); PG8_BAR;
;             PG8_LDA(At, 0, 1); PG8_STAGE(PG8_SA(0, 0), a2, voffA);
;             PG8_BAR; PG8_WAIT_L(0); PG8_MMA(1, 0, At, B0); PG8_BAR; PG8_SCHED;
;             PG8_STAGE(PG8_SB(0, 1), b2 + hstepB, voffB);
;             PG8_WAIT_V(6); PG8_BAR; PG8_MMA(1, 1, At, B1); PG8_BAR;
.LBB0_1298:
	ds_read_b128 v[82:85], v79
	ds_read_b128 v[86:89], v79 offset:1024
	ds_read_b128 v[90:93], v79 offset:2048
	ds_read_b128 v[94:97], v79 offset:3072
	s_add_i32 s60, s20, 2
	s_add_u32 s18, s16, 0x100
	s_addc_u32 s19, s17, 0
	s_cmp_eq_u32 s57, s20
	s_cselect_b32 s20, s56, s58
	s_cselect_b32 s23, s9, s19
	s_cselect_b32 s22, s8, s18
	s_cselect_b32 s21, s55, s59
	s_mov_b32 m0, s38
	v_lshl_add_u64 v[130:131], s[16:17], 0, v[74:75]
	ds_read_b128 v[98:101], v80
	ds_read_b128 v[102:105], v80 offset:1024
	ds_read_b128 v[106:109], v80 offset:2048
	ds_read_b128 v[110:113], v80 offset:3072
	ds_read_b128 v[114:117], v80 offset:4096
	ds_read_b128 v[118:121], v80 offset:5120
	ds_read_b128 v[122:125], v80 offset:6144
	ds_read_b128 v[126:129], v80 offset:7168
	global_load_lds_dwordx4 v[130:131], off
	v_lshl_add_u64 v[130:131], s[16:17], 0, v[76:77]
	s_mov_b32 m0, s39
	s_nop 0
	global_load_lds_dwordx4 v[130:131], off
	s_waitcnt lgkmcnt(8)
	s_setprio 1
	s_barrier
	s_waitcnt lgkmcnt(0)
	v_mfma_f32_16x16x32_bf16 v[60:63], v[82:85], v[98:101], v[60:63]
	v_mfma_f32_16x16x32_bf16 v[56:59], v[90:93], v[98:101], v[56:59]
	v_mfma_f32_16x16x32_bf16 v[52:55], v[82:85], v[106:109], v[52:55]
	v_mfma_f32_16x16x32_bf16 v[48:51], v[90:93], v[106:109], v[48:51]
	v_mfma_f32_16x16x32_bf16 v[44:47], v[82:85], v[114:117], v[44:47]
	v_mfma_f32_16x16x32_bf16 v[40:43], v[90:93], v[114:117], v[40:43]
	v_mfma_f32_16x16x32_bf16 v[36:39], v[82:85], v[122:125], v[36:39]
	v_mfma_f32_16x16x32_bf16 v[32:35], v[90:93], v[122:125], v[32:35]
	v_mfma_f32_16x16x32_bf16 v[60:63], v[86:89], v[102:105], v[60:63]
	v_mfma_f32_16x16x32_bf16 v[56:59], v[94:97], v[102:105], v[56:59]
	v_mfma_f32_16x16x32_bf16 v[52:55], v[86:89], v[110:113], v[52:55]
	v_mfma_f32_16x16x32_bf16 v[48:51], v[94:97], v[110:113], v[48:51]
	v_mfma_f32_16x16x32_bf16 v[44:47], v[86:89], v[118:121], v[44:47]
	v_mfma_f32_16x16x32_bf16 v[40:43], v[94:97], v[118:121], v[40:43]
	v_mfma_f32_16x16x32_bf16 v[36:39], v[86:89], v[126:129], v[36:39]
	v_mfma_f32_16x16x32_bf16 v[32:35], v[94:97], v[126:129], v[32:35]
	s_barrier
	s_setprio 0
	s_mov_b32 m0, s40
	v_lshl_add_u64 v[130:131], s[20:21], 0, v[68:69]
	global_load_lds_dwordx4 v[130:131], off
	v_lshl_add_u64 v[132:133], s[20:21], 0, v[64:65]
	s_mov_b32 m0, s41
	s_nop 0
	global_load_lds_dwordx4 v[132:133], off
	s_barrier
	s_waitcnt lgkmcnt(0)
	s_setprio 1
	s_setprio 0
	s_mov_b32 m0, s25
	v_lshl_add_u64 v[134:135], s[22:23], 0, v[70:71]
	s_barrier
	ds_read_b128 v[98:101], v80 offset:16384
	ds_read_b128 v[102:105], v80 offset:17408
	ds_read_b128 v[106:109], v80 offset:18432
	ds_read_b128 v[110:113], v80 offset:19456
	ds_read_b128 v[114:117], v80 offset:20480
	ds_read_b128 v[118:121], v80 offset:21504
	ds_read_b128 v[122:125], v80 offset:22528
	ds_read_b128 v[126:129], v80 offset:23552
	global_load_lds_dwordx4 v[134:135], off
	v_lshl_add_u64 v[136:137], s[22:23], 0, v[66:67]
	s_mov_b32 m0, s26
	s_nop 0
	global_load_lds_dwordx4 v[136:137], off
	s_setprio 1
	s_barrier
	s_waitcnt lgkmcnt(0)
	v_mfma_f32_16x16x32_bf16 v[28:31], v[82:85], v[98:101], v[28:31]
	v_mfma_f32_16x16x32_bf16 v[24:27], v[90:93], v[98:101], v[24:27]
	v_mfma_f32_16x16x32_bf16 v[20:23], v[82:85], v[106:109], v[20:23]
	v_mfma_f32_16x16x32_bf16 v[16:19], v[90:93], v[106:109], v[16:19]
	v_mfma_f32_16x16x32_bf16 v[12:15], v[82:85], v[114:117], v[12:15]
	v_mfma_f32_16x16x32_bf16 v[8:11], v[90:93], v[114:117], v[8:11]
	v_mfma_f32_16x16x32_bf16 v[4:7], v[82:85], v[122:125], v[4:7]
	v_mfma_f32_16x16x32_bf16 v[0:3], v[90:93], v[122:125], v[0:3]
	v_mfma_f32_16x16x32_bf16 v[28:31], v[86:89], v[102:105], v[28:31]
	v_mfma_f32_16x16x32_bf16 v[24:27], v[94:97], v[102:105], v[24:27]
	v_mfma_f32_16x16x32_bf16 v[20:23], v[86:89], v[110:113], v[20:23]
	v_mfma_f32_16x16x32_bf16 v[16:19], v[94:97], v[110:113], v[16:19]
	v_mfma_f32_16x16x32_bf16 v[12:15], v[86:89], v[118:121], v[12:15]
	v_mfma_f32_16x16x32_bf16 v[8:11], v[94:97], v[118:121], v[8:11]
	v_mfma_f32_16x16x32_bf16 v[4:7], v[86:89], v[126:129], v[4:7]
	v_mfma_f32_16x16x32_bf16 v[0:3], v[94:97], v[126:129], v[0:3]
	s_barrier
	s_setprio 0
	s_add_u32 s16, s20, 0x10000
	s_addc_u32 s17, s21, 0
	s_mov_b32 m0, s27
	v_lshl_add_u64 v[82:83], s[16:17], 0, v[68:69]
	global_load_lds_dwordx4 v[82:83], off
	v_lshl_add_u64 v[82:83], s[16:17], 0, v[64:65]
	s_mov_b32 m0, s28
	s_nop 0
	global_load_lds_dwordx4 v[82:83], off
	s_waitcnt vmcnt(6)
	s_barrier
	s_setprio 1
	s_setprio 0
	s_barrier
; #define PG8_STAGE(bufoff, gbase, voff) do { _Pragma("unroll") for (int _i = 0; _i < 2; ++_i) \
;         __builtin_amdgcn_global_load_lds((const unsigned*)((const char*)(gbase) + (voff)[_i]), (LAS unsigned*)(lds + (bufoff) + ldsw + _i * 8192), 16, 0, 0); } while (0)
; #define PG8_LDA(dst, b, h) do { _Pragma("unroll") for (int m = 0; m < 4; ++m) _Pragma("unroll") for (int k = 0; k < 2; ++k) dst[m][k] = *(const LAS bf16x8*)(lds + PG8_SA(b, h) + aoff + m * 2048 + k * 1024); } while (0)
; #define PG8_LDB(dst, b, h) do { _Pragma("unroll") for (int n = 0; n < 2; ++n) _Pragma("unroll") for (int k = 0; k < 2; ++k) dst[n][k] = *(const LAS bf16x8*)(lds + PG8_SB(b, h) + boff + n * 2048 + k * 1024); } while (0)
; #define PG8_MMA(ai, bj, At, Bt) do { __builtin_amdgcn_s_setprio(1); _Pragma("unroll") for (int m = 0; m < 4; ++m) _Pragma("unroll") for (int n = 0; n < 2; ++n) _Pragma("unroll") for (int k = 0; k < 2; ++k) \
;         acc[ai][bj][m][n] = __builtin_amdgcn_mfma_f32_16x16x32_bf16(Bt[n][k], At[m][k], acc[ai][bj][m][n], 0, 0, 0); __builtin_amdgcn_s_setprio(0); } while (0)
; #define PG8_WAIT_V(n) asm volatile("s_waitcnt vmcnt(" #n ")" ::: "memory")
; #define PG8_WAIT_L(n) asm volatile("s_waitcnt lgkmcnt(" #n ")" ::: "memory")
; #define PG8_BAR __builtin_amdgcn_s_barrier()
; #define PG8_SCHED __builtin_amdgcn_sched_barrier(0)
; template <class Epi, class Sched, bool ATILE = false>
; __device__ __forceinline__ void gemm_phase(LAS unsigned char* lds, const Gemm g, const Sched& S, const Epi& E) {
;     ...
;             PG8_LDB(B0, 1, 0); PG8_SCHED; PG8_LDA(At, 1, 0); PG8_STAGE(PG8_SA(0, 1), a2 + hstepA, voffA);
;             PG8_WAIT_L(8); PG8_BAR; PG8_WAIT_L(0); PG8_MMA(0, 0, At, B0); PG8_BAR; PG8_SCHED;
;             PG8_LDB(B1, 1, 1); PG8_STAGE(PG8_SB(1, 0), b3, voffB);
;             PG8_BAR; PG8_WAIT_L(0); PG8_MMA(0, 1, At, B1); PG8_BAR;
;             PG8_LDA(At, 1, 1); PG8_STAGE(PG8_SA(1, 0), a3, voffA);
;             PG8_BAR; PG8_WAIT_L(0); PG8_MMA(1, 0, At, B0); PG8_BAR; PG8_SCHED;
;             PG8_STAGE(PG8_SB(1, 1), b3 + hstepB, voffB);
;             PG8_WAIT_V(6); PG8_BAR; PG8_MMA(1, 1, At, B1); PG8_BAR;
	ds_read_b128 v[82:85], v81
	ds_read_b128 v[86:89], v81 offset:1024
	ds_read_b128 v[90:93], v81 offset:2048
	ds_read_b128 v[94:97], v81 offset:3072
	s_add_u32 s16, s22, 0x18000
	s_addc_u32 s17, s23, 0
	s_mov_b32 m0, s29
	v_lshl_add_u64 v[138:139], s[16:17], 0, v[70:71]
	ds_read_b128 v[98:101], v80 offset:32768
	ds_read_b128 v[102:105], v80 offset:33792
	ds_read_b128 v[106:109], v80 offset:34816
	ds_read_b128 v[110:113], v80 offset:35840
	ds_read_b128 v[114:117], v80 offset:36864
	ds_read_b128 v[118:121], v80 offset:37888
	ds_read_b128 v[122:125], v80 offset:38912
	ds_read_b128 v[126:129], v80 offset:39936
	global_load_lds_dwordx4 v[138:139], off
	v_lshl_add_u64 v[138:139], s[16:17], 0, v[66:67]
	s_mov_b32 m0, s30
	s_nop 0
	global_load_lds_dwordx4 v[138:139], off
	s_waitcnt lgkmcnt(8)
	s_setprio 1
	s_barrier
	s_waitcnt lgkmcnt(0)
	v_mfma_f32_16x16x32_bf16 v[60:63], v[82:85], v[98:101], v[60:63]
	v_mfma_f32_16x16x32_bf16 v[56:59], v[90:93], v[98:101], v[56:59]
	v_mfma_f32_16x16x32_bf16 v[52:55], v[82:85], v[106:109], v[52:55]
	v_mfma_f32_16x16x32_bf16 v[48:51], v[90:93], v[106:109], v[48:51]
	v_mfma_f32_16x16x32_bf16 v[44:47], v[82:85], v[114:117], v[44:47]
	v_mfma_f32_16x16x32_bf16 v[40:43], v[90:93], v[114:117], v[40:43]
	v_mfma_f32_16x16x32_bf16 v[36:39], v[82:85], v[122:125], v[36:39]
	v_mfma_f32_16x16x32_bf16 v[32:35], v[90:93], v[122:125], v[32:35]
	v_mfma_f32_16x16x32_bf16 v[60:63], v[86:89], v[102:105], v[60:63]
	v_mfma_f32_16x16x32_bf16 v[56:59], v[94:97], v[102:105], v[56:59]
	v_mfma_f32_16x16x32_bf16 v[52:55], v[86:89], v[110:113], v[52:55]
	v_mfma_f32_16x16x32_bf16 v[48:51], v[94:97], v[110:113], v[48:51]
	v_mfma_f32_16x16x32_bf16 v[44:47], v[86:89], v[118:121], v[44:47]
	v_mfma_f32_16x16x32_bf16 v[40:43], v[94:97], v[118:121], v[40:43]
	v_mfma_f32_16x16x32_bf16 v[36:39], v[86:89], v[126:129], v[36:39]
	v_mfma_f32_16x16x32_bf16 v[32:35], v[94:97], v[126:129], v[32:35]
	s_barrier
	s_setprio 0
	s_mov_b32 m0, s43
	v_lshl_add_u64 v[98:99], v[130:131], 0, s[6:7]
	global_load_lds_dwordx4 v[98:99], off
	v_lshl_add_u64 v[98:99], v[132:133], 0, s[6:7]
	s_mov_b32 m0, s44
	s_nop 0
	global_load_lds_dwordx4 v[98:99], off
	s_barrier
	s_waitcnt lgkmcnt(0)
	s_setprio 1
	s_setprio 0
	s_mov_b32 m0, s34
	v_lshl_add_u64 v[130:131], v[134:135], 0, s[6:7]
	s_barrier
	ds_read_b128 v[98:101], v80 offset:49152
	ds_read_b128 v[102:105], v80 offset:50176
	ds_read_b128 v[106:109], v80 offset:51200
	ds_read_b128 v[110:113], v80 offset:52224
	ds_read_b128 v[114:117], v80 offset:53248
	ds_read_b128 v[118:121], v80 offset:54272
	ds_read_b128 v[122:125], v80 offset:55296
	ds_read_b128 v[126:129], v80 offset:56320
	global_load_lds_dwordx4 v[130:131], off
	v_lshl_add_u64 v[130:131], v[136:137], 0, s[6:7]
	s_mov_b32 m0, s35
	s_nop 0
	global_load_lds_dwordx4 v[130:131], off
	s_setprio 1
	s_barrier
	s_waitcnt lgkmcnt(0)
	v_mfma_f32_16x16x32_bf16 v[28:31], v[82:85], v[98:101], v[28:31]
	v_mfma_f32_16x16x32_bf16 v[24:27], v[90:93], v[98:101], v[24:27]
	v_mfma_f32_16x16x32_bf16 v[20:23], v[82:85], v[106:109], v[20:23]
	v_mfma_f32_16x16x32_bf16 v[16:19], v[90:93], v[106:109], v[16:19]
	v_mfma_f32_16x16x32_bf16 v[12:15], v[82:85], v[114:117], v[12:15]
	v_mfma_f32_16x16x32_bf16 v[8:11], v[90:93], v[114:117], v[8:11]
	v_mfma_f32_16x16x32_bf16 v[4:7], v[82:85], v[122:125], v[4:7]
	v_mfma_f32_16x16x32_bf16 v[0:3], v[90:93], v[122:125], v[0:3]
	v_mfma_f32_16x16x32_bf16 v[28:31], v[86:89], v[102:105], v[28:31]
	v_mfma_f32_16x16x32_bf16 v[24:27], v[94:97], v[102:105], v[24:27]
	v_mfma_f32_16x16x32_bf16 v[20:23], v[86:89], v[110:113], v[20:23]
	v_mfma_f32_16x16x32_bf16 v[16:19], v[94:97], v[110:113], v[16:19]
	v_mfma_f32_16x16x32_bf16 v[12:15], v[86:89], v[118:121], v[12:15]
	v_mfma_f32_16x16x32_bf16 v[8:11], v[94:97], v[118:121], v[8:11]
	v_mfma_f32_16x16x32_bf16 v[4:7], v[86:89], v[126:129], v[4:7]
	v_mfma_f32_16x16x32_bf16 v[0:3], v[94:97], v[126:129], v[0:3]
	s_barrier
	s_setprio 0
	s_add_u32 s16, s20, 0x10080
	s_addc_u32 s17, s21, 0
	s_mov_b32 m0, s36
	v_lshl_add_u64 v[82:83], s[16:17], 0, v[68:69]
	global_load_lds_dwordx4 v[82:83], off
	v_lshl_add_u64 v[82:83], s[16:17], 0, v[64:65]
	s_mov_b32 m0, s37
	s_nop 0
	global_load_lds_dwordx4 v[82:83], off
	s_waitcnt vmcnt(6)
	s_barrier
	s_setprio 1
	s_setprio 0
	s_add_u32 s58, s58, 0x100
	s_addc_u32 s59, s59, 0
	s_cmp_ge_i32 s60, s54
	s_mov_b64 s[16:17], s[18:19]
	s_mov_b32 s20, s60
	s_barrier
	s_cbranch_scc0 .LBB0_1298
	s_branch .LBB0_1293

; #define PG8_STAGE(bufoff, gbase, voff) do { _Pragma("unroll") for (int _i = 0; _i < 2; ++_i) \
;         __builtin_amdgcn_global_load_lds((const unsigned*)((const char*)(gbase) + (voff)[_i]), (LAS unsigned*)(lds + (bufoff) + ldsw + _i * 8192), 16, 0, 0); } while (0)
; #define PG8_LDA(dst, b, h) do { _Pragma("unroll") for (int m = 0; m < 4; ++m) _Pragma("unroll") for (int k = 0; k < 2; ++k) dst[m][k] = *(const LAS bf16x8*)(lds + PG8_SA(b, h) + aoff + m * 2048 + k * 1024); } while (0)
; #define PG8_LDB(dst, b, h) do { _Pragma("unroll") for (int n = 0; n < 2; ++n) _Pragma("unroll") for (int k = 0; k < 2; ++k) dst[n][k] = *(const LAS bf16x8*)(lds + PG8_SB(b, h) + boff + n * 2048 + k * 1024); } while (0)
; #define PG8_MMA(ai, bj, At, Bt) do { __builtin_amdgcn_s_setprio(1); _Pragma("unroll") for (int m = 0; m < 4; ++m) _Pragma("unroll") for (int n = 0; n < 2; ++n) _Pragma("unroll") for (int k = 0; k < 2; ++k) \
;         acc[ai][bj][m][n] = __builtin_amdgcn_mfma_f32_16x16x32_bf16(Bt[n][k], At[m][k], acc[ai][bj][m][n], 0, 0, 0); __builtin_amdgcn_s_setprio(0); } while (0)
; #define PG8_WAIT_L(n) asm volatile("s_waitcnt lgkmcnt(" #n ")" ::: "memory")
; #define PG8_BAR __builtin_amdgcn_s_barrier()
; #define PG8_SCHED __builtin_amdgcn_sched_barrier(0)
; template <class Epi, class Sched, bool ATILE = false>
; __device__ __forceinline__ void gemm_phase(LAS unsigned char* lds, const Gemm g, const Sched& S, const Epi& E) {
;     ...
;         for (int t = 0; t < nt; t += 2) {
;             const bool last = (t == nt - 2);
;             const char* a1 = cA + (size_t)(t + 1) * kstepA;
;             const char* a2 = last ? nA : cA + (size_t)(t + 2) * kstepA; const char* b2 = last ? nB : cB + (size_t)(t + 2) * kstep;
;             const char* a3 = a2 + kstepA; const char* b3 = b2 + kstep;
;             PG8_LDB(B0, 0, 0); PG8_SCHED; PG8_LDA(At, 0, 0); PG8_STAGE(PG8_SA(1, 1), a1 + hstepA, voffA);
;             PG8_WAIT_L(8); PG8_BAR; PG8_WAIT_L(0); PG8_MMA(0, 0, At, B0); PG8_BAR; PG8_SCHED;
;             PG8_LDB(B1, 0, 1); PG8_STAGE(PG8_SB(0, 0), b2, voffB);
;             PG8_BAR; PG8_WAIT_L(0); PG8_MMA(0, 1, At, B1); PG8_BAR;
;             PG8_LDA(At, 0, 1); PG8_STAGE(PG8_SA(0, 0), a2, voffA);
;             PG8_BAR; PG8_WAIT_L(0); PG8_MMA(1, 0, At, B0); PG8_BAR; PG8_SCHED;
.LBB0_1426:
	ds_read_b128 v[162:165], v147
	ds_read_b128 v[166:169], v147 offset:1024
	ds_read_b128 v[170:173], v147 offset:2048
	ds_read_b128 v[174:177], v147 offset:3072
	s_add_i32 s58, s18, 2
	s_add_u32 s16, s12, 0x100
	s_addc_u32 s17, s13, 0
	s_cmp_eq_u32 s55, s18
	s_cselect_b32 s18, s10, s56
	s_cselect_b32 s21, s7, s17
	s_cselect_b32 s20, s6, s16
	s_cselect_b32 s19, s11, s57
	s_mov_b32 m0, s30
	v_lshl_add_u64 v[144:145], s[12:13], 0, v[140:141]
	ds_read_b128 v[178:181], v148
	ds_read_b128 v[182:185], v148 offset:1024
	ds_read_b128 v[186:189], v148 offset:2048
	ds_read_b128 v[190:193], v148 offset:3072
	ds_read_b128 v[194:197], v148 offset:4096
	ds_read_b128 v[198:201], v148 offset:5120
	ds_read_b128 v[202:205], v148 offset:6144
	ds_read_b128 v[206:209], v148 offset:7168
	global_load_lds_dwordx4 v[144:145], off
	v_lshl_add_u64 v[144:145], s[12:13], 0, v[142:143]
	s_mov_b32 m0, s31
	s_nop 0
	global_load_lds_dwordx4 v[144:145], off
	s_waitcnt lgkmcnt(8)
	s_setprio 1
	s_barrier
	s_waitcnt lgkmcnt(0)
	v_mfma_f32_16x16x32_bf16 v[124:127], v[162:165], v[178:181], v[124:127]
	v_mfma_f32_16x16x32_bf16 v[120:123], v[170:173], v[178:181], v[120:123]
	v_mfma_f32_16x16x32_bf16 v[108:111], v[162:165], v[186:189], v[108:111]
	v_mfma_f32_16x16x32_bf16 v[104:107], v[170:173], v[186:189], v[104:107]
	v_mfma_f32_16x16x32_bf16 v[92:95], v[162:165], v[194:197], v[92:95]
	v_mfma_f32_16x16x32_bf16 v[88:91], v[170:173], v[194:197], v[88:91]
	v_mfma_f32_16x16x32_bf16 v[76:79], v[162:165], v[202:205], v[76:79]
	v_mfma_f32_16x16x32_bf16 v[72:75], v[170:173], v[202:205], v[72:75]
	v_mfma_f32_16x16x32_bf16 v[124:127], v[166:169], v[182:185], v[124:127]
	v_mfma_f32_16x16x32_bf16 v[120:123], v[174:177], v[182:185], v[120:123]
	v_mfma_f32_16x16x32_bf16 v[108:111], v[166:169], v[190:193], v[108:111]
	v_mfma_f32_16x16x32_bf16 v[104:107], v[174:177], v[190:193], v[104:107]
	v_mfma_f32_16x16x32_bf16 v[92:95], v[166:169], v[198:201], v[92:95]
	v_mfma_f32_16x16x32_bf16 v[88:91], v[174:177], v[198:201], v[88:91]
	v_mfma_f32_16x16x32_bf16 v[76:79], v[166:169], v[206:209], v[76:79]
	v_mfma_f32_16x16x32_bf16 v[72:75], v[174:177], v[206:209], v[72:75]
	s_barrier
	s_setprio 0
	s_mov_b32 m0, s33
	v_lshl_add_u64 v[144:145], s[18:19], 0, v[132:133]
	ds_read_b128 v[210:213], v149
	ds_read_b128 v[214:217], v149 offset:1024
	ds_read_b128 v[218:221], v149 offset:2048
	ds_read_b128 v[222:225], v149 offset:3072
	global_load_lds_dwordx4 v[144:145], off
	v_lshl_add_u64 v[226:227], s[18:19], 0, v[128:129]
	s_mov_b32 m0, s34
	s_nop 0
	global_load_lds_dwordx4 v[226:227], off
	s_setprio 1
	s_barrier
	s_waitcnt lgkmcnt(0)
	v_mfma_f32_16x16x32_bf16 v[116:119], v[210:213], v[178:181], v[116:119]
	v_mfma_f32_16x16x32_bf16 v[112:115], v[218:221], v[178:181], v[112:115]
	v_mfma_f32_16x16x32_bf16 v[100:103], v[210:213], v[186:189], v[100:103]
	v_mfma_f32_16x16x32_bf16 v[96:99], v[218:221], v[186:189], v[96:99]
	v_mfma_f32_16x16x32_bf16 v[84:87], v[210:213], v[194:197], v[84:87]
	v_mfma_f32_16x16x32_bf16 v[80:83], v[218:221], v[194:197], v[80:83]
	v_mfma_f32_16x16x32_bf16 v[68:71], v[210:213], v[202:205], v[68:71]
	v_mfma_f32_16x16x32_bf16 v[64:67], v[218:221], v[202:205], v[64:67]
	v_mfma_f32_16x16x32_bf16 v[116:119], v[214:217], v[182:185], v[116:119]
	v_mfma_f32_16x16x32_bf16 v[112:115], v[222:225], v[182:185], v[112:115]
	v_mfma_f32_16x16x32_bf16 v[100:103], v[214:217], v[190:193], v[100:103]
	v_mfma_f32_16x16x32_bf16 v[96:99], v[222:225], v[190:193], v[96:99]
	v_mfma_f32_16x16x32_bf16 v[84:87], v[214:217], v[198:201], v[84:87]
	v_mfma_f32_16x16x32_bf16 v[80:83], v[222:225], v[198:201], v[80:83]
	v_mfma_f32_16x16x32_bf16 v[68:71], v[214:217], v[206:209], v[68:71]
	v_mfma_f32_16x16x32_bf16 v[64:67], v[222:225], v[206:209], v[64:67]
	s_barrier
	s_setprio 0
	s_mov_b32 m0, s22
	v_lshl_add_u64 v[228:229], s[20:21], 0, v[134:135]
	ds_read_b128 v[178:181], v148 offset:16384
	ds_read_b128 v[182:185], v148 offset:17408
	ds_read_b128 v[186:189], v148 offset:18432
	ds_read_b128 v[190:193], v148 offset:19456
	ds_read_b128 v[194:197], v148 offset:20480
	ds_read_b128 v[198:201], v148 offset:21504
	ds_read_b128 v[202:205], v148 offset:22528
	ds_read_b128 v[206:209], v148 offset:23552
	global_load_lds_dwordx4 v[228:229], off
	v_lshl_add_u64 v[230:231], s[20:21], 0, v[130:131]
	s_mov_b32 m0, s23
	s_nop 0
	global_load_lds_dwordx4 v[230:231], off
	s_setprio 1
	s_barrier
	s_waitcnt lgkmcnt(0)
	v_mfma_f32_16x16x32_bf16 v[60:63], v[162:165], v[178:181], v[60:63]
	v_mfma_f32_16x16x32_bf16 v[56:59], v[170:173], v[178:181], v[56:59]
	v_mfma_f32_16x16x32_bf16 v[44:47], v[162:165], v[186:189], v[44:47]
	v_mfma_f32_16x16x32_bf16 v[40:43], v[170:173], v[186:189], v[40:43]
	v_mfma_f32_16x16x32_bf16 v[28:31], v[162:165], v[194:197], v[28:31]
	v_mfma_f32_16x16x32_bf16 v[24:27], v[170:173], v[194:197], v[24:27]
	v_mfma_f32_16x16x32_bf16 v[12:15], v[162:165], v[202:205], v[12:15]
	v_mfma_f32_16x16x32_bf16 v[8:11], v[170:173], v[202:205], v[8:11]
	v_mfma_f32_16x16x32_bf16 v[60:63], v[166:169], v[182:185], v[60:63]
	v_mfma_f32_16x16x32_bf16 v[56:59], v[174:177], v[182:185], v[56:59]
	v_mfma_f32_16x16x32_bf16 v[44:47], v[166:169], v[190:193], v[44:47]
	v_mfma_f32_16x16x32_bf16 v[40:43], v[174:177], v[190:193], v[40:43]
	v_mfma_f32_16x16x32_bf16 v[28:31], v[166:169], v[198:201], v[28:31]
	v_mfma_f32_16x16x32_bf16 v[24:27], v[174:177], v[198:201], v[24:27]
	v_mfma_f32_16x16x32_bf16 v[12:15], v[166:169], v[206:209], v[12:15]
	v_mfma_f32_16x16x32_bf16 v[8:11], v[174:177], v[206:209], v[8:11]
	s_barrier
; #define PG8_STAGE(bufoff, gbase, voff) do { _Pragma("unroll") for (int _i = 0; _i < 2; ++_i) \
;         __builtin_amdgcn_global_load_lds((const unsigned*)((const char*)(gbase) + (voff)[_i]), (LAS unsigned*)(lds + (bufoff) + ldsw + _i * 8192), 16, 0, 0); } while (0)
; #define PG8_LDA(dst, b, h) do { _Pragma("unroll") for (int m = 0; m < 4; ++m) _Pragma("unroll") for (int k = 0; k < 2; ++k) dst[m][k] = *(const LAS bf16x8*)(lds + PG8_SA(b, h) + aoff + m * 2048 + k * 1024); } while (0)
; #define PG8_LDB(dst, b, h) do { _Pragma("unroll") for (int n = 0; n < 2; ++n) _Pragma("unroll") for (int k = 0; k < 2; ++k) dst[n][k] = *(const LAS bf16x8*)(lds + PG8_SB(b, h) + boff + n * 2048 + k * 1024); } while (0)
; #define PG8_MMA(ai, bj, At, Bt) do { __builtin_amdgcn_s_setprio(1); _Pragma("unroll") for (int m = 0; m < 4; ++m) _Pragma("unroll") for (int n = 0; n < 2; ++n) _Pragma("unroll") for (int k = 0; k < 2; ++k) \
;         acc[ai][bj][m][n] = __builtin_amdgcn_mfma_f32_16x16x32_bf16(Bt[n][k], At[m][k], acc[ai][bj][m][n], 0, 0, 0); __builtin_amdgcn_s_setprio(0); } while (0)
; #define PG8_WAIT_V(n) asm volatile("s_waitcnt vmcnt(" #n ")" ::: "memory")
; #define PG8_WAIT_L(n) asm volatile("s_waitcnt lgkmcnt(" #n ")" ::: "memory")
; #define PG8_BAR __builtin_amdgcn_s_barrier()
; #define PG8_SCHED __builtin_amdgcn_sched_barrier(0)
; template <class Epi, class Sched, bool ATILE = false>
; __device__ __forceinline__ void gemm_phase(LAS unsigned char* lds, const Gemm g, const Sched& S, const Epi& E) {
;     ...
;             PG8_BAR; PG8_WAIT_L(0); PG8_MMA(1, 0, At, B0); PG8_BAR; PG8_SCHED;
;             PG8_STAGE(PG8_SB(0, 1), b2 + hstepB, voffB);
;             PG8_WAIT_V(6); PG8_BAR; PG8_MMA(1, 1, At, B1); PG8_BAR;
;             PG8_LDB(B0, 1, 0); PG8_SCHED; PG8_LDA(At, 1, 0); PG8_STAGE(PG8_SA(0, 1), a2 + hstepA, voffA);
;             PG8_WAIT_L(8); PG8_BAR; PG8_WAIT_L(0); PG8_MMA(0, 0, At, B0); PG8_BAR; PG8_SCHED;
;             PG8_LDB(B1, 1, 1); PG8_STAGE(PG8_SB(1, 0), b3, voffB);
;             PG8_BAR; PG8_WAIT_L(0); PG8_MMA(0, 1, At, B1); PG8_BAR;
	s_setprio 0
	s_add_u32 s12, s18, 0x18000
	s_addc_u32 s13, s19, 0
	s_mov_b32 m0, s35
	v_lshl_add_u64 v[162:163], s[12:13], 0, v[132:133]
	global_load_lds_dwordx4 v[162:163], off
	v_lshl_add_u64 v[162:163], s[12:13], 0, v[128:129]
	s_mov_b32 m0, s36
	s_nop 0
	global_load_lds_dwordx4 v[162:163], off
	s_waitcnt vmcnt(6)
	s_setprio 1
	s_barrier
	v_mfma_f32_16x16x32_bf16 v[52:55], v[210:213], v[178:181], v[52:55]
	v_mfma_f32_16x16x32_bf16 v[48:51], v[218:221], v[178:181], v[48:51]
	v_mfma_f32_16x16x32_bf16 v[36:39], v[210:213], v[186:189], v[36:39]
	v_mfma_f32_16x16x32_bf16 v[32:35], v[218:221], v[186:189], v[32:35]
	v_mfma_f32_16x16x32_bf16 v[20:23], v[210:213], v[194:197], v[20:23]
	v_mfma_f32_16x16x32_bf16 v[16:19], v[218:221], v[194:197], v[16:19]
	v_mfma_f32_16x16x32_bf16 v[4:7], v[210:213], v[202:205], v[4:7]
	v_mfma_f32_16x16x32_bf16 v[0:3], v[218:221], v[202:205], v[0:3]
	v_mfma_f32_16x16x32_bf16 v[52:55], v[214:217], v[182:185], v[52:55]
	v_mfma_f32_16x16x32_bf16 v[48:51], v[222:225], v[182:185], v[48:51]
	v_mfma_f32_16x16x32_bf16 v[36:39], v[214:217], v[190:193], v[36:39]
	v_mfma_f32_16x16x32_bf16 v[32:35], v[222:225], v[190:193], v[32:35]
	v_mfma_f32_16x16x32_bf16 v[20:23], v[214:217], v[198:201], v[20:23]
	v_mfma_f32_16x16x32_bf16 v[16:19], v[222:225], v[198:201], v[16:19]
	v_mfma_f32_16x16x32_bf16 v[4:7], v[214:217], v[206:209], v[4:7]
	v_mfma_f32_16x16x32_bf16 v[0:3], v[222:225], v[206:209], v[0:3]
	s_barrier
	s_setprio 0
	ds_read_b128 v[162:165], v150
	ds_read_b128 v[166:169], v150 offset:1024
	ds_read_b128 v[170:173], v150 offset:2048
	ds_read_b128 v[174:177], v150 offset:3072
	s_add_u32 s12, s20, 0x18000
	s_addc_u32 s13, s21, 0
	s_mov_b32 m0, s24
	v_lshl_add_u64 v[210:211], s[12:13], 0, v[134:135]
	ds_read_b128 v[178:181], v148 offset:32768
	ds_read_b128 v[182:185], v148 offset:33792
	ds_read_b128 v[186:189], v148 offset:34816
	ds_read_b128 v[190:193], v148 offset:35840
	ds_read_b128 v[194:197], v148 offset:36864
	ds_read_b128 v[198:201], v148 offset:37888
	ds_read_b128 v[202:205], v148 offset:38912
	ds_read_b128 v[206:209], v148 offset:39936
	global_load_lds_dwordx4 v[210:211], off
	v_lshl_add_u64 v[210:211], s[12:13], 0, v[130:131]
	s_mov_b32 m0, s25
	s_nop 0
	global_load_lds_dwordx4 v[210:211], off
	s_waitcnt lgkmcnt(8)
	s_setprio 1
	s_barrier
	s_waitcnt lgkmcnt(0)
	v_mfma_f32_16x16x32_bf16 v[124:127], v[162:165], v[178:181], v[124:127]
	v_mfma_f32_16x16x32_bf16 v[120:123], v[170:173], v[178:181], v[120:123]
	v_mfma_f32_16x16x32_bf16 v[108:111], v[162:165], v[186:189], v[108:111]
	v_mfma_f32_16x16x32_bf16 v[104:107], v[170:173], v[186:189], v[104:107]
	v_mfma_f32_16x16x32_bf16 v[92:95], v[162:165], v[194:197], v[92:95]
	v_mfma_f32_16x16x32_bf16 v[88:91], v[170:173], v[194:197], v[88:91]
	v_mfma_f32_16x16x32_bf16 v[76:79], v[162:165], v[202:205], v[76:79]
	v_mfma_f32_16x16x32_bf16 v[72:75], v[170:173], v[202:205], v[72:75]
	v_mfma_f32_16x16x32_bf16 v[124:127], v[166:169], v[182:185], v[124:127]
	v_mfma_f32_16x16x32_bf16 v[120:123], v[174:177], v[182:185], v[120:123]
	v_mfma_f32_16x16x32_bf16 v[108:111], v[166:169], v[190:193], v[108:111]
	v_mfma_f32_16x16x32_bf16 v[104:107], v[174:177], v[190:193], v[104:107]
	v_mfma_f32_16x16x32_bf16 v[92:95], v[166:169], v[198:201], v[92:95]
	v_mfma_f32_16x16x32_bf16 v[88:91], v[174:177], v[198:201], v[88:91]
	v_mfma_f32_16x16x32_bf16 v[76:79], v[166:169], v[206:209], v[76:79]
	v_mfma_f32_16x16x32_bf16 v[72:75], v[174:177], v[206:209], v[72:75]
	s_barrier
	s_setprio 0
	s_mov_b32 m0, s40
	v_lshl_add_u64 v[144:145], v[144:145], 0, s[0:1]
	ds_read_b128 v[210:213], v157
	ds_read_b128 v[214:217], v157 offset:1024
	ds_read_b128 v[218:221], v157 offset:2048
	ds_read_b128 v[222:225], v157 offset:3072
	global_load_lds_dwordx4 v[144:145], off
	v_lshl_add_u64 v[144:145], v[226:227], 0, s[0:1]
	s_mov_b32 m0, s41
	s_nop 0
	global_load_lds_dwordx4 v[144:145], off
	s_setprio 1
	s_barrier
; #define PG8_STAGE(bufoff, gbase, voff) do { _Pragma("unroll") for (int _i = 0; _i < 2; ++_i) \
;         __builtin_amdgcn_global_load_lds((const unsigned*)((const char*)(gbase) + (voff)[_i]), (LAS unsigned*)(lds + (bufoff) + ldsw + _i * 8192), 16, 0, 0); } while (0)
; #define PG8_LDA(dst, b, h) do { _Pragma("unroll") for (int m = 0; m < 4; ++m) _Pragma("unroll") for (int k = 0; k < 2; ++k) dst[m][k] = *(const LAS bf16x8*)(lds + PG8_SA(b, h) + aoff + m * 2048 + k * 1024); } while (0)
; #define PG8_MMA(ai, bj, At, Bt) do { __builtin_amdgcn_s_setprio(1); _Pragma("unroll") for (int m = 0; m < 4; ++m) _Pragma("unroll") for (int n = 0; n < 2; ++n) _Pragma("unroll") for (int k = 0; k < 2; ++k) \
;         acc[ai][bj][m][n] = __builtin_amdgcn_mfma_f32_16x16x32_bf16(Bt[n][k], At[m][k], acc[ai][bj][m][n], 0, 0, 0); __builtin_amdgcn_s_setprio(0); } while (0)
; #define PG8_WAIT_V(n) asm volatile("s_waitcnt vmcnt(" #n ")" ::: "memory")
; #define PG8_WAIT_L(n) asm volatile("s_waitcnt lgkmcnt(" #n ")" ::: "memory")
; #define PG8_BAR __builtin_amdgcn_s_barrier()
; #define PG8_SCHED __builtin_amdgcn_sched_barrier(0)
; template <class Epi, class Sched, bool ATILE = false>
; __device__ __forceinline__ void gemm_phase(LAS unsigned char* lds, const Gemm g, const Sched& S, const Epi& E) {
;     ...
;             PG8_BAR; PG8_WAIT_L(0); PG8_MMA(0, 1, At, B1); PG8_BAR;
;             PG8_LDA(At, 1, 1); PG8_STAGE(PG8_SA(1, 0), a3, voffA);
;             PG8_BAR; PG8_WAIT_L(0); PG8_MMA(1, 0, At, B0); PG8_BAR; PG8_SCHED;
;             PG8_STAGE(PG8_SB(1, 1), b3 + hstepB, voffB);
;             PG8_WAIT_V(6); PG8_BAR; PG8_MMA(1, 1, At, B1); PG8_BAR;
	s_waitcnt lgkmcnt(0)
	v_mfma_f32_16x16x32_bf16 v[116:119], v[210:213], v[178:181], v[116:119]
	v_mfma_f32_16x16x32_bf16 v[112:115], v[218:221], v[178:181], v[112:115]
	v_mfma_f32_16x16x32_bf16 v[100:103], v[210:213], v[186:189], v[100:103]
	v_mfma_f32_16x16x32_bf16 v[96:99], v[218:221], v[186:189], v[96:99]
	v_mfma_f32_16x16x32_bf16 v[84:87], v[210:213], v[194:197], v[84:87]
	v_mfma_f32_16x16x32_bf16 v[80:83], v[218:221], v[194:197], v[80:83]
	v_mfma_f32_16x16x32_bf16 v[68:71], v[210:213], v[202:205], v[68:71]
	v_mfma_f32_16x16x32_bf16 v[64:67], v[218:221], v[202:205], v[64:67]
	v_mfma_f32_16x16x32_bf16 v[116:119], v[214:217], v[182:185], v[116:119]
	v_mfma_f32_16x16x32_bf16 v[112:115], v[222:225], v[182:185], v[112:115]
	v_mfma_f32_16x16x32_bf16 v[100:103], v[214:217], v[190:193], v[100:103]
	v_mfma_f32_16x16x32_bf16 v[96:99], v[222:225], v[190:193], v[96:99]
	v_mfma_f32_16x16x32_bf16 v[84:87], v[214:217], v[198:201], v[84:87]
	v_mfma_f32_16x16x32_bf16 v[80:83], v[222:225], v[198:201], v[80:83]
	v_mfma_f32_16x16x32_bf16 v[68:71], v[214:217], v[206:209], v[68:71]
	v_mfma_f32_16x16x32_bf16 v[64:67], v[222:225], v[206:209], v[64:67]
	s_barrier
	s_setprio 0
	s_mov_b32 m0, s28
	v_lshl_add_u64 v[144:145], v[228:229], 0, s[0:1]
	ds_read_b128 v[178:181], v148 offset:49152
	ds_read_b128 v[182:185], v148 offset:50176
	ds_read_b128 v[186:189], v148 offset:51200
	ds_read_b128 v[190:193], v148 offset:52224
	ds_read_b128 v[194:197], v148 offset:53248
	ds_read_b128 v[198:201], v148 offset:54272
	ds_read_b128 v[202:205], v148 offset:55296
	ds_read_b128 v[206:209], v148 offset:56320
	global_load_lds_dwordx4 v[144:145], off
	v_lshl_add_u64 v[144:145], v[230:231], 0, s[0:1]
	s_mov_b32 m0, s29
	s_nop 0
	global_load_lds_dwordx4 v[144:145], off
	s_setprio 1
	s_barrier
	s_waitcnt lgkmcnt(0)
	v_mfma_f32_16x16x32_bf16 v[60:63], v[162:165], v[178:181], v[60:63]
	v_mfma_f32_16x16x32_bf16 v[56:59], v[170:173], v[178:181], v[56:59]
	v_mfma_f32_16x16x32_bf16 v[44:47], v[162:165], v[186:189], v[44:47]
	v_mfma_f32_16x16x32_bf16 v[40:43], v[170:173], v[186:189], v[40:43]
	v_mfma_f32_16x16x32_bf16 v[28:31], v[162:165], v[194:197], v[28:31]
	v_mfma_f32_16x16x32_bf16 v[24:27], v[170:173], v[194:197], v[24:27]
	v_mfma_f32_16x16x32_bf16 v[12:15], v[162:165], v[202:205], v[12:15]
	v_mfma_f32_16x16x32_bf16 v[8:11], v[170:173], v[202:205], v[8:11]
	v_mfma_f32_16x16x32_bf16 v[60:63], v[166:169], v[182:185], v[60:63]
	v_mfma_f32_16x16x32_bf16 v[56:59], v[174:177], v[182:185], v[56:59]
	v_mfma_f32_16x16x32_bf16 v[44:47], v[166:169], v[190:193], v[44:47]
	v_mfma_f32_16x16x32_bf16 v[40:43], v[174:177], v[190:193], v[40:43]
	v_mfma_f32_16x16x32_bf16 v[28:31], v[166:169], v[198:201], v[28:31]
	v_mfma_f32_16x16x32_bf16 v[24:27], v[174:177], v[198:201], v[24:27]
	v_mfma_f32_16x16x32_bf16 v[12:15], v[166:169], v[206:209], v[12:15]
	v_mfma_f32_16x16x32_bf16 v[8:11], v[174:177], v[206:209], v[8:11]
	s_barrier
	s_setprio 0
	s_add_u32 s12, s18, 0x18080
	s_addc_u32 s13, s19, 0
	s_mov_b32 m0, s42
	v_lshl_add_u64 v[144:145], s[12:13], 0, v[132:133]
	global_load_lds_dwordx4 v[144:145], off
	v_lshl_add_u64 v[144:145], s[12:13], 0, v[128:129]
	s_mov_b32 m0, s43
	s_nop 0
	global_load_lds_dwordx4 v[144:145], off
	s_waitcnt vmcnt(6)
	s_setprio 1
	s_barrier
	v_mfma_f32_16x16x32_bf16 v[52:55], v[210:213], v[178:181], v[52:55]
	v_mfma_f32_16x16x32_bf16 v[48:51], v[218:221], v[178:181], v[48:51]
	v_mfma_f32_16x16x32_bf16 v[36:39], v[210:213], v[186:189], v[36:39]
	v_mfma_f32_16x16x32_bf16 v[32:35], v[218:221], v[186:189], v[32:35]
	v_mfma_f32_16x16x32_bf16 v[20:23], v[210:213], v[194:197], v[20:23]
	v_mfma_f32_16x16x32_bf16 v[16:19], v[218:221], v[194:197], v[16:19]
	v_mfma_f32_16x16x32_bf16 v[4:7], v[210:213], v[202:205], v[4:7]
	v_mfma_f32_16x16x32_bf16 v[0:3], v[218:221], v[202:205], v[0:3]
	v_mfma_f32_16x16x32_bf16 v[52:55], v[214:217], v[182:185], v[52:55]
	v_mfma_f32_16x16x32_bf16 v[48:51], v[222:225], v[182:185], v[48:51]
	v_mfma_f32_16x16x32_bf16 v[36:39], v[214:217], v[190:193], v[36:39]
	v_mfma_f32_16x16x32_bf16 v[32:35], v[222:225], v[190:193], v[32:35]
	v_mfma_f32_16x16x32_bf16 v[20:23], v[214:217], v[198:201], v[20:23]
	v_mfma_f32_16x16x32_bf16 v[16:19], v[222:225], v[198:201], v[16:19]
	v_mfma_f32_16x16x32_bf16 v[4:7], v[214:217], v[206:209], v[4:7]
	v_mfma_f32_16x16x32_bf16 v[0:3], v[222:225], v[206:209], v[0:3]
	s_barrier
	s_setprio 0
	s_add_u32 s56, s56, 0x100
	s_addc_u32 s57, s57, 0
	s_cmp_ge_i32 s58, s54
	s_mov_b64 s[12:13], s[16:17]
	s_mov_b32 s18, s58
	s_cbranch_scc0 .LBB0_1426
	s_branch .LBB0_1428

; #define PG8_STAGE(bufoff, gbase, voff) do { _Pragma("unroll") for (int _i = 0; _i < 2; ++_i) \
;         __builtin_amdgcn_global_load_lds((const unsigned*)((const char*)(gbase) + (voff)[_i]), (LAS unsigned*)(lds + (bufoff) + ldsw + _i * 8192), 16, 0, 0); } while (0)
; #define PG8_LDA(dst, b, h) do { _Pragma("unroll") for (int m = 0; m < 4; ++m) _Pragma("unroll") for (int k = 0; k < 2; ++k) dst[m][k] = *(const LAS bf16x8*)(lds + PG8_SA(b, h) + aoff + m * 2048 + k * 1024); } while (0)
; #define PG8_LDB(dst, b, h) do { _Pragma("unroll") for (int n = 0; n < 2; ++n) _Pragma("unroll") for (int k = 0; k < 2; ++k) dst[n][k] = *(const LAS bf16x8*)(lds + PG8_SB(b, h) + boff + n * 2048 + k * 1024); } while (0)
; #define PG8_MMA(ai, bj, At, Bt) do { __builtin_amdgcn_s_setprio(1); _Pragma("unroll") for (int m = 0; m < 4; ++m) _Pragma("unroll") for (int n = 0; n < 2; ++n) _Pragma("unroll") for (int k = 0; k < 2; ++k) \
;         acc[ai][bj][m][n] = __builtin_amdgcn_mfma_f32_16x16x32_bf16(Bt[n][k], At[m][k], acc[ai][bj][m][n], 0, 0, 0); __builtin_amdgcn_s_setprio(0); } while (0)
; #define PG8_WAIT_L(n) asm volatile("s_waitcnt lgkmcnt(" #n ")" ::: "memory")
; #define PG8_BAR __builtin_amdgcn_s_barrier()
; #define PG8_SCHED __builtin_amdgcn_sched_barrier(0)
; template <class Epi, class Sched, bool ATILE = false>
; __device__ __forceinline__ void gemm_phase(LAS unsigned char* lds, const Gemm g, const Sched& S, const Epi& E) {
;     ...
;         for (int t = 0; t < nt; t += 2) {
;             const bool last = (t == nt - 2);
;             const char* a1 = cA + (size_t)(t + 1) * kstepA;
;             const char* a2 = last ? nA : cA + (size_t)(t + 2) * kstepA; const char* b2 = last ? nB : cB + (size_t)(t + 2) * kstep;
;             const char* a3 = a2 + kstepA; const char* b3 = b2 + kstep;
;             PG8_LDB(B0, 0, 0); PG8_SCHED; PG8_LDA(At, 0, 0); PG8_STAGE(PG8_SA(1, 1), a1 + hstepA, voffA);
;             PG8_WAIT_L(8); PG8_BAR; PG8_WAIT_L(0); PG8_MMA(0, 0, At, B0); PG8_BAR; PG8_SCHED;
;             PG8_LDB(B1, 0, 1); PG8_STAGE(PG8_SB(0, 0), b2, voffB);
;             PG8_BAR; PG8_WAIT_L(0); PG8_MMA(0, 1, At, B1); PG8_BAR;
;             PG8_LDA(At, 0, 1); PG8_STAGE(PG8_SA(0, 0), a2, voffA);
;             PG8_BAR; PG8_WAIT_L(0); PG8_MMA(1, 0, At, B0); PG8_BAR; PG8_SCHED;
.LBB0_1517:
	ds_read_b128 v[96:99], v182
	ds_read_b128 v[100:103], v182 offset:1024
	ds_read_b128 v[112:115], v182 offset:2048
	ds_read_b128 v[116:119], v182 offset:3072
	s_add_i32 s54, s26, 2
	s_add_u32 s27, s24, 0xfffc0080
	s_addc_u32 s28, s25, -1
	s_cmp_eq_u32 s45, s26
	s_cselect_b32 s26, s44, s52
	s_cselect_b32 s29, s17, s28
	s_cselect_b32 s28, s42, s27
	s_cselect_b32 s27, s43, s53
	v_lshl_add_u64 v[206:207], s[24:25], 0, v[166:167]
	s_add_i32 m0, s23, 0xc000
	ds_read_b128 v[144:147], v183
	ds_read_b128 v[174:177], v183 offset:1024
	ds_read_b128 v[178:181], v183 offset:2048
	ds_read_b128 v[186:189], v183 offset:3072
	ds_read_b128 v[190:193], v183 offset:4096
	ds_read_b128 v[194:197], v183 offset:5120
	ds_read_b128 v[198:201], v183 offset:6144
	ds_read_b128 v[202:205], v183 offset:7168
	global_load_lds_dwordx4 v[206:207], off
	v_lshl_add_u64 v[206:207], s[24:25], 0, v[168:169]
	s_add_i32 m0, s23, 0xe000
	s_nop 0
	global_load_lds_dwordx4 v[206:207], off
	s_waitcnt lgkmcnt(8)
	s_setprio 1
	s_barrier
	s_waitcnt lgkmcnt(0)
	v_mfma_f32_16x16x32_bf16 v[140:143], v[96:99], v[144:147], v[140:143]
	v_mfma_f32_16x16x32_bf16 v[136:139], v[112:115], v[144:147], v[136:139]
	v_mfma_f32_16x16x32_bf16 v[124:127], v[96:99], v[178:181], v[124:127]
	v_mfma_f32_16x16x32_bf16 v[120:123], v[112:115], v[178:181], v[120:123]
	v_mfma_f32_16x16x32_bf16 v[92:95], v[96:99], v[190:193], v[92:95]
	v_mfma_f32_16x16x32_bf16 v[88:91], v[112:115], v[190:193], v[88:91]
	v_mfma_f32_16x16x32_bf16 v[76:79], v[96:99], v[198:201], v[76:79]
	v_mfma_f32_16x16x32_bf16 v[72:75], v[112:115], v[198:201], v[72:75]
	v_mfma_f32_16x16x32_bf16 v[140:143], v[100:103], v[174:177], v[140:143]
	v_mfma_f32_16x16x32_bf16 v[136:139], v[116:119], v[174:177], v[136:139]
	v_mfma_f32_16x16x32_bf16 v[124:127], v[100:103], v[186:189], v[124:127]
	v_mfma_f32_16x16x32_bf16 v[120:123], v[116:119], v[186:189], v[120:123]
	v_mfma_f32_16x16x32_bf16 v[92:95], v[100:103], v[194:197], v[92:95]
	v_mfma_f32_16x16x32_bf16 v[88:91], v[116:119], v[194:197], v[88:91]
	v_mfma_f32_16x16x32_bf16 v[76:79], v[100:103], v[202:205], v[76:79]
	v_mfma_f32_16x16x32_bf16 v[72:75], v[116:119], v[202:205], v[72:75]
	s_barrier
	s_setprio 0
	s_add_i32 s55, s39, s5
	v_lshl_add_u64 v[222:223], s[26:27], 0, v[150:151]
	s_mov_b32 m0, s55
	ds_read_b128 v[206:209], v184
	ds_read_b128 v[210:213], v184 offset:1024
	ds_read_b128 v[214:217], v184 offset:2048
	ds_read_b128 v[218:221], v184 offset:3072
	global_load_lds_dwordx4 v[222:223], off
	v_lshl_add_u64 v[224:225], s[26:27], 0, v[164:165]
	s_add_i32 m0, s55, 0x2000
	s_nop 0
	global_load_lds_dwordx4 v[224:225], off
	s_setprio 1
	s_barrier
	s_waitcnt lgkmcnt(0)
	v_mfma_f32_16x16x32_bf16 v[132:135], v[206:209], v[144:147], v[132:135]
	v_mfma_f32_16x16x32_bf16 v[128:131], v[214:217], v[144:147], v[128:131]
	v_mfma_f32_16x16x32_bf16 v[108:111], v[206:209], v[178:181], v[108:111]
	v_mfma_f32_16x16x32_bf16 v[104:107], v[214:217], v[178:181], v[104:107]
	v_mfma_f32_16x16x32_bf16 v[84:87], v[206:209], v[190:193], v[84:87]
	v_mfma_f32_16x16x32_bf16 v[80:83], v[214:217], v[190:193], v[80:83]
	v_mfma_f32_16x16x32_bf16 v[68:71], v[206:209], v[198:201], v[68:71]
	v_mfma_f32_16x16x32_bf16 v[64:67], v[214:217], v[198:201], v[64:67]
	v_mfma_f32_16x16x32_bf16 v[132:135], v[210:213], v[174:177], v[132:135]
	v_mfma_f32_16x16x32_bf16 v[128:131], v[218:221], v[174:177], v[128:131]
	v_mfma_f32_16x16x32_bf16 v[108:111], v[210:213], v[186:189], v[108:111]
	v_mfma_f32_16x16x32_bf16 v[104:107], v[218:221], v[186:189], v[104:107]
	v_mfma_f32_16x16x32_bf16 v[84:87], v[210:213], v[194:197], v[84:87]
	v_mfma_f32_16x16x32_bf16 v[80:83], v[218:221], v[194:197], v[80:83]
	v_mfma_f32_16x16x32_bf16 v[68:71], v[210:213], v[202:205], v[68:71]
	v_mfma_f32_16x16x32_bf16 v[64:67], v[218:221], v[202:205], v[64:67]
	s_barrier
	s_setprio 0
	s_mov_b32 m0, s23
	v_lshl_add_u64 v[226:227], s[28:29], 0, v[148:149]
	ds_read_b128 v[144:147], v183 offset:16384
	ds_read_b128 v[174:177], v183 offset:17408
	ds_read_b128 v[178:181], v183 offset:18432
	ds_read_b128 v[186:189], v183 offset:19456
	ds_read_b128 v[190:193], v183 offset:20480
	ds_read_b128 v[194:197], v183 offset:21504
	ds_read_b128 v[198:201], v183 offset:22528
	ds_read_b128 v[202:205], v183 offset:23552
	global_load_lds_dwordx4 v[226:227], off
	v_lshl_add_u64 v[228:229], s[28:29], 0, v[162:163]
	s_mov_b32 m0, s30
	s_nop 0
	global_load_lds_dwordx4 v[228:229], off
	s_setprio 1
	s_barrier
	s_waitcnt lgkmcnt(0)
	v_mfma_f32_16x16x32_bf16 v[60:63], v[96:99], v[144:147], v[60:63]
	v_mfma_f32_16x16x32_bf16 v[56:59], v[112:115], v[144:147], v[56:59]
	v_mfma_f32_16x16x32_bf16 v[44:47], v[96:99], v[178:181], v[44:47]
	v_mfma_f32_16x16x32_bf16 v[40:43], v[112:115], v[178:181], v[40:43]
	v_mfma_f32_16x16x32_bf16 v[28:31], v[96:99], v[190:193], v[28:31]
	v_mfma_f32_16x16x32_bf16 v[24:27], v[112:115], v[190:193], v[24:27]
	v_mfma_f32_16x16x32_bf16 v[12:15], v[96:99], v[198:201], v[12:15]
	v_mfma_f32_16x16x32_bf16 v[8:11], v[112:115], v[198:201], v[8:11]
	v_mfma_f32_16x16x32_bf16 v[60:63], v[100:103], v[174:177], v[60:63]
	v_mfma_f32_16x16x32_bf16 v[56:59], v[116:119], v[174:177], v[56:59]
	v_mfma_f32_16x16x32_bf16 v[44:47], v[100:103], v[186:189], v[44:47]
	v_mfma_f32_16x16x32_bf16 v[40:43], v[116:119], v[186:189], v[40:43]
	v_mfma_f32_16x16x32_bf16 v[28:31], v[100:103], v[194:197], v[28:31]
	v_mfma_f32_16x16x32_bf16 v[24:27], v[116:119], v[194:197], v[24:27]
	v_mfma_f32_16x16x32_bf16 v[12:15], v[100:103], v[202:205], v[12:15]
	v_mfma_f32_16x16x32_bf16 v[8:11], v[116:119], v[202:205], v[8:11]
	s_barrier
; #define PG8_STAGE(bufoff, gbase, voff) do { _Pragma("unroll") for (int _i = 0; _i < 2; ++_i) \
;         __builtin_amdgcn_global_load_lds((const unsigned*)((const char*)(gbase) + (voff)[_i]), (LAS unsigned*)(lds + (bufoff) + ldsw + _i * 8192), 16, 0, 0); } while (0)
; #define PG8_LDA(dst, b, h) do { _Pragma("unroll") for (int m = 0; m < 4; ++m) _Pragma("unroll") for (int k = 0; k < 2; ++k) dst[m][k] = *(const LAS bf16x8*)(lds + PG8_SA(b, h) + aoff + m * 2048 + k * 1024); } while (0)
; #define PG8_LDB(dst, b, h) do { _Pragma("unroll") for (int n = 0; n < 2; ++n) _Pragma("unroll") for (int k = 0; k < 2; ++k) dst[n][k] = *(const LAS bf16x8*)(lds + PG8_SB(b, h) + boff + n * 2048 + k * 1024); } while (0)
; #define PG8_MMA(ai, bj, At, Bt) do { __builtin_amdgcn_s_setprio(1); _Pragma("unroll") for (int m = 0; m < 4; ++m) _Pragma("unroll") for (int n = 0; n < 2; ++n) _Pragma("unroll") for (int k = 0; k < 2; ++k) \
;         acc[ai][bj][m][n] = __builtin_amdgcn_mfma_f32_16x16x32_bf16(Bt[n][k], At[m][k], acc[ai][bj][m][n], 0, 0, 0); __builtin_amdgcn_s_setprio(0); } while (0)
; #define PG8_WAIT_V(n) asm volatile("s_waitcnt vmcnt(" #n ")" ::: "memory")
; #define PG8_WAIT_L(n) asm volatile("s_waitcnt lgkmcnt(" #n ")" ::: "memory")
; #define PG8_BAR __builtin_amdgcn_s_barrier()
; #define PG8_SCHED __builtin_amdgcn_sched_barrier(0)
; template <class Epi, class Sched, bool ATILE = false>
; __device__ __forceinline__ void gemm_phase(LAS unsigned char* lds, const Gemm g, const Sched& S, const Epi& E) {
;     ...
;             PG8_BAR; PG8_WAIT_L(0); PG8_MMA(1, 0, At, B0); PG8_BAR; PG8_SCHED;
;             PG8_STAGE(PG8_SB(0, 1), b2 + hstepB, voffB);
;             PG8_WAIT_V(6); PG8_BAR; PG8_MMA(1, 1, At, B1); PG8_BAR;
;             PG8_LDB(B0, 1, 0); PG8_SCHED; PG8_LDA(At, 1, 0); PG8_STAGE(PG8_SA(0, 1), a2 + hstepA, voffA);
;             PG8_WAIT_L(8); PG8_BAR; PG8_WAIT_L(0); PG8_MMA(0, 0, At, B0); PG8_BAR; PG8_SCHED;
;             PG8_LDB(B1, 1, 1); PG8_STAGE(PG8_SB(1, 0), b3, voffB);
;             PG8_BAR; PG8_WAIT_L(0); PG8_MMA(0, 1, At, B1); PG8_BAR;
	s_setprio 0
	s_add_u32 s56, s26, 0x40000
	s_addc_u32 s57, s27, 0
	s_add_i32 s55, s40, s5
	v_lshl_add_u64 v[96:97], s[56:57], 0, v[150:151]
	s_mov_b32 m0, s55
	s_nop 0
	global_load_lds_dwordx4 v[96:97], off
	v_lshl_add_u64 v[96:97], s[56:57], 0, v[164:165]
	s_add_i32 m0, s55, 0x2000
	s_nop 0
	global_load_lds_dwordx4 v[96:97], off
	s_waitcnt vmcnt(6)
	s_setprio 1
	s_barrier
	v_mfma_f32_16x16x32_bf16 v[52:55], v[206:209], v[144:147], v[52:55]
	v_mfma_f32_16x16x32_bf16 v[48:51], v[214:217], v[144:147], v[48:51]
	v_mfma_f32_16x16x32_bf16 v[36:39], v[206:209], v[178:181], v[36:39]
	v_mfma_f32_16x16x32_bf16 v[32:35], v[214:217], v[178:181], v[32:35]
	v_mfma_f32_16x16x32_bf16 v[20:23], v[206:209], v[190:193], v[20:23]
	v_mfma_f32_16x16x32_bf16 v[16:19], v[214:217], v[190:193], v[16:19]
	v_mfma_f32_16x16x32_bf16 v[4:7], v[206:209], v[198:201], v[4:7]
	v_mfma_f32_16x16x32_bf16 v[0:3], v[214:217], v[198:201], v[0:3]
	v_mfma_f32_16x16x32_bf16 v[52:55], v[210:213], v[174:177], v[52:55]
	v_mfma_f32_16x16x32_bf16 v[48:51], v[218:221], v[174:177], v[48:51]
	v_mfma_f32_16x16x32_bf16 v[36:39], v[210:213], v[186:189], v[36:39]
	v_mfma_f32_16x16x32_bf16 v[32:35], v[218:221], v[186:189], v[32:35]
	v_mfma_f32_16x16x32_bf16 v[20:23], v[210:213], v[194:197], v[20:23]
	v_mfma_f32_16x16x32_bf16 v[16:19], v[218:221], v[194:197], v[16:19]
	v_mfma_f32_16x16x32_bf16 v[4:7], v[210:213], v[202:205], v[4:7]
	v_mfma_f32_16x16x32_bf16 v[0:3], v[218:221], v[202:205], v[0:3]
	s_barrier
	s_setprio 0
	s_add_i32 s55, 0, 0x18000
	v_add_u32_e32 v116, s55, v159
	ds_read_b128 v[96:99], v116
	ds_read_b128 v[100:103], v116 offset:1024
	ds_read_b128 v[112:115], v116 offset:2048
	ds_read_b128 v[116:119], v116 offset:3072
	s_add_u32 s28, s28, 0x40000
	s_addc_u32 s29, s29, 0
	s_mov_b32 m0, s31
	v_lshl_add_u64 v[206:207], s[28:29], 0, v[148:149]
	ds_read_b128 v[144:147], v183 offset:32768
	ds_read_b128 v[174:177], v183 offset:33792
	ds_read_b128 v[178:181], v183 offset:34816
	ds_read_b128 v[186:189], v183 offset:35840
	ds_read_b128 v[190:193], v183 offset:36864
	ds_read_b128 v[194:197], v183 offset:37888
	ds_read_b128 v[198:201], v183 offset:38912
	ds_read_b128 v[202:205], v183 offset:39936
	global_load_lds_dwordx4 v[206:207], off
	v_lshl_add_u64 v[206:207], s[28:29], 0, v[162:163]
	s_mov_b32 m0, s33
	s_nop 0
	global_load_lds_dwordx4 v[206:207], off
	s_waitcnt lgkmcnt(8)
	s_setprio 1
	s_barrier
	s_waitcnt lgkmcnt(0)
	v_mfma_f32_16x16x32_bf16 v[140:143], v[96:99], v[144:147], v[140:143]
	v_mfma_f32_16x16x32_bf16 v[136:139], v[112:115], v[144:147], v[136:139]
	v_mfma_f32_16x16x32_bf16 v[124:127], v[96:99], v[178:181], v[124:127]
	v_mfma_f32_16x16x32_bf16 v[120:123], v[112:115], v[178:181], v[120:123]
	v_mfma_f32_16x16x32_bf16 v[92:95], v[96:99], v[190:193], v[92:95]
	v_mfma_f32_16x16x32_bf16 v[88:91], v[112:115], v[190:193], v[88:91]
	v_mfma_f32_16x16x32_bf16 v[76:79], v[96:99], v[198:201], v[76:79]
	v_mfma_f32_16x16x32_bf16 v[72:75], v[112:115], v[198:201], v[72:75]
	v_mfma_f32_16x16x32_bf16 v[140:143], v[100:103], v[174:177], v[140:143]
	v_mfma_f32_16x16x32_bf16 v[136:139], v[116:119], v[174:177], v[136:139]
	v_mfma_f32_16x16x32_bf16 v[124:127], v[100:103], v[186:189], v[124:127]
	v_mfma_f32_16x16x32_bf16 v[120:123], v[116:119], v[186:189], v[120:123]
	v_mfma_f32_16x16x32_bf16 v[92:95], v[100:103], v[194:197], v[92:95]
	v_mfma_f32_16x16x32_bf16 v[88:91], v[116:119], v[194:197], v[88:91]
	v_mfma_f32_16x16x32_bf16 v[76:79], v[100:103], v[202:205], v[76:79]
	v_mfma_f32_16x16x32_bf16 v[72:75], v[116:119], v[202:205], v[72:75]
	s_barrier
	s_setprio 0
	s_add_i32 s28, 0, 0x1c000
	s_add_i32 s29, s55, s5
	v_add_u32_e32 v185, s28, v159
	v_lshl_add_u64 v[222:223], v[222:223], 0, s[10:11]
	s_mov_b32 m0, s29
	ds_read_b128 v[206:209], v185
	ds_read_b128 v[210:213], v185 offset:1024
	ds_read_b128 v[214:217], v185 offset:2048
	ds_read_b128 v[218:221], v185 offset:3072
	global_load_lds_dwordx4 v[222:223], off
	v_lshl_add_u64 v[222:223], v[224:225], 0, s[10:11]
	s_add_i32 m0, s29, 0x2000
	s_nop 0
	global_load_lds_dwordx4 v[222:223], off
	s_setprio 1
	s_barrier
; #define PG8_STAGE(bufoff, gbase, voff) do { _Pragma("unroll") for (int _i = 0; _i < 2; ++_i) \
;         __builtin_amdgcn_global_load_lds((const unsigned*)((const char*)(gbase) + (voff)[_i]), (LAS unsigned*)(lds + (bufoff) + ldsw + _i * 8192), 16, 0, 0); } while (0)
; #define PG8_LDA(dst, b, h) do { _Pragma("unroll") for (int m = 0; m < 4; ++m) _Pragma("unroll") for (int k = 0; k < 2; ++k) dst[m][k] = *(const LAS bf16x8*)(lds + PG8_SA(b, h) + aoff + m * 2048 + k * 1024); } while (0)
; #define PG8_MMA(ai, bj, At, Bt) do { __builtin_amdgcn_s_setprio(1); _Pragma("unroll") for (int m = 0; m < 4; ++m) _Pragma("unroll") for (int n = 0; n < 2; ++n) _Pragma("unroll") for (int k = 0; k < 2; ++k) \
;         acc[ai][bj][m][n] = __builtin_amdgcn_mfma_f32_16x16x32_bf16(Bt[n][k], At[m][k], acc[ai][bj][m][n], 0, 0, 0); __builtin_amdgcn_s_setprio(0); } while (0)
; #define PG8_WAIT_V(n) asm volatile("s_waitcnt vmcnt(" #n ")" ::: "memory")
; #define PG8_WAIT_L(n) asm volatile("s_waitcnt lgkmcnt(" #n ")" ::: "memory")
; #define PG8_BAR __builtin_amdgcn_s_barrier()
; #define PG8_SCHED __builtin_amdgcn_sched_barrier(0)
; template <class Epi, class Sched, bool ATILE = false>
; __device__ __forceinline__ void gemm_phase(LAS unsigned char* lds, const Gemm g, const Sched& S, const Epi& E) {
;     ...
;             PG8_BAR; PG8_WAIT_L(0); PG8_MMA(0, 1, At, B1); PG8_BAR;
;             PG8_LDA(At, 1, 1); PG8_STAGE(PG8_SA(1, 0), a3, voffA);
;             PG8_BAR; PG8_WAIT_L(0); PG8_MMA(1, 0, At, B0); PG8_BAR; PG8_SCHED;
;             PG8_STAGE(PG8_SB(1, 1), b3 + hstepB, voffB);
;             PG8_WAIT_V(6); PG8_BAR; PG8_MMA(1, 1, At, B1); PG8_BAR;
	s_waitcnt lgkmcnt(0)
	v_mfma_f32_16x16x32_bf16 v[132:135], v[206:209], v[144:147], v[132:135]
	v_mfma_f32_16x16x32_bf16 v[128:131], v[214:217], v[144:147], v[128:131]
	v_mfma_f32_16x16x32_bf16 v[108:111], v[206:209], v[178:181], v[108:111]
	v_mfma_f32_16x16x32_bf16 v[104:107], v[214:217], v[178:181], v[104:107]
	v_mfma_f32_16x16x32_bf16 v[84:87], v[206:209], v[190:193], v[84:87]
	v_mfma_f32_16x16x32_bf16 v[80:83], v[214:217], v[190:193], v[80:83]
	v_mfma_f32_16x16x32_bf16 v[68:71], v[206:209], v[198:201], v[68:71]
	v_mfma_f32_16x16x32_bf16 v[64:67], v[214:217], v[198:201], v[64:67]
	v_mfma_f32_16x16x32_bf16 v[132:135], v[210:213], v[174:177], v[132:135]
	v_mfma_f32_16x16x32_bf16 v[128:131], v[218:221], v[174:177], v[128:131]
	v_mfma_f32_16x16x32_bf16 v[108:111], v[210:213], v[186:189], v[108:111]
	v_mfma_f32_16x16x32_bf16 v[104:107], v[218:221], v[186:189], v[104:107]
	v_mfma_f32_16x16x32_bf16 v[84:87], v[210:213], v[194:197], v[84:87]
	v_mfma_f32_16x16x32_bf16 v[80:83], v[218:221], v[194:197], v[80:83]
	v_mfma_f32_16x16x32_bf16 v[68:71], v[210:213], v[202:205], v[68:71]
	v_mfma_f32_16x16x32_bf16 v[64:67], v[218:221], v[202:205], v[64:67]
	s_barrier
	s_setprio 0
	s_mov_b32 m0, s35
	v_lshl_add_u64 v[222:223], v[226:227], 0, s[10:11]
	ds_read_b128 v[144:147], v183 offset:49152
	ds_read_b128 v[174:177], v183 offset:50176
	ds_read_b128 v[178:181], v183 offset:51200
	ds_read_b128 v[186:189], v183 offset:52224
	ds_read_b128 v[190:193], v183 offset:53248
	ds_read_b128 v[194:197], v183 offset:54272
	ds_read_b128 v[198:201], v183 offset:55296
	ds_read_b128 v[202:205], v183 offset:56320
	global_load_lds_dwordx4 v[222:223], off
	v_lshl_add_u64 v[222:223], v[228:229], 0, s[10:11]
	s_mov_b32 m0, s36
	s_nop 0
	global_load_lds_dwordx4 v[222:223], off
	s_setprio 1
	s_barrier
	s_waitcnt lgkmcnt(0)
	v_mfma_f32_16x16x32_bf16 v[60:63], v[96:99], v[144:147], v[60:63]
	v_mfma_f32_16x16x32_bf16 v[56:59], v[112:115], v[144:147], v[56:59]
	v_mfma_f32_16x16x32_bf16 v[44:47], v[96:99], v[178:181], v[44:47]
	v_mfma_f32_16x16x32_bf16 v[40:43], v[112:115], v[178:181], v[40:43]
	v_mfma_f32_16x16x32_bf16 v[28:31], v[96:99], v[190:193], v[28:31]
	v_mfma_f32_16x16x32_bf16 v[24:27], v[112:115], v[190:193], v[24:27]
	v_mfma_f32_16x16x32_bf16 v[12:15], v[96:99], v[198:201], v[12:15]
	v_mfma_f32_16x16x32_bf16 v[8:11], v[112:115], v[198:201], v[8:11]
	v_mfma_f32_16x16x32_bf16 v[60:63], v[100:103], v[174:177], v[60:63]
	v_mfma_f32_16x16x32_bf16 v[56:59], v[116:119], v[174:177], v[56:59]
	v_mfma_f32_16x16x32_bf16 v[44:47], v[100:103], v[186:189], v[44:47]
	v_mfma_f32_16x16x32_bf16 v[40:43], v[116:119], v[186:189], v[40:43]
	v_mfma_f32_16x16x32_bf16 v[28:31], v[100:103], v[194:197], v[28:31]
	v_mfma_f32_16x16x32_bf16 v[24:27], v[116:119], v[194:197], v[24:27]
	v_mfma_f32_16x16x32_bf16 v[12:15], v[100:103], v[202:205], v[12:15]
	v_mfma_f32_16x16x32_bf16 v[8:11], v[116:119], v[202:205], v[8:11]
	s_barrier
	s_setprio 0
	s_add_u32 s26, s26, 0x40080
	s_addc_u32 s27, s27, 0
	s_add_i32 s28, s28, s5
	v_lshl_add_u64 v[96:97], s[26:27], 0, v[150:151]
	s_mov_b32 m0, s28
	s_nop 0
	global_load_lds_dwordx4 v[96:97], off
	v_lshl_add_u64 v[96:97], s[26:27], 0, v[164:165]
	s_add_i32 m0, s28, 0x2000
	s_nop 0
	global_load_lds_dwordx4 v[96:97], off
	s_waitcnt vmcnt(6)
	s_setprio 1
	s_barrier
	v_mfma_f32_16x16x32_bf16 v[52:55], v[206:209], v[144:147], v[52:55]
	v_mfma_f32_16x16x32_bf16 v[48:51], v[214:217], v[144:147], v[48:51]
	v_mfma_f32_16x16x32_bf16 v[36:39], v[206:209], v[178:181], v[36:39]
	v_mfma_f32_16x16x32_bf16 v[32:35], v[214:217], v[178:181], v[32:35]
	v_mfma_f32_16x16x32_bf16 v[20:23], v[206:209], v[190:193], v[20:23]
	v_mfma_f32_16x16x32_bf16 v[16:19], v[214:217], v[190:193], v[16:19]
	v_mfma_f32_16x16x32_bf16 v[4:7], v[206:209], v[198:201], v[4:7]
	v_mfma_f32_16x16x32_bf16 v[0:3], v[214:217], v[198:201], v[0:3]
	v_mfma_f32_16x16x32_bf16 v[52:55], v[210:213], v[174:177], v[52:55]
	v_mfma_f32_16x16x32_bf16 v[48:51], v[218:221], v[174:177], v[48:51]
	v_mfma_f32_16x16x32_bf16 v[36:39], v[210:213], v[186:189], v[36:39]
	v_mfma_f32_16x16x32_bf16 v[32:35], v[218:221], v[186:189], v[32:35]
	v_mfma_f32_16x16x32_bf16 v[20:23], v[210:213], v[194:197], v[20:23]
	v_mfma_f32_16x16x32_bf16 v[16:19], v[218:221], v[194:197], v[16:19]
	v_mfma_f32_16x16x32_bf16 v[4:7], v[210:213], v[202:205], v[4:7]
	v_mfma_f32_16x16x32_bf16 v[0:3], v[218:221], v[202:205], v[0:3]
	s_barrier
	s_setprio 0
	s_add_u32 s24, s24, 0x100
	s_addc_u32 s25, s25, 0
	s_add_u32 s52, s52, 0x100
	s_addc_u32 s53, s53, 0
	s_cmp_ge_i32 s54, s13
	s_mov_b32 s26, s54
	s_cbranch_scc0 .LBB0_1517
	s_branch .LBB0_1508

; #define PG8_STAGE(bufoff, gbase, voff) do { _Pragma("unroll") for (int _i = 0; _i < 2; ++_i) \
;         __builtin_amdgcn_global_load_lds((const unsigned*)((const char*)(gbase) + (voff)[_i]), (LAS unsigned*)(lds + (bufoff) + ldsw + _i * 8192), 16, 0, 0); } while (0)
; #define PG8_LDA(dst, b, h) do { _Pragma("unroll") for (int m = 0; m < 4; ++m) _Pragma("unroll") for (int k = 0; k < 2; ++k) dst[m][k] = *(const LAS bf16x8*)(lds + PG8_SA(b, h) + aoff + m * 2048 + k * 1024); } while (0)
; #define PG8_LDB(dst, b, h) do { _Pragma("unroll") for (int n = 0; n < 2; ++n) _Pragma("unroll") for (int k = 0; k < 2; ++k) dst[n][k] = *(const LAS bf16x8*)(lds + PG8_SB(b, h) + boff + n * 2048 + k * 1024); } while (0)
; #define PG8_MMA(ai, bj, At, Bt) do { __builtin_amdgcn_s_setprio(1); _Pragma("unroll") for (int m = 0; m < 4; ++m) _Pragma("unroll") for (int n = 0; n < 2; ++n) _Pragma("unroll") for (int k = 0; k < 2; ++k) \
;         acc[ai][bj][m][n] = __builtin_amdgcn_mfma_f32_16x16x32_bf16(Bt[n][k], At[m][k], acc[ai][bj][m][n], 0, 0, 0); __builtin_amdgcn_s_setprio(0); } while (0)
; #define PG8_WAIT_L(n) asm volatile("s_waitcnt lgkmcnt(" #n ")" ::: "memory")
; #define PG8_BAR __builtin_amdgcn_s_barrier()
; #define PG8_SCHED __builtin_amdgcn_sched_barrier(0)
; template <class Epi, class Sched, bool ATILE = false>
; __device__ __forceinline__ void gemm_phase(LAS unsigned char* lds, const Gemm g, const Sched& S, const Epi& E) {
;     ...
;         for (int t = 0; t < nt; t += 2) {
;             const bool last = (t == nt - 2);
;             const char* a1 = cA + (size_t)(t + 1) * kstepA;
;             const char* a2 = last ? nA : cA + (size_t)(t + 2) * kstepA; const char* b2 = last ? nB : cB + (size_t)(t + 2) * kstep;
;             const char* a3 = a2 + kstepA; const char* b3 = b2 + kstep;
;             PG8_LDB(B0, 0, 0); PG8_SCHED; PG8_LDA(At, 0, 0); PG8_STAGE(PG8_SA(1, 1), a1 + hstepA, voffA);
;             PG8_WAIT_L(8); PG8_BAR; PG8_WAIT_L(0); PG8_MMA(0, 0, At, B0); PG8_BAR; PG8_SCHED;
;             PG8_LDB(B1, 0, 1); PG8_STAGE(PG8_SB(0, 0), b2, voffB);
;             PG8_BAR; PG8_WAIT_L(0); PG8_MMA(0, 1, At, B1); PG8_BAR;
;             PG8_LDA(At, 0, 1); PG8_STAGE(PG8_SA(0, 0), a2, voffA);
;             PG8_BAR; PG8_WAIT_L(0); PG8_MMA(1, 0, At, B0); PG8_BAR; PG8_SCHED;
.LBB0_1658:
	s_waitcnt lgkmcnt(0)
	ds_read_b128 v[128:131], v169
	ds_read_b128 v[132:135], v169 offset:1024
	ds_read_b128 v[136:139], v169 offset:2048
	ds_read_b128 v[140:143], v169 offset:3072
	s_add_i32 s29, s27, 2
	s_add_u32 s34, s30, 0x4000
	s_addc_u32 s35, s31, 0
	s_cmp_eq_u32 s11, s27
	s_cselect_b32 s38, s22, s34
	s_cselect_b32 s39, s23, s35
	s_cselect_b32 s34, s24, s13
	s_cselect_b32 s35, s25, s17
	s_add_u32 s36, s38, 0x8000
	s_addc_u32 s37, s39, 0
	v_lshl_add_u64 v[208:209], s[30:31], 0, v[186:187]
	s_add_i32 m0, s5, 0xc000
	ds_read_b128 v[144:147], v210
	ds_read_b128 v[148:151], v210 offset:1024
	ds_read_b128 v[192:195], v210 offset:2048
	ds_read_b128 v[196:199], v210 offset:3072
	ds_read_b128 v[200:203], v210 offset:4096
	ds_read_b128 v[204:207], v210 offset:5120
	ds_read_b128 v[214:217], v210 offset:6144
	ds_read_b128 v[218:221], v210 offset:7168
	global_load_lds_dwordx4 v[208:209], off
	v_lshl_add_u64 v[208:209], s[30:31], 0, v[188:189]
	s_add_i32 m0, s5, 0xe000
	s_nop 0
	global_load_lds_dwordx4 v[208:209], off
	s_waitcnt lgkmcnt(8)
	s_setprio 1
	s_barrier
	s_waitcnt lgkmcnt(0)
	v_mfma_f32_16x16x32_bf16 v[120:123], v[128:131], v[144:147], v[120:123]
	v_mfma_f32_16x16x32_bf16 v[116:119], v[136:139], v[144:147], v[116:119]
	v_mfma_f32_16x16x32_bf16 v[108:111], v[128:131], v[192:195], v[108:111]
	v_mfma_f32_16x16x32_bf16 v[100:103], v[136:139], v[192:195], v[100:103]
	v_mfma_f32_16x16x32_bf16 v[92:95], v[128:131], v[200:203], v[92:95]
	v_mfma_f32_16x16x32_bf16 v[84:87], v[136:139], v[200:203], v[84:87]
	v_mfma_f32_16x16x32_bf16 v[76:79], v[128:131], v[214:217], v[76:79]
	v_mfma_f32_16x16x32_bf16 v[68:71], v[136:139], v[214:217], v[68:71]
	v_mfma_f32_16x16x32_bf16 v[120:123], v[132:135], v[148:151], v[120:123]
	v_mfma_f32_16x16x32_bf16 v[116:119], v[140:143], v[148:151], v[116:119]
	v_mfma_f32_16x16x32_bf16 v[108:111], v[132:135], v[196:199], v[108:111]
	v_mfma_f32_16x16x32_bf16 v[100:103], v[140:143], v[196:199], v[100:103]
	v_mfma_f32_16x16x32_bf16 v[92:95], v[132:135], v[204:207], v[92:95]
	v_mfma_f32_16x16x32_bf16 v[84:87], v[140:143], v[204:207], v[84:87]
	v_mfma_f32_16x16x32_bf16 v[76:79], v[132:135], v[218:221], v[76:79]
	v_mfma_f32_16x16x32_bf16 v[68:71], v[140:143], v[218:221], v[68:71]
	s_barrier
	s_setprio 0
	s_add_i32 s27, s52, s4
	v_lshl_add_u64 v[208:209], s[34:35], 0, v[162:163]
	s_mov_b32 m0, s27
	ds_read_b128 v[222:225], v211
	ds_read_b128 v[226:229], v211 offset:1024
	ds_read_b128 v[230:233], v211 offset:2048
	ds_read_b128 v[234:237], v211 offset:3072
	global_load_lds_dwordx4 v[208:209], off
	v_lshl_add_u64 v[238:239], s[34:35], 0, v[166:167]
	s_add_i32 m0, s27, 0x2000
	s_nop 0
	global_load_lds_dwordx4 v[238:239], off
	s_setprio 1
	s_barrier
	s_waitcnt lgkmcnt(0)
	v_mfma_f32_16x16x32_bf16 v[124:127], v[222:225], v[144:147], v[124:127]
	v_mfma_f32_16x16x32_bf16 v[112:115], v[230:233], v[144:147], v[112:115]
	v_mfma_f32_16x16x32_bf16 v[104:107], v[222:225], v[192:195], v[104:107]
	v_mfma_f32_16x16x32_bf16 v[96:99], v[230:233], v[192:195], v[96:99]
	v_mfma_f32_16x16x32_bf16 v[88:91], v[222:225], v[200:203], v[88:91]
	v_mfma_f32_16x16x32_bf16 v[80:83], v[230:233], v[200:203], v[80:83]
	v_mfma_f32_16x16x32_bf16 v[72:75], v[222:225], v[214:217], v[72:75]
	v_mfma_f32_16x16x32_bf16 v[64:67], v[230:233], v[214:217], v[64:67]
	v_mfma_f32_16x16x32_bf16 v[124:127], v[226:229], v[148:151], v[124:127]
	v_mfma_f32_16x16x32_bf16 v[112:115], v[234:237], v[148:151], v[112:115]
	v_mfma_f32_16x16x32_bf16 v[104:107], v[226:229], v[196:199], v[104:107]
	v_mfma_f32_16x16x32_bf16 v[96:99], v[234:237], v[196:199], v[96:99]
	v_mfma_f32_16x16x32_bf16 v[88:91], v[226:229], v[204:207], v[88:91]
	v_mfma_f32_16x16x32_bf16 v[80:83], v[234:237], v[204:207], v[80:83]
	v_mfma_f32_16x16x32_bf16 v[72:75], v[226:229], v[218:221], v[72:75]
	v_mfma_f32_16x16x32_bf16 v[64:67], v[234:237], v[218:221], v[64:67]
	s_barrier
	s_setprio 0
	s_mov_b32 m0, s5
	v_lshl_add_u64 v[240:241], s[38:39], 0, v[160:161]
	ds_read_b128 v[144:147], v210 offset:16384
	ds_read_b128 v[148:151], v210 offset:17408
	ds_read_b128 v[192:195], v210 offset:18432
	ds_read_b128 v[196:199], v210 offset:19456
	ds_read_b128 v[200:203], v210 offset:20480
	ds_read_b128 v[204:207], v210 offset:21504
	ds_read_b128 v[214:217], v210 offset:22528
	ds_read_b128 v[218:221], v210 offset:23552
	global_load_lds_dwordx4 v[240:241], off
	v_lshl_add_u64 v[240:241], s[38:39], 0, v[164:165]
	s_mov_b32 m0, s33
	s_nop 0
	global_load_lds_dwordx4 v[240:241], off
	s_setprio 1
	s_barrier
	s_waitcnt lgkmcnt(0)
	v_mfma_f32_16x16x32_bf16 v[60:63], v[128:131], v[144:147], v[60:63]
	v_mfma_f32_16x16x32_bf16 v[56:59], v[136:139], v[144:147], v[56:59]
	v_mfma_f32_16x16x32_bf16 v[44:47], v[128:131], v[192:195], v[44:47]
	v_mfma_f32_16x16x32_bf16 v[40:43], v[136:139], v[192:195], v[40:43]
	v_mfma_f32_16x16x32_bf16 v[28:31], v[128:131], v[200:203], v[28:31]
	v_mfma_f32_16x16x32_bf16 v[24:27], v[136:139], v[200:203], v[24:27]
	v_mfma_f32_16x16x32_bf16 v[12:15], v[128:131], v[214:217], v[12:15]
	v_mfma_f32_16x16x32_bf16 v[8:11], v[136:139], v[214:217], v[8:11]
	v_mfma_f32_16x16x32_bf16 v[60:63], v[132:135], v[148:151], v[60:63]
	v_mfma_f32_16x16x32_bf16 v[56:59], v[140:143], v[148:151], v[56:59]
	v_mfma_f32_16x16x32_bf16 v[44:47], v[132:135], v[196:199], v[44:47]
	v_mfma_f32_16x16x32_bf16 v[40:43], v[140:143], v[196:199], v[40:43]
	v_mfma_f32_16x16x32_bf16 v[28:31], v[132:135], v[204:207], v[28:31]
	v_mfma_f32_16x16x32_bf16 v[24:27], v[140:143], v[204:207], v[24:27]
	v_mfma_f32_16x16x32_bf16 v[12:15], v[132:135], v[218:221], v[12:15]
	v_mfma_f32_16x16x32_bf16 v[8:11], v[140:143], v[218:221], v[8:11]
	s_barrier
; #define PG8_STAGE(bufoff, gbase, voff) do { _Pragma("unroll") for (int _i = 0; _i < 2; ++_i) \
;         __builtin_amdgcn_global_load_lds((const unsigned*)((const char*)(gbase) + (voff)[_i]), (LAS unsigned*)(lds + (bufoff) + ldsw + _i * 8192), 16, 0, 0); } while (0)
; #define PG8_LDA(dst, b, h) do { _Pragma("unroll") for (int m = 0; m < 4; ++m) _Pragma("unroll") for (int k = 0; k < 2; ++k) dst[m][k] = *(const LAS bf16x8*)(lds + PG8_SA(b, h) + aoff + m * 2048 + k * 1024); } while (0)
; #define PG8_LDB(dst, b, h) do { _Pragma("unroll") for (int n = 0; n < 2; ++n) _Pragma("unroll") for (int k = 0; k < 2; ++k) dst[n][k] = *(const LAS bf16x8*)(lds + PG8_SB(b, h) + boff + n * 2048 + k * 1024); } while (0)
; #define PG8_MMA(ai, bj, At, Bt) do { __builtin_amdgcn_s_setprio(1); _Pragma("unroll") for (int m = 0; m < 4; ++m) _Pragma("unroll") for (int n = 0; n < 2; ++n) _Pragma("unroll") for (int k = 0; k < 2; ++k) \
;         acc[ai][bj][m][n] = __builtin_amdgcn_mfma_f32_16x16x32_bf16(Bt[n][k], At[m][k], acc[ai][bj][m][n], 0, 0, 0); __builtin_amdgcn_s_setprio(0); } while (0)
; #define PG8_WAIT_V(n) asm volatile("s_waitcnt vmcnt(" #n ")" ::: "memory")
; #define PG8_WAIT_L(n) asm volatile("s_waitcnt lgkmcnt(" #n ")" ::: "memory")
; #define PG8_BAR __builtin_amdgcn_s_barrier()
; #define PG8_SCHED __builtin_amdgcn_sched_barrier(0)
; template <class Epi, class Sched, bool ATILE = false>
; __device__ __forceinline__ void gemm_phase(LAS unsigned char* lds, const Gemm g, const Sched& S, const Epi& E) {
;     ...
;             PG8_BAR; PG8_WAIT_L(0); PG8_MMA(1, 0, At, B0); PG8_BAR; PG8_SCHED;
;             PG8_STAGE(PG8_SB(0, 1), b2 + hstepB, voffB);
;             PG8_WAIT_V(6); PG8_BAR; PG8_MMA(1, 1, At, B1); PG8_BAR;
;             PG8_LDB(B0, 1, 0); PG8_SCHED; PG8_LDA(At, 1, 0); PG8_STAGE(PG8_SA(0, 1), a2 + hstepA, voffA);
;             PG8_WAIT_L(8); PG8_BAR; PG8_WAIT_L(0); PG8_MMA(0, 0, At, B0); PG8_BAR; PG8_SCHED;
;             PG8_LDB(B1, 1, 1); PG8_STAGE(PG8_SB(1, 0), b3, voffB);
;             PG8_BAR; PG8_WAIT_L(0); PG8_MMA(0, 1, At, B1); PG8_BAR;
	s_setprio 0
	s_add_u32 s56, s34, 0x80000
	s_addc_u32 s57, s35, 0
	s_add_i32 s27, s53, s4
	v_lshl_add_u64 v[128:129], s[56:57], 0, v[162:163]
	s_mov_b32 m0, s27
	s_nop 0
	global_load_lds_dwordx4 v[128:129], off
	v_lshl_add_u64 v[128:129], s[56:57], 0, v[166:167]
	s_add_i32 m0, s27, 0x2000
	s_nop 0
	global_load_lds_dwordx4 v[128:129], off
	s_waitcnt vmcnt(6)
	s_setprio 1
	s_barrier
	v_mfma_f32_16x16x32_bf16 v[52:55], v[222:225], v[144:147], v[52:55]
	v_mfma_f32_16x16x32_bf16 v[48:51], v[230:233], v[144:147], v[48:51]
	v_mfma_f32_16x16x32_bf16 v[36:39], v[222:225], v[192:195], v[36:39]
	v_mfma_f32_16x16x32_bf16 v[32:35], v[230:233], v[192:195], v[32:35]
	v_mfma_f32_16x16x32_bf16 v[20:23], v[222:225], v[200:203], v[20:23]
	v_mfma_f32_16x16x32_bf16 v[16:19], v[230:233], v[200:203], v[16:19]
	v_mfma_f32_16x16x32_bf16 v[4:7], v[222:225], v[214:217], v[4:7]
	v_mfma_f32_16x16x32_bf16 v[0:3], v[230:233], v[214:217], v[0:3]
	v_mfma_f32_16x16x32_bf16 v[52:55], v[226:229], v[148:151], v[52:55]
	v_mfma_f32_16x16x32_bf16 v[48:51], v[234:237], v[148:151], v[48:51]
	v_mfma_f32_16x16x32_bf16 v[36:39], v[226:229], v[196:199], v[36:39]
	v_mfma_f32_16x16x32_bf16 v[32:35], v[234:237], v[196:199], v[32:35]
	v_mfma_f32_16x16x32_bf16 v[20:23], v[226:229], v[204:207], v[20:23]
	v_mfma_f32_16x16x32_bf16 v[16:19], v[234:237], v[204:207], v[16:19]
	v_mfma_f32_16x16x32_bf16 v[4:7], v[226:229], v[218:221], v[4:7]
	v_mfma_f32_16x16x32_bf16 v[0:3], v[234:237], v[218:221], v[0:3]
	s_barrier
	s_setprio 0
	s_add_i32 s27, 0, 0x18000
	v_add_u32_e32 v140, s27, v157
	ds_read_b128 v[128:131], v140
	ds_read_b128 v[132:135], v140 offset:1024
	ds_read_b128 v[136:139], v140 offset:2048
	ds_read_b128 v[140:143], v140 offset:3072
	s_add_u32 s38, s38, 0x4000
	s_addc_u32 s39, s39, 0
	s_mov_b32 m0, s40
	v_lshl_add_u64 v[222:223], s[38:39], 0, v[160:161]
	ds_read_b128 v[144:147], v210 offset:32768
	ds_read_b128 v[148:151], v210 offset:33792
	ds_read_b128 v[192:195], v210 offset:34816
	ds_read_b128 v[196:199], v210 offset:35840
	ds_read_b128 v[200:203], v210 offset:36864
	ds_read_b128 v[204:207], v210 offset:37888
	ds_read_b128 v[214:217], v210 offset:38912
	ds_read_b128 v[218:221], v210 offset:39936
	global_load_lds_dwordx4 v[222:223], off
	v_lshl_add_u64 v[222:223], s[38:39], 0, v[164:165]
	s_mov_b32 m0, s41
	s_nop 0
	global_load_lds_dwordx4 v[222:223], off
	s_waitcnt lgkmcnt(8)
	s_setprio 1
	s_barrier
	s_waitcnt lgkmcnt(0)
	v_mfma_f32_16x16x32_bf16 v[120:123], v[128:131], v[144:147], v[120:123]
	v_mfma_f32_16x16x32_bf16 v[116:119], v[136:139], v[144:147], v[116:119]
	v_mfma_f32_16x16x32_bf16 v[108:111], v[128:131], v[192:195], v[108:111]
	v_mfma_f32_16x16x32_bf16 v[100:103], v[136:139], v[192:195], v[100:103]
	v_mfma_f32_16x16x32_bf16 v[92:95], v[128:131], v[200:203], v[92:95]
	v_mfma_f32_16x16x32_bf16 v[84:87], v[136:139], v[200:203], v[84:87]
	v_mfma_f32_16x16x32_bf16 v[76:79], v[128:131], v[214:217], v[76:79]
	v_mfma_f32_16x16x32_bf16 v[68:71], v[136:139], v[214:217], v[68:71]
	v_mfma_f32_16x16x32_bf16 v[120:123], v[132:135], v[148:151], v[120:123]
	v_mfma_f32_16x16x32_bf16 v[116:119], v[140:143], v[148:151], v[116:119]
	v_mfma_f32_16x16x32_bf16 v[108:111], v[132:135], v[196:199], v[108:111]
	v_mfma_f32_16x16x32_bf16 v[100:103], v[140:143], v[196:199], v[100:103]
	v_mfma_f32_16x16x32_bf16 v[92:95], v[132:135], v[204:207], v[92:95]
	v_mfma_f32_16x16x32_bf16 v[84:87], v[140:143], v[204:207], v[84:87]
	v_mfma_f32_16x16x32_bf16 v[76:79], v[132:135], v[218:221], v[76:79]
	v_mfma_f32_16x16x32_bf16 v[68:71], v[140:143], v[218:221], v[68:71]
	s_barrier
	s_setprio 0
	s_add_i32 s38, 0, 0x1c000
	s_add_i32 s27, s27, s4
	v_add_u32_e32 v213, s38, v157
	v_lshl_add_u64 v[208:209], v[208:209], 0, s[8:9]
	s_mov_b32 m0, s27
	ds_read_b128 v[222:225], v213
	ds_read_b128 v[226:229], v213 offset:1024
	ds_read_b128 v[230:233], v213 offset:2048
	ds_read_b128 v[234:237], v213 offset:3072
	global_load_lds_dwordx4 v[208:209], off
	v_lshl_add_u64 v[208:209], v[238:239], 0, s[8:9]
	s_add_i32 m0, s27, 0x2000
	s_nop 0
	global_load_lds_dwordx4 v[208:209], off
	s_setprio 1
	s_barrier
; #define PG8_STAGE(bufoff, gbase, voff) do { _Pragma("unroll") for (int _i = 0; _i < 2; ++_i) \
;         __builtin_amdgcn_global_load_lds((const unsigned*)((const char*)(gbase) + (voff)[_i]), (LAS unsigned*)(lds + (bufoff) + ldsw + _i * 8192), 16, 0, 0); } while (0)
; #define PG8_LDA(dst, b, h) do { _Pragma("unroll") for (int m = 0; m < 4; ++m) _Pragma("unroll") for (int k = 0; k < 2; ++k) dst[m][k] = *(const LAS bf16x8*)(lds + PG8_SA(b, h) + aoff + m * 2048 + k * 1024); } while (0)
; #define PG8_MMA(ai, bj, At, Bt) do { __builtin_amdgcn_s_setprio(1); _Pragma("unroll") for (int m = 0; m < 4; ++m) _Pragma("unroll") for (int n = 0; n < 2; ++n) _Pragma("unroll") for (int k = 0; k < 2; ++k) \
;         acc[ai][bj][m][n] = __builtin_amdgcn_mfma_f32_16x16x32_bf16(Bt[n][k], At[m][k], acc[ai][bj][m][n], 0, 0, 0); __builtin_amdgcn_s_setprio(0); } while (0)
; #define PG8_WAIT_V(n) asm volatile("s_waitcnt vmcnt(" #n ")" ::: "memory")
; #define PG8_WAIT_L(n) asm volatile("s_waitcnt lgkmcnt(" #n ")" ::: "memory")
; #define PG8_BAR __builtin_amdgcn_s_barrier()
; #define PG8_SCHED __builtin_amdgcn_sched_barrier(0)
; template <class Epi, class Sched, bool ATILE = false>
; __device__ __forceinline__ void gemm_phase(LAS unsigned char* lds, const Gemm g, const Sched& S, const Epi& E) {
;     ...
;             PG8_BAR; PG8_WAIT_L(0); PG8_MMA(0, 1, At, B1); PG8_BAR;
;             PG8_LDA(At, 1, 1); PG8_STAGE(PG8_SA(1, 0), a3, voffA);
;             PG8_BAR; PG8_WAIT_L(0); PG8_MMA(1, 0, At, B0); PG8_BAR; PG8_SCHED;
;             PG8_STAGE(PG8_SB(1, 1), b3 + hstepB, voffB);
;             PG8_WAIT_V(6); PG8_BAR; PG8_MMA(1, 1, At, B1); PG8_BAR;
	s_waitcnt lgkmcnt(0)
	v_mfma_f32_16x16x32_bf16 v[124:127], v[222:225], v[144:147], v[124:127]
	v_mfma_f32_16x16x32_bf16 v[112:115], v[230:233], v[144:147], v[112:115]
	v_mfma_f32_16x16x32_bf16 v[104:107], v[222:225], v[192:195], v[104:107]
	v_mfma_f32_16x16x32_bf16 v[96:99], v[230:233], v[192:195], v[96:99]
	v_mfma_f32_16x16x32_bf16 v[88:91], v[222:225], v[200:203], v[88:91]
	v_mfma_f32_16x16x32_bf16 v[80:83], v[230:233], v[200:203], v[80:83]
	v_mfma_f32_16x16x32_bf16 v[72:75], v[222:225], v[214:217], v[72:75]
	v_mfma_f32_16x16x32_bf16 v[64:67], v[230:233], v[214:217], v[64:67]
	v_mfma_f32_16x16x32_bf16 v[124:127], v[226:229], v[148:151], v[124:127]
	v_mfma_f32_16x16x32_bf16 v[112:115], v[234:237], v[148:151], v[112:115]
	v_mfma_f32_16x16x32_bf16 v[104:107], v[226:229], v[196:199], v[104:107]
	v_mfma_f32_16x16x32_bf16 v[96:99], v[234:237], v[196:199], v[96:99]
	v_mfma_f32_16x16x32_bf16 v[88:91], v[226:229], v[204:207], v[88:91]
	v_mfma_f32_16x16x32_bf16 v[80:83], v[234:237], v[204:207], v[80:83]
	v_mfma_f32_16x16x32_bf16 v[72:75], v[226:229], v[218:221], v[72:75]
	v_mfma_f32_16x16x32_bf16 v[64:67], v[234:237], v[218:221], v[64:67]
	s_barrier
	s_setprio 0
	s_mov_b32 m0, s43
	v_lshl_add_u64 v[208:209], s[36:37], 0, v[160:161]
	ds_read_b128 v[144:147], v210 offset:49152
	ds_read_b128 v[148:151], v210 offset:50176
	ds_read_b128 v[192:195], v210 offset:51200
	ds_read_b128 v[196:199], v210 offset:52224
	ds_read_b128 v[200:203], v210 offset:53248
	ds_read_b128 v[204:207], v210 offset:54272
	ds_read_b128 v[214:217], v210 offset:55296
	ds_read_b128 v[218:221], v210 offset:56320
	global_load_lds_dwordx4 v[208:209], off
	v_lshl_add_u64 v[208:209], s[36:37], 0, v[164:165]
	s_mov_b32 m0, s44
	s_nop 0
	global_load_lds_dwordx4 v[208:209], off
	s_setprio 1
	s_barrier
	s_waitcnt lgkmcnt(0)
	v_mfma_f32_16x16x32_bf16 v[60:63], v[128:131], v[144:147], v[60:63]
	v_mfma_f32_16x16x32_bf16 v[56:59], v[136:139], v[144:147], v[56:59]
	v_mfma_f32_16x16x32_bf16 v[44:47], v[128:131], v[192:195], v[44:47]
	v_mfma_f32_16x16x32_bf16 v[40:43], v[136:139], v[192:195], v[40:43]
	v_mfma_f32_16x16x32_bf16 v[28:31], v[128:131], v[200:203], v[28:31]
	v_mfma_f32_16x16x32_bf16 v[24:27], v[136:139], v[200:203], v[24:27]
	v_mfma_f32_16x16x32_bf16 v[12:15], v[128:131], v[214:217], v[12:15]
	v_mfma_f32_16x16x32_bf16 v[8:11], v[136:139], v[214:217], v[8:11]
	v_mfma_f32_16x16x32_bf16 v[60:63], v[132:135], v[148:151], v[60:63]
	v_mfma_f32_16x16x32_bf16 v[56:59], v[140:143], v[148:151], v[56:59]
	v_mfma_f32_16x16x32_bf16 v[44:47], v[132:135], v[196:199], v[44:47]
	v_mfma_f32_16x16x32_bf16 v[40:43], v[140:143], v[196:199], v[40:43]
	v_mfma_f32_16x16x32_bf16 v[28:31], v[132:135], v[204:207], v[28:31]
	v_mfma_f32_16x16x32_bf16 v[24:27], v[140:143], v[204:207], v[24:27]
	v_mfma_f32_16x16x32_bf16 v[12:15], v[132:135], v[218:221], v[12:15]
	v_mfma_f32_16x16x32_bf16 v[8:11], v[140:143], v[218:221], v[8:11]
	s_barrier
	s_setprio 0
	s_add_u32 s34, s34, 0x80080
	s_addc_u32 s35, s35, 0
	s_add_i32 s27, s38, s4
	v_lshl_add_u64 v[128:129], s[34:35], 0, v[162:163]
	s_mov_b32 m0, s27
	s_nop 0
	global_load_lds_dwordx4 v[128:129], off
	v_lshl_add_u64 v[128:129], s[34:35], 0, v[166:167]
	s_add_i32 m0, s27, 0x2000
	s_nop 0
	global_load_lds_dwordx4 v[128:129], off
	s_waitcnt vmcnt(6)
	s_setprio 1
	s_barrier
	v_mfma_f32_16x16x32_bf16 v[52:55], v[222:225], v[144:147], v[52:55]
	v_mfma_f32_16x16x32_bf16 v[48:51], v[230:233], v[144:147], v[48:51]
	v_mfma_f32_16x16x32_bf16 v[36:39], v[222:225], v[192:195], v[36:39]
	v_mfma_f32_16x16x32_bf16 v[32:35], v[230:233], v[192:195], v[32:35]
	v_mfma_f32_16x16x32_bf16 v[20:23], v[222:225], v[200:203], v[20:23]
	v_mfma_f32_16x16x32_bf16 v[16:19], v[230:233], v[200:203], v[16:19]
	v_mfma_f32_16x16x32_bf16 v[4:7], v[222:225], v[214:217], v[4:7]
	v_mfma_f32_16x16x32_bf16 v[0:3], v[230:233], v[214:217], v[0:3]
	v_mfma_f32_16x16x32_bf16 v[52:55], v[226:229], v[148:151], v[52:55]
	v_mfma_f32_16x16x32_bf16 v[48:51], v[234:237], v[148:151], v[48:51]
	v_mfma_f32_16x16x32_bf16 v[36:39], v[226:229], v[196:199], v[36:39]
	v_mfma_f32_16x16x32_bf16 v[32:35], v[234:237], v[196:199], v[32:35]
	v_mfma_f32_16x16x32_bf16 v[20:23], v[226:229], v[204:207], v[20:23]
	v_mfma_f32_16x16x32_bf16 v[16:19], v[234:237], v[204:207], v[16:19]
	v_mfma_f32_16x16x32_bf16 v[4:7], v[226:229], v[218:221], v[4:7]
	v_mfma_f32_16x16x32_bf16 v[0:3], v[234:237], v[218:221], v[0:3]
	s_barrier
	s_setprio 0
	s_add_u32 s13, s13, 0x100
	s_addc_u32 s17, s17, 0
	s_add_u32 s30, s30, 0x10000
	s_addc_u32 s31, s31, 0
	s_cmp_ge_i32 s29, s1
	s_mov_b32 s27, s29
	s_cbranch_scc0 .LBB0_1658
	s_branch .LBB0_1662

; #define PG8_STAGE(bufoff, gbase, voff) do { _Pragma("unroll") for (int _i = 0; _i < 2; ++_i) \
;         __builtin_amdgcn_global_load_lds((const unsigned*)((const char*)(gbase) + (voff)[_i]), (LAS unsigned*)(lds + (bufoff) + ldsw + _i * 8192), 16, 0, 0); } while (0)
; #define PG8_LDA(dst, b, h) do { _Pragma("unroll") for (int m = 0; m < 4; ++m) _Pragma("unroll") for (int k = 0; k < 2; ++k) dst[m][k] = *(const LAS bf16x8*)(lds + PG8_SA(b, h) + aoff + m * 2048 + k * 1024); } while (0)
; #define PG8_LDB(dst, b, h) do { _Pragma("unroll") for (int n = 0; n < 2; ++n) _Pragma("unroll") for (int k = 0; k < 2; ++k) dst[n][k] = *(const LAS bf16x8*)(lds + PG8_SB(b, h) + boff + n * 2048 + k * 1024); } while (0)
; #define PG8_MMA(ai, bj, At, Bt) do { __builtin_amdgcn_s_setprio(1); _Pragma("unroll") for (int m = 0; m < 4; ++m) _Pragma("unroll") for (int n = 0; n < 2; ++n) _Pragma("unroll") for (int k = 0; k < 2; ++k) \
;         acc[ai][bj][m][n] = __builtin_amdgcn_mfma_f32_16x16x32_bf16(Bt[n][k], At[m][k], acc[ai][bj][m][n], 0, 0, 0); __builtin_amdgcn_s_setprio(0); } while (0)
; #define PG8_WAIT_L(n) asm volatile("s_waitcnt lgkmcnt(" #n ")" ::: "memory")
; #define PG8_BAR __builtin_amdgcn_s_barrier()
; #define PG8_SCHED __builtin_amdgcn_sched_barrier(0)
; template <class Epi, class Sched, bool ATILE = false>
; __device__ __forceinline__ void gemm_phase(LAS unsigned char* lds, const Gemm g, const Sched& S, const Epi& E) {
;     ...
;         for (int t = 0; t < nt; t += 2) {
;             const bool last = (t == nt - 2);
;             const char* a1 = cA + (size_t)(t + 1) * kstepA;
;             const char* a2 = last ? nA : cA + (size_t)(t + 2) * kstepA; const char* b2 = last ? nB : cB + (size_t)(t + 2) * kstep;
;             const char* a3 = a2 + kstepA; const char* b3 = b2 + kstep;
;             PG8_LDB(B0, 0, 0); PG8_SCHED; PG8_LDA(At, 0, 0); PG8_STAGE(PG8_SA(1, 1), a1 + hstepA, voffA);
;             PG8_WAIT_L(8); PG8_BAR; PG8_WAIT_L(0); PG8_MMA(0, 0, At, B0); PG8_BAR; PG8_SCHED;
;             PG8_LDB(B1, 0, 1); PG8_STAGE(PG8_SB(0, 0), b2, voffB);
;             PG8_BAR; PG8_WAIT_L(0); PG8_MMA(0, 1, At, B1); PG8_BAR;
;             PG8_LDA(At, 0, 1); PG8_STAGE(PG8_SA(0, 0), a2, voffA);
;             PG8_BAR; PG8_WAIT_L(0); PG8_MMA(1, 0, At, B0); PG8_BAR; PG8_SCHED;
.LBB0_1812:
	ds_read_b128 v[176:179], v139
	ds_read_b128 v[180:183], v139 offset:1024
	ds_read_b128 v[184:187], v139 offset:2048
	ds_read_b128 v[188:191], v139 offset:3072
	s_add_i32 s34, s8, 2
	s_add_u32 s9, s6, 0xfff80080
	s_addc_u32 s10, s7, -1
	s_cmp_eq_u32 s19, s8
	s_cselect_b32 s8, s18, s25
	s_cselect_b32 s11, s13, s10
	s_cselect_b32 s10, s16, s9
	s_cselect_b32 s9, s17, s27
	v_lshl_add_u64 v[224:225], s[6:7], 0, v[164:165]
	s_add_i32 m0, s37, 0xc000
	ds_read_b128 v[192:195], v159
	ds_read_b128 v[196:199], v159 offset:1024
	ds_read_b128 v[200:203], v159 offset:2048
	ds_read_b128 v[204:207], v159 offset:3072
	ds_read_b128 v[208:211], v159 offset:4096
	ds_read_b128 v[212:215], v159 offset:5120
	ds_read_b128 v[216:219], v159 offset:6144
	ds_read_b128 v[220:223], v159 offset:7168
	global_load_lds_dwordx4 v[224:225], off
	v_lshl_add_u64 v[224:225], s[6:7], 0, v[166:167]
	s_add_i32 m0, s37, 0xe000
	s_nop 0
	global_load_lds_dwordx4 v[224:225], off
	s_waitcnt lgkmcnt(8)
	s_setprio 1
	s_barrier
	s_waitcnt lgkmcnt(0)
	v_mfma_f32_16x16x32_bf16 v[120:123], v[176:179], v[192:195], v[120:123]
	v_mfma_f32_16x16x32_bf16 v[112:115], v[184:187], v[192:195], v[112:115]
	v_mfma_f32_16x16x32_bf16 v[104:107], v[176:179], v[200:203], v[104:107]
	v_mfma_f32_16x16x32_bf16 v[96:99], v[184:187], v[200:203], v[96:99]
	v_mfma_f32_16x16x32_bf16 v[88:91], v[176:179], v[208:211], v[88:91]
	v_mfma_f32_16x16x32_bf16 v[80:83], v[184:187], v[208:211], v[80:83]
	v_mfma_f32_16x16x32_bf16 v[72:75], v[176:179], v[216:219], v[72:75]
	v_mfma_f32_16x16x32_bf16 v[64:67], v[184:187], v[216:219], v[64:67]
	v_mfma_f32_16x16x32_bf16 v[120:123], v[180:183], v[196:199], v[120:123]
	v_mfma_f32_16x16x32_bf16 v[112:115], v[188:191], v[196:199], v[112:115]
	v_mfma_f32_16x16x32_bf16 v[104:107], v[180:183], v[204:207], v[104:107]
	v_mfma_f32_16x16x32_bf16 v[96:99], v[188:191], v[204:207], v[96:99]
	v_mfma_f32_16x16x32_bf16 v[88:91], v[180:183], v[212:215], v[88:91]
	v_mfma_f32_16x16x32_bf16 v[80:83], v[188:191], v[212:215], v[80:83]
	v_mfma_f32_16x16x32_bf16 v[72:75], v[180:183], v[220:223], v[72:75]
	v_mfma_f32_16x16x32_bf16 v[64:67], v[188:191], v[220:223], v[64:67]
	s_barrier
	s_setprio 0
	s_add_i32 s35, s51, s36
	v_lshl_add_u64 v[240:241], s[8:9], 0, v[130:131]
	s_mov_b32 m0, s35
	ds_read_b128 v[224:227], v173
	ds_read_b128 v[228:231], v173 offset:1024
	ds_read_b128 v[232:235], v173 offset:2048
	ds_read_b128 v[236:239], v173 offset:3072
	global_load_lds_dwordx4 v[240:241], off
	v_lshl_add_u64 v[242:243], s[8:9], 0, v[134:135]
	s_add_i32 m0, s35, 0x2000
	s_nop 0
	global_load_lds_dwordx4 v[242:243], off
	s_setprio 1
	s_barrier
	s_waitcnt lgkmcnt(0)
	v_mfma_f32_16x16x32_bf16 v[124:127], v[224:227], v[192:195], v[124:127]
	v_mfma_f32_16x16x32_bf16 v[116:119], v[232:235], v[192:195], v[116:119]
	v_mfma_f32_16x16x32_bf16 v[108:111], v[224:227], v[200:203], v[108:111]
	v_mfma_f32_16x16x32_bf16 v[100:103], v[232:235], v[200:203], v[100:103]
	v_mfma_f32_16x16x32_bf16 v[92:95], v[224:227], v[208:211], v[92:95]
	v_mfma_f32_16x16x32_bf16 v[84:87], v[232:235], v[208:211], v[84:87]
	v_mfma_f32_16x16x32_bf16 v[76:79], v[224:227], v[216:219], v[76:79]
	v_mfma_f32_16x16x32_bf16 v[68:71], v[232:235], v[216:219], v[68:71]
	v_mfma_f32_16x16x32_bf16 v[124:127], v[228:231], v[196:199], v[124:127]
	v_mfma_f32_16x16x32_bf16 v[116:119], v[236:239], v[196:199], v[116:119]
	v_mfma_f32_16x16x32_bf16 v[108:111], v[228:231], v[204:207], v[108:111]
	v_mfma_f32_16x16x32_bf16 v[100:103], v[236:239], v[204:207], v[100:103]
	v_mfma_f32_16x16x32_bf16 v[92:95], v[228:231], v[212:215], v[92:95]
	v_mfma_f32_16x16x32_bf16 v[84:87], v[236:239], v[212:215], v[84:87]
	v_mfma_f32_16x16x32_bf16 v[76:79], v[228:231], v[220:223], v[76:79]
	v_mfma_f32_16x16x32_bf16 v[68:71], v[236:239], v[220:223], v[68:71]
	s_barrier
	s_setprio 0
	s_mov_b32 m0, s37
	v_lshl_add_u64 v[244:245], s[10:11], 0, v[128:129]
	ds_read_b128 v[192:195], v159 offset:16384
	ds_read_b128 v[196:199], v159 offset:17408
	ds_read_b128 v[200:203], v159 offset:18432
	ds_read_b128 v[204:207], v159 offset:19456
	ds_read_b128 v[208:211], v159 offset:20480
	ds_read_b128 v[212:215], v159 offset:21504
	ds_read_b128 v[216:219], v159 offset:22528
	ds_read_b128 v[220:223], v159 offset:23552
	global_load_lds_dwordx4 v[244:245], off
	v_lshl_add_u64 v[246:247], s[10:11], 0, v[132:133]
	s_mov_b32 m0, s38
	s_nop 0
	global_load_lds_dwordx4 v[246:247], off
	s_setprio 1
	s_barrier
	s_waitcnt lgkmcnt(0)
	v_mfma_f32_16x16x32_bf16 v[56:59], v[176:179], v[192:195], v[56:59]
	v_mfma_f32_16x16x32_bf16 v[48:51], v[184:187], v[192:195], v[48:51]
	v_mfma_f32_16x16x32_bf16 v[40:43], v[176:179], v[200:203], v[40:43]
	v_mfma_f32_16x16x32_bf16 v[32:35], v[184:187], v[200:203], v[32:35]
	v_mfma_f32_16x16x32_bf16 v[24:27], v[176:179], v[208:211], v[24:27]
	v_mfma_f32_16x16x32_bf16 v[16:19], v[184:187], v[208:211], v[16:19]
	v_mfma_f32_16x16x32_bf16 v[8:11], v[176:179], v[216:219], v[8:11]
	v_mfma_f32_16x16x32_bf16 v[4:7], v[184:187], v[216:219], v[4:7]
	v_mfma_f32_16x16x32_bf16 v[56:59], v[180:183], v[196:199], v[56:59]
	v_mfma_f32_16x16x32_bf16 v[48:51], v[188:191], v[196:199], v[48:51]
	v_mfma_f32_16x16x32_bf16 v[40:43], v[180:183], v[204:207], v[40:43]
	v_mfma_f32_16x16x32_bf16 v[32:35], v[188:191], v[204:207], v[32:35]
	v_mfma_f32_16x16x32_bf16 v[24:27], v[180:183], v[212:215], v[24:27]
	v_mfma_f32_16x16x32_bf16 v[16:19], v[188:191], v[212:215], v[16:19]
	v_mfma_f32_16x16x32_bf16 v[8:11], v[180:183], v[220:223], v[8:11]
	v_mfma_f32_16x16x32_bf16 v[4:7], v[188:191], v[220:223], v[4:7]
	s_barrier
; #define PG8_STAGE(bufoff, gbase, voff) do { _Pragma("unroll") for (int _i = 0; _i < 2; ++_i) \
;         __builtin_amdgcn_global_load_lds((const unsigned*)((const char*)(gbase) + (voff)[_i]), (LAS unsigned*)(lds + (bufoff) + ldsw + _i * 8192), 16, 0, 0); } while (0)
; #define PG8_LDA(dst, b, h) do { _Pragma("unroll") for (int m = 0; m < 4; ++m) _Pragma("unroll") for (int k = 0; k < 2; ++k) dst[m][k] = *(const LAS bf16x8*)(lds + PG8_SA(b, h) + aoff + m * 2048 + k * 1024); } while (0)
; #define PG8_LDB(dst, b, h) do { _Pragma("unroll") for (int n = 0; n < 2; ++n) _Pragma("unroll") for (int k = 0; k < 2; ++k) dst[n][k] = *(const LAS bf16x8*)(lds + PG8_SB(b, h) + boff + n * 2048 + k * 1024); } while (0)
; #define PG8_MMA(ai, bj, At, Bt) do { __builtin_amdgcn_s_setprio(1); _Pragma("unroll") for (int m = 0; m < 4; ++m) _Pragma("unroll") for (int n = 0; n < 2; ++n) _Pragma("unroll") for (int k = 0; k < 2; ++k) \
;         acc[ai][bj][m][n] = __builtin_amdgcn_mfma_f32_16x16x32_bf16(Bt[n][k], At[m][k], acc[ai][bj][m][n], 0, 0, 0); __builtin_amdgcn_s_setprio(0); } while (0)
; #define PG8_WAIT_V(n) asm volatile("s_waitcnt vmcnt(" #n ")" ::: "memory")
; #define PG8_WAIT_L(n) asm volatile("s_waitcnt lgkmcnt(" #n ")" ::: "memory")
; #define PG8_BAR __builtin_amdgcn_s_barrier()
; #define PG8_SCHED __builtin_amdgcn_sched_barrier(0)
; template <class Epi, class Sched, bool ATILE = false>
; __device__ __forceinline__ void gemm_phase(LAS unsigned char* lds, const Gemm g, const Sched& S, const Epi& E) {
;     ...
;             PG8_BAR; PG8_WAIT_L(0); PG8_MMA(1, 0, At, B0); PG8_BAR; PG8_SCHED;
;             PG8_STAGE(PG8_SB(0, 1), b2 + hstepB, voffB);
;             PG8_WAIT_V(6); PG8_BAR; PG8_MMA(1, 1, At, B1); PG8_BAR;
;             PG8_LDB(B0, 1, 0); PG8_SCHED; PG8_LDA(At, 1, 0); PG8_STAGE(PG8_SA(0, 1), a2 + hstepA, voffA);
;             PG8_WAIT_L(8); PG8_BAR; PG8_WAIT_L(0); PG8_MMA(0, 0, At, B0); PG8_BAR; PG8_SCHED;
;             PG8_LDB(B1, 1, 1); PG8_STAGE(PG8_SB(1, 0), b3, voffB);
;             PG8_BAR; PG8_WAIT_L(0); PG8_MMA(0, 1, At, B1); PG8_BAR;
	s_setprio 0
	s_add_u32 s54, s8, 0x80000
	s_addc_u32 s55, s9, 0
	s_add_i32 s35, s52, s36
	v_lshl_add_u64 v[176:177], s[54:55], 0, v[130:131]
	s_mov_b32 m0, s35
	s_nop 0
	global_load_lds_dwordx4 v[176:177], off
	v_lshl_add_u64 v[176:177], s[54:55], 0, v[134:135]
	s_add_i32 m0, s35, 0x2000
	s_nop 0
	global_load_lds_dwordx4 v[176:177], off
	s_waitcnt vmcnt(6)
	s_setprio 1
	s_barrier
	v_mfma_f32_16x16x32_bf16 v[60:63], v[224:227], v[192:195], v[60:63]
	v_mfma_f32_16x16x32_bf16 v[52:55], v[232:235], v[192:195], v[52:55]
	v_mfma_f32_16x16x32_bf16 v[44:47], v[224:227], v[200:203], v[44:47]
	v_mfma_f32_16x16x32_bf16 v[36:39], v[232:235], v[200:203], v[36:39]
	v_mfma_f32_16x16x32_bf16 v[28:31], v[224:227], v[208:211], v[28:31]
	v_mfma_f32_16x16x32_bf16 v[20:23], v[232:235], v[208:211], v[20:23]
	v_mfma_f32_16x16x32_bf16 v[12:15], v[224:227], v[216:219], v[12:15]
	v_mfma_f32_16x16x32_bf16 v[0:3], v[232:235], v[216:219], v[0:3]
	v_mfma_f32_16x16x32_bf16 v[60:63], v[228:231], v[196:199], v[60:63]
	v_mfma_f32_16x16x32_bf16 v[52:55], v[236:239], v[196:199], v[52:55]
	v_mfma_f32_16x16x32_bf16 v[44:47], v[228:231], v[204:207], v[44:47]
	v_mfma_f32_16x16x32_bf16 v[36:39], v[236:239], v[204:207], v[36:39]
	v_mfma_f32_16x16x32_bf16 v[28:31], v[228:231], v[212:215], v[28:31]
	v_mfma_f32_16x16x32_bf16 v[20:23], v[236:239], v[212:215], v[20:23]
	v_mfma_f32_16x16x32_bf16 v[12:15], v[228:231], v[220:223], v[12:15]
	v_mfma_f32_16x16x32_bf16 v[0:3], v[236:239], v[220:223], v[0:3]
	s_barrier
	s_setprio 0
	s_add_i32 s35, 0, 0x18000
	v_add_u32_e32 v172, s35, v157
	ds_read_b128 v[176:179], v172
	ds_read_b128 v[180:183], v172 offset:1024
	ds_read_b128 v[184:187], v172 offset:2048
	ds_read_b128 v[188:191], v172 offset:3072
	s_add_u32 s10, s10, 0x80000
	s_addc_u32 s11, s11, 0
	s_mov_b32 m0, s39
	v_lshl_add_u64 v[224:225], s[10:11], 0, v[128:129]
	ds_read_b128 v[192:195], v159 offset:32768
	ds_read_b128 v[196:199], v159 offset:33792
	ds_read_b128 v[200:203], v159 offset:34816
	ds_read_b128 v[204:207], v159 offset:35840
	ds_read_b128 v[208:211], v159 offset:36864
	ds_read_b128 v[212:215], v159 offset:37888
	ds_read_b128 v[216:219], v159 offset:38912
	ds_read_b128 v[220:223], v159 offset:39936
	global_load_lds_dwordx4 v[224:225], off
	v_lshl_add_u64 v[224:225], s[10:11], 0, v[132:133]
	s_mov_b32 m0, s40
	s_nop 0
	global_load_lds_dwordx4 v[224:225], off
	s_waitcnt lgkmcnt(8)
	s_setprio 1
	s_barrier
	s_waitcnt lgkmcnt(0)
	v_mfma_f32_16x16x32_bf16 v[120:123], v[176:179], v[192:195], v[120:123]
	v_mfma_f32_16x16x32_bf16 v[112:115], v[184:187], v[192:195], v[112:115]
	v_mfma_f32_16x16x32_bf16 v[104:107], v[176:179], v[200:203], v[104:107]
	v_mfma_f32_16x16x32_bf16 v[96:99], v[184:187], v[200:203], v[96:99]
	v_mfma_f32_16x16x32_bf16 v[88:91], v[176:179], v[208:211], v[88:91]
	v_mfma_f32_16x16x32_bf16 v[80:83], v[184:187], v[208:211], v[80:83]
	v_mfma_f32_16x16x32_bf16 v[72:75], v[176:179], v[216:219], v[72:75]
	v_mfma_f32_16x16x32_bf16 v[64:67], v[184:187], v[216:219], v[64:67]
	v_mfma_f32_16x16x32_bf16 v[120:123], v[180:183], v[196:199], v[120:123]
	v_mfma_f32_16x16x32_bf16 v[112:115], v[188:191], v[196:199], v[112:115]
	v_mfma_f32_16x16x32_bf16 v[104:107], v[180:183], v[204:207], v[104:107]
	v_mfma_f32_16x16x32_bf16 v[96:99], v[188:191], v[204:207], v[96:99]
	v_mfma_f32_16x16x32_bf16 v[88:91], v[180:183], v[212:215], v[88:91]
	v_mfma_f32_16x16x32_bf16 v[80:83], v[188:191], v[212:215], v[80:83]
	v_mfma_f32_16x16x32_bf16 v[72:75], v[180:183], v[220:223], v[72:75]
	v_mfma_f32_16x16x32_bf16 v[64:67], v[188:191], v[220:223], v[64:67]
	s_barrier
	s_setprio 0
	s_add_i32 s10, 0, 0x1c000
	s_add_i32 s11, s35, s36
	v_add_u32_e32 v172, s10, v157
	v_lshl_add_u64 v[240:241], v[240:241], 0, s[22:23]
	s_mov_b32 m0, s11
	ds_read_b128 v[224:227], v172
	ds_read_b128 v[228:231], v172 offset:1024
	ds_read_b128 v[232:235], v172 offset:2048
	ds_read_b128 v[236:239], v172 offset:3072
	global_load_lds_dwordx4 v[240:241], off
	v_lshl_add_u64 v[240:241], v[242:243], 0, s[22:23]
	s_add_i32 m0, s11, 0x2000
	s_nop 0
	global_load_lds_dwordx4 v[240:241], off
	s_setprio 1
	s_barrier
; #define PG8_STAGE(bufoff, gbase, voff) do { _Pragma("unroll") for (int _i = 0; _i < 2; ++_i) \
;         __builtin_amdgcn_global_load_lds((const unsigned*)((const char*)(gbase) + (voff)[_i]), (LAS unsigned*)(lds + (bufoff) + ldsw + _i * 8192), 16, 0, 0); } while (0)
; #define PG8_LDA(dst, b, h) do { _Pragma("unroll") for (int m = 0; m < 4; ++m) _Pragma("unroll") for (int k = 0; k < 2; ++k) dst[m][k] = *(const LAS bf16x8*)(lds + PG8_SA(b, h) + aoff + m * 2048 + k * 1024); } while (0)
; #define PG8_MMA(ai, bj, At, Bt) do { __builtin_amdgcn_s_setprio(1); _Pragma("unroll") for (int m = 0; m < 4; ++m) _Pragma("unroll") for (int n = 0; n < 2; ++n) _Pragma("unroll") for (int k = 0; k < 2; ++k) \
;         acc[ai][bj][m][n] = __builtin_amdgcn_mfma_f32_16x16x32_bf16(Bt[n][k], At[m][k], acc[ai][bj][m][n], 0, 0, 0); __builtin_amdgcn_s_setprio(0); } while (0)
; #define PG8_WAIT_V(n) asm volatile("s_waitcnt vmcnt(" #n ")" ::: "memory")
; #define PG8_WAIT_L(n) asm volatile("s_waitcnt lgkmcnt(" #n ")" ::: "memory")
; #define PG8_BAR __builtin_amdgcn_s_barrier()
; #define PG8_SCHED __builtin_amdgcn_sched_barrier(0)
; template <class Epi, class Sched, bool ATILE = false>
; __device__ __forceinline__ void gemm_phase(LAS unsigned char* lds, const Gemm g, const Sched& S, const Epi& E) {
;     ...
;             PG8_BAR; PG8_WAIT_L(0); PG8_MMA(0, 1, At, B1); PG8_BAR;
;             PG8_LDA(At, 1, 1); PG8_STAGE(PG8_SA(1, 0), a3, voffA);
;             PG8_BAR; PG8_WAIT_L(0); PG8_MMA(1, 0, At, B0); PG8_BAR; PG8_SCHED;
;             PG8_STAGE(PG8_SB(1, 1), b3 + hstepB, voffB);
;             PG8_WAIT_V(6); PG8_BAR; PG8_MMA(1, 1, At, B1); PG8_BAR;
	s_waitcnt lgkmcnt(0)
	v_mfma_f32_16x16x32_bf16 v[124:127], v[224:227], v[192:195], v[124:127]
	v_mfma_f32_16x16x32_bf16 v[116:119], v[232:235], v[192:195], v[116:119]
	v_mfma_f32_16x16x32_bf16 v[108:111], v[224:227], v[200:203], v[108:111]
	v_mfma_f32_16x16x32_bf16 v[100:103], v[232:235], v[200:203], v[100:103]
	v_mfma_f32_16x16x32_bf16 v[92:95], v[224:227], v[208:211], v[92:95]
	v_mfma_f32_16x16x32_bf16 v[84:87], v[232:235], v[208:211], v[84:87]
	v_mfma_f32_16x16x32_bf16 v[76:79], v[224:227], v[216:219], v[76:79]
	v_mfma_f32_16x16x32_bf16 v[68:71], v[232:235], v[216:219], v[68:71]
	v_mfma_f32_16x16x32_bf16 v[124:127], v[228:231], v[196:199], v[124:127]
	v_mfma_f32_16x16x32_bf16 v[116:119], v[236:239], v[196:199], v[116:119]
	v_mfma_f32_16x16x32_bf16 v[108:111], v[228:231], v[204:207], v[108:111]
	v_mfma_f32_16x16x32_bf16 v[100:103], v[236:239], v[204:207], v[100:103]
	v_mfma_f32_16x16x32_bf16 v[92:95], v[228:231], v[212:215], v[92:95]
	v_mfma_f32_16x16x32_bf16 v[84:87], v[236:239], v[212:215], v[84:87]
	v_mfma_f32_16x16x32_bf16 v[76:79], v[228:231], v[220:223], v[76:79]
	v_mfma_f32_16x16x32_bf16 v[68:71], v[236:239], v[220:223], v[68:71]
	s_barrier
	s_setprio 0
	s_mov_b32 m0, s43
	v_lshl_add_u64 v[240:241], v[244:245], 0, s[22:23]
	ds_read_b128 v[192:195], v159 offset:49152
	ds_read_b128 v[196:199], v159 offset:50176
	ds_read_b128 v[200:203], v159 offset:51200
	ds_read_b128 v[204:207], v159 offset:52224
	ds_read_b128 v[208:211], v159 offset:53248
	ds_read_b128 v[212:215], v159 offset:54272
	ds_read_b128 v[216:219], v159 offset:55296
	ds_read_b128 v[220:223], v159 offset:56320
	global_load_lds_dwordx4 v[240:241], off
	v_lshl_add_u64 v[240:241], v[246:247], 0, s[22:23]
	s_mov_b32 m0, s44
	s_nop 0
	global_load_lds_dwordx4 v[240:241], off
	s_setprio 1
	s_barrier
	s_waitcnt lgkmcnt(0)
	v_mfma_f32_16x16x32_bf16 v[56:59], v[176:179], v[192:195], v[56:59]
	v_mfma_f32_16x16x32_bf16 v[48:51], v[184:187], v[192:195], v[48:51]
	v_mfma_f32_16x16x32_bf16 v[40:43], v[176:179], v[200:203], v[40:43]
	v_mfma_f32_16x16x32_bf16 v[32:35], v[184:187], v[200:203], v[32:35]
	v_mfma_f32_16x16x32_bf16 v[24:27], v[176:179], v[208:211], v[24:27]
	v_mfma_f32_16x16x32_bf16 v[16:19], v[184:187], v[208:211], v[16:19]
	v_mfma_f32_16x16x32_bf16 v[8:11], v[176:179], v[216:219], v[8:11]
	v_mfma_f32_16x16x32_bf16 v[4:7], v[184:187], v[216:219], v[4:7]
	v_mfma_f32_16x16x32_bf16 v[56:59], v[180:183], v[196:199], v[56:59]
	v_mfma_f32_16x16x32_bf16 v[48:51], v[188:191], v[196:199], v[48:51]
	v_mfma_f32_16x16x32_bf16 v[40:43], v[180:183], v[204:207], v[40:43]
	v_mfma_f32_16x16x32_bf16 v[32:35], v[188:191], v[204:207], v[32:35]
	v_mfma_f32_16x16x32_bf16 v[24:27], v[180:183], v[212:215], v[24:27]
	v_mfma_f32_16x16x32_bf16 v[16:19], v[188:191], v[212:215], v[16:19]
	v_mfma_f32_16x16x32_bf16 v[8:11], v[180:183], v[220:223], v[8:11]
	v_mfma_f32_16x16x32_bf16 v[4:7], v[188:191], v[220:223], v[4:7]
	s_barrier
	s_setprio 0
	s_add_u32 s8, s8, 0x80080
	s_addc_u32 s9, s9, 0
	s_add_i32 s10, s10, s36
	v_lshl_add_u64 v[176:177], s[8:9], 0, v[130:131]
	s_mov_b32 m0, s10
	s_nop 0
	global_load_lds_dwordx4 v[176:177], off
	v_lshl_add_u64 v[176:177], s[8:9], 0, v[134:135]
	s_add_i32 m0, s10, 0x2000
	s_nop 0
	global_load_lds_dwordx4 v[176:177], off
	s_waitcnt vmcnt(6)
	s_setprio 1
	s_barrier
	v_mfma_f32_16x16x32_bf16 v[60:63], v[224:227], v[192:195], v[60:63]
	v_mfma_f32_16x16x32_bf16 v[52:55], v[232:235], v[192:195], v[52:55]
	v_mfma_f32_16x16x32_bf16 v[44:47], v[224:227], v[200:203], v[44:47]
	v_mfma_f32_16x16x32_bf16 v[36:39], v[232:235], v[200:203], v[36:39]
	v_mfma_f32_16x16x32_bf16 v[28:31], v[224:227], v[208:211], v[28:31]
	v_mfma_f32_16x16x32_bf16 v[20:23], v[232:235], v[208:211], v[20:23]
	v_mfma_f32_16x16x32_bf16 v[12:15], v[224:227], v[216:219], v[12:15]
	v_mfma_f32_16x16x32_bf16 v[0:3], v[232:235], v[216:219], v[0:3]
	v_mfma_f32_16x16x32_bf16 v[60:63], v[228:231], v[196:199], v[60:63]
	v_mfma_f32_16x16x32_bf16 v[52:55], v[236:239], v[196:199], v[52:55]
	v_mfma_f32_16x16x32_bf16 v[44:47], v[228:231], v[204:207], v[44:47]
	v_mfma_f32_16x16x32_bf16 v[36:39], v[236:239], v[204:207], v[36:39]
	v_mfma_f32_16x16x32_bf16 v[28:31], v[228:231], v[212:215], v[28:31]
	v_mfma_f32_16x16x32_bf16 v[20:23], v[236:239], v[212:215], v[20:23]
	v_mfma_f32_16x16x32_bf16 v[12:15], v[228:231], v[220:223], v[12:15]
	v_mfma_f32_16x16x32_bf16 v[0:3], v[236:239], v[220:223], v[0:3]
	s_barrier
	s_setprio 0
	s_add_u32 s6, s6, 0x100
	s_addc_u32 s7, s7, 0
	s_add_u32 s25, s25, 0x100
	s_addc_u32 s27, s27, 0
	s_cmp_ge_i32 s34, s12
	s_mov_b32 s8, s34
	s_cbranch_scc0 .LBB0_1812
	s_branch .LBB0_1803

; #define PG8_STAGE(bufoff, gbase, voff) do { _Pragma("unroll") for (int _i = 0; _i < 2; ++_i) \
;         __builtin_amdgcn_global_load_lds((const unsigned*)((const char*)(gbase) + (voff)[_i]), (LAS unsigned*)(lds + (bufoff) + ldsw + _i * 8192), 16, 0, 0); } while (0)
; #define PG8_LDA(dst, b, h) do { _Pragma("unroll") for (int m = 0; m < 4; ++m) _Pragma("unroll") for (int k = 0; k < 2; ++k) dst[m][k] = *(const LAS bf16x8*)(lds + PG8_SA(b, h) + aoff + m * 2048 + k * 1024); } while (0)
; #define PG8_LDB(dst, b, h) do { _Pragma("unroll") for (int n = 0; n < 2; ++n) _Pragma("unroll") for (int k = 0; k < 2; ++k) dst[n][k] = *(const LAS bf16x8*)(lds + PG8_SB(b, h) + boff + n * 2048 + k * 1024); } while (0)
; #define PG8_MMA(ai, bj, At, Bt) do { __builtin_amdgcn_s_setprio(1); _Pragma("unroll") for (int m = 0; m < 4; ++m) _Pragma("unroll") for (int n = 0; n < 2; ++n) _Pragma("unroll") for (int k = 0; k < 2; ++k) \
;         acc[ai][bj][m][n] = __builtin_amdgcn_mfma_f32_16x16x32_bf16(Bt[n][k], At[m][k], acc[ai][bj][m][n], 0, 0, 0); __builtin_amdgcn_s_setprio(0); } while (0)
; #define PG8_WAIT_L(n) asm volatile("s_waitcnt lgkmcnt(" #n ")" ::: "memory")
; #define PG8_BAR __builtin_amdgcn_s_barrier()
; #define PG8_SCHED __builtin_amdgcn_sched_barrier(0)
; template <class Epi, class Sched, bool ATILE = false>
; __device__ __forceinline__ void gemm_phase(LAS unsigned char* lds, const Gemm g, const Sched& S, const Epi& E) {
;     ...
;         for (int t = 0; t < nt; t += 2) {
;             const bool last = (t == nt - 2);
;             const char* a1 = cA + (size_t)(t + 1) * kstepA;
;             const char* a2 = last ? nA : cA + (size_t)(t + 2) * kstepA; const char* b2 = last ? nB : cB + (size_t)(t + 2) * kstep;
;             const char* a3 = a2 + kstepA; const char* b3 = b2 + kstep;
;             PG8_LDB(B0, 0, 0); PG8_SCHED; PG8_LDA(At, 0, 0); PG8_STAGE(PG8_SA(1, 1), a1 + hstepA, voffA);
;             PG8_WAIT_L(8); PG8_BAR; PG8_WAIT_L(0); PG8_MMA(0, 0, At, B0); PG8_BAR; PG8_SCHED;
;             PG8_LDB(B1, 0, 1); PG8_STAGE(PG8_SB(0, 0), b2, voffB);
;             PG8_BAR; PG8_WAIT_L(0); PG8_MMA(0, 1, At, B1); PG8_BAR;
;             PG8_LDA(At, 0, 1); PG8_STAGE(PG8_SA(0, 0), a2, voffA);
;             PG8_BAR; PG8_WAIT_L(0); PG8_MMA(1, 0, At, B0); PG8_BAR; PG8_SCHED;
.LBB0_1898:
	ds_read_b128 v[20:23], v180
	ds_read_b128 v[28:31], v180 offset:1024
	ds_read_b128 v[174:177], v180 offset:2048
	ds_read_b128 v[184:187], v180 offset:3072
	s_add_i32 s58, s26, 2
	s_add_u32 s27, s24, 0x4000
	s_addc_u32 s28, s25, 0
	s_cmp_eq_u32 s17, s26
	s_cselect_b32 s30, s20, s27
	s_cselect_b32 s31, s21, s28
	s_cselect_b32 s26, s22, s56
	s_cselect_b32 s27, s23, s57
	s_add_u32 s28, s30, 0x8000
	s_addc_u32 s29, s31, 0
	v_lshl_add_u64 v[178:179], s[24:25], 0, v[168:169]
	s_add_i32 m0, s34, 0xc000
	ds_read_b128 v[188:191], v181
	ds_read_b128 v[192:195], v181 offset:1024
	ds_read_b128 v[196:199], v181 offset:2048
	ds_read_b128 v[200:203], v181 offset:3072
	ds_read_b128 v[204:207], v181 offset:4096
	ds_read_b128 v[208:211], v181 offset:5120
	ds_read_b128 v[212:215], v181 offset:6144
	ds_read_b128 v[216:219], v181 offset:7168
	global_load_lds_dwordx4 v[178:179], off
	v_lshl_add_u64 v[178:179], s[24:25], 0, v[170:171]
	s_add_i32 m0, s34, 0xe000
	s_nop 0
	global_load_lds_dwordx4 v[178:179], off
	s_waitcnt lgkmcnt(8)
	s_setprio 1
	s_barrier
	s_waitcnt lgkmcnt(0)
	v_mfma_f32_16x16x32_bf16 v[0:3], v[20:23], v[188:191], v[0:3]
	v_mfma_f32_16x16x32_bf16 v[4:7], v[174:177], v[188:191], v[4:7]
	v_mfma_f32_16x16x32_bf16 v[44:47], v[20:23], v[196:199], v[44:47]
	v_mfma_f32_16x16x32_bf16 v[36:39], v[174:177], v[196:199], v[36:39]
	v_mfma_f32_16x16x32_bf16 v[52:55], v[20:23], v[204:207], v[52:55]
	v_mfma_f32_16x16x32_bf16 v[48:51], v[174:177], v[204:207], v[48:51]
	v_mfma_f32_16x16x32_bf16 v[92:95], v[20:23], v[212:215], v[92:95]
	v_mfma_f32_16x16x32_bf16 v[84:87], v[174:177], v[212:215], v[84:87]
	v_mfma_f32_16x16x32_bf16 v[0:3], v[28:31], v[192:195], v[0:3]
	v_mfma_f32_16x16x32_bf16 v[4:7], v[184:187], v[192:195], v[4:7]
	v_mfma_f32_16x16x32_bf16 v[44:47], v[28:31], v[200:203], v[44:47]
	v_mfma_f32_16x16x32_bf16 v[36:39], v[184:187], v[200:203], v[36:39]
	v_mfma_f32_16x16x32_bf16 v[52:55], v[28:31], v[208:211], v[52:55]
	v_mfma_f32_16x16x32_bf16 v[48:51], v[184:187], v[208:211], v[48:51]
	v_mfma_f32_16x16x32_bf16 v[92:95], v[28:31], v[216:219], v[92:95]
	v_mfma_f32_16x16x32_bf16 v[84:87], v[184:187], v[216:219], v[84:87]
	s_barrier
	s_setprio 0
	s_add_i32 s59, s44, s33
	v_lshl_add_u64 v[178:179], s[26:27], 0, v[138:139]
	s_mov_b32 m0, s59
	ds_read_b128 v[220:223], v182
	ds_read_b128 v[224:227], v182 offset:1024
	ds_read_b128 v[228:231], v182 offset:2048
	ds_read_b128 v[232:235], v182 offset:3072
	global_load_lds_dwordx4 v[178:179], off
	v_lshl_add_u64 v[236:237], s[26:27], 0, v[142:143]
	s_add_i32 m0, s59, 0x2000
	s_nop 0
	global_load_lds_dwordx4 v[236:237], off
	s_setprio 1
	s_barrier
	s_waitcnt lgkmcnt(0)
	v_mfma_f32_16x16x32_bf16 v[12:15], v[220:223], v[188:191], v[12:15]
	v_mfma_f32_16x16x32_bf16 v[8:11], v[228:231], v[188:191], v[8:11]
	v_mfma_f32_16x16x32_bf16 v[24:27], v[220:223], v[196:199], v[24:27]
	v_mfma_f32_16x16x32_bf16 v[16:19], v[228:231], v[196:199], v[16:19]
	v_mfma_f32_16x16x32_bf16 v[40:43], v[220:223], v[204:207], v[40:43]
	v_mfma_f32_16x16x32_bf16 v[32:35], v[228:231], v[204:207], v[32:35]
	v_mfma_f32_16x16x32_bf16 v[56:59], v[220:223], v[212:215], v[56:59]
	v_mfma_f32_16x16x32_bf16 v[60:63], v[228:231], v[212:215], v[60:63]
	v_mfma_f32_16x16x32_bf16 v[12:15], v[224:227], v[192:195], v[12:15]
	v_mfma_f32_16x16x32_bf16 v[8:11], v[232:235], v[192:195], v[8:11]
	v_mfma_f32_16x16x32_bf16 v[24:27], v[224:227], v[200:203], v[24:27]
	v_mfma_f32_16x16x32_bf16 v[16:19], v[232:235], v[200:203], v[16:19]
	v_mfma_f32_16x16x32_bf16 v[40:43], v[224:227], v[208:211], v[40:43]
	v_mfma_f32_16x16x32_bf16 v[32:35], v[232:235], v[208:211], v[32:35]
	v_mfma_f32_16x16x32_bf16 v[56:59], v[224:227], v[216:219], v[56:59]
	v_mfma_f32_16x16x32_bf16 v[60:63], v[232:235], v[216:219], v[60:63]
	s_barrier
	s_setprio 0
	s_mov_b32 m0, s34
	v_lshl_add_u64 v[238:239], s[30:31], 0, v[136:137]
	ds_read_b128 v[188:191], v181 offset:16384
	ds_read_b128 v[192:195], v181 offset:17408
	ds_read_b128 v[196:199], v181 offset:18432
	ds_read_b128 v[200:203], v181 offset:19456
	ds_read_b128 v[204:207], v181 offset:20480
	ds_read_b128 v[208:211], v181 offset:21504
	ds_read_b128 v[212:215], v181 offset:22528
	ds_read_b128 v[216:219], v181 offset:23552
	global_load_lds_dwordx4 v[238:239], off
	v_lshl_add_u64 v[238:239], s[30:31], 0, v[140:141]
	s_mov_b32 m0, s35
	s_nop 0
	global_load_lds_dwordx4 v[238:239], off
	s_setprio 1
	s_barrier
	s_waitcnt lgkmcnt(0)
	v_mfma_f32_16x16x32_bf16 v[64:67], v[20:23], v[188:191], v[64:67]
	v_mfma_f32_16x16x32_bf16 v[68:71], v[174:177], v[188:191], v[68:71]
	v_mfma_f32_16x16x32_bf16 v[108:111], v[20:23], v[196:199], v[108:111]
	v_mfma_f32_16x16x32_bf16 v[100:103], v[174:177], v[196:199], v[100:103]
	v_mfma_f32_16x16x32_bf16 v[116:119], v[20:23], v[204:207], v[116:119]
	v_mfma_f32_16x16x32_bf16 v[112:115], v[174:177], v[204:207], v[112:115]
	v_mfma_f32_16x16x32_bf16 v[20:23], v[20:23], v[212:215], v[132:135]
	v_mfma_f32_16x16x32_bf16 v[64:67], v[28:31], v[192:195], v[64:67]
	v_mfma_f32_16x16x32_bf16 v[68:71], v[184:187], v[192:195], v[68:71]
	v_mfma_f32_16x16x32_bf16 v[108:111], v[28:31], v[200:203], v[108:111]
	v_mfma_f32_16x16x32_bf16 v[100:103], v[184:187], v[200:203], v[100:103]
	v_mfma_f32_16x16x32_bf16 v[116:119], v[28:31], v[208:211], v[116:119]
	v_mfma_f32_16x16x32_bf16 v[112:115], v[184:187], v[208:211], v[112:115]
	v_mfma_f32_16x16x32_bf16 v[20:23], v[28:31], v[216:219], v[20:23]
	v_mfma_f32_16x16x32_bf16 v[28:31], v[174:177], v[212:215], v[128:131]
	v_mfma_f32_16x16x32_bf16 v[28:31], v[184:187], v[216:219], v[28:31]
	s_barrier
; #define PG8_STAGE(bufoff, gbase, voff) do { _Pragma("unroll") for (int _i = 0; _i < 2; ++_i) \
;         __builtin_amdgcn_global_load_lds((const unsigned*)((const char*)(gbase) + (voff)[_i]), (LAS unsigned*)(lds + (bufoff) + ldsw + _i * 8192), 16, 0, 0); } while (0)
; #define PG8_LDA(dst, b, h) do { _Pragma("unroll") for (int m = 0; m < 4; ++m) _Pragma("unroll") for (int k = 0; k < 2; ++k) dst[m][k] = *(const LAS bf16x8*)(lds + PG8_SA(b, h) + aoff + m * 2048 + k * 1024); } while (0)
; #define PG8_LDB(dst, b, h) do { _Pragma("unroll") for (int n = 0; n < 2; ++n) _Pragma("unroll") for (int k = 0; k < 2; ++k) dst[n][k] = *(const LAS bf16x8*)(lds + PG8_SB(b, h) + boff + n * 2048 + k * 1024); } while (0)
; #define PG8_MMA(ai, bj, At, Bt) do { __builtin_amdgcn_s_setprio(1); _Pragma("unroll") for (int m = 0; m < 4; ++m) _Pragma("unroll") for (int n = 0; n < 2; ++n) _Pragma("unroll") for (int k = 0; k < 2; ++k) \
;         acc[ai][bj][m][n] = __builtin_amdgcn_mfma_f32_16x16x32_bf16(Bt[n][k], At[m][k], acc[ai][bj][m][n], 0, 0, 0); __builtin_amdgcn_s_setprio(0); } while (0)
; #define PG8_WAIT_V(n) asm volatile("s_waitcnt vmcnt(" #n ")" ::: "memory")
; #define PG8_WAIT_L(n) asm volatile("s_waitcnt lgkmcnt(" #n ")" ::: "memory")
; #define PG8_BAR __builtin_amdgcn_s_barrier()
; #define PG8_SCHED __builtin_amdgcn_sched_barrier(0)
; template <class Epi, class Sched, bool ATILE = false>
; __device__ __forceinline__ void gemm_phase(LAS unsigned char* lds, const Gemm g, const Sched& S, const Epi& E) {
;     ...
;             PG8_STAGE(PG8_SB(0, 1), b2 + hstepB, voffB);
;             PG8_WAIT_V(6); PG8_BAR; PG8_MMA(1, 1, At, B1); PG8_BAR;
;             PG8_LDB(B0, 1, 0); PG8_SCHED; PG8_LDA(At, 1, 0); PG8_STAGE(PG8_SA(0, 1), a2 + hstepA, voffA);
;             PG8_WAIT_L(8); PG8_BAR; PG8_WAIT_L(0); PG8_MMA(0, 0, At, B0); PG8_BAR; PG8_SCHED;
;             PG8_LDB(B1, 1, 1); PG8_STAGE(PG8_SB(1, 0), b3, voffB);
;             PG8_BAR; PG8_WAIT_L(0); PG8_MMA(0, 1, At, B1); PG8_BAR;
;             PG8_LDA(At, 1, 1); PG8_STAGE(PG8_SA(1, 0), a3, voffA);
;             PG8_BAR; PG8_WAIT_L(0); PG8_MMA(1, 0, At, B0); PG8_BAR; PG8_SCHED;
;             PG8_STAGE(PG8_SB(1, 1), b3 + hstepB, voffB);
;             PG8_WAIT_V(6); PG8_BAR; PG8_MMA(1, 1, At, B1); PG8_BAR;
	s_setprio 0
	s_add_u32 s60, s26, 0x158000
	s_addc_u32 s61, s27, 0
	s_add_i32 s59, s45, s33
	v_lshl_add_u64 v[128:129], s[60:61], 0, v[138:139]
	s_mov_b32 m0, s59
	s_nop 0
	global_load_lds_dwordx4 v[128:129], off
	v_lshl_add_u64 v[128:129], s[60:61], 0, v[142:143]
	s_add_i32 m0, s59, 0x2000
	s_nop 0
	global_load_lds_dwordx4 v[128:129], off
	s_waitcnt vmcnt(6)
	s_setprio 1
	s_barrier
	v_mfma_f32_16x16x32_bf16 v[76:79], v[220:223], v[188:191], v[76:79]
	v_mfma_f32_16x16x32_bf16 v[72:75], v[228:231], v[188:191], v[72:75]
	v_mfma_f32_16x16x32_bf16 v[88:91], v[220:223], v[196:199], v[88:91]
	v_mfma_f32_16x16x32_bf16 v[80:83], v[228:231], v[196:199], v[80:83]
	v_mfma_f32_16x16x32_bf16 v[104:107], v[220:223], v[204:207], v[104:107]
	v_mfma_f32_16x16x32_bf16 v[96:99], v[228:231], v[204:207], v[96:99]
	v_mfma_f32_16x16x32_bf16 v[120:123], v[220:223], v[212:215], v[120:123]
	v_mfma_f32_16x16x32_bf16 v[124:127], v[228:231], v[212:215], v[124:127]
	v_mfma_f32_16x16x32_bf16 v[76:79], v[224:227], v[192:195], v[76:79]
	v_mfma_f32_16x16x32_bf16 v[72:75], v[232:235], v[192:195], v[72:75]
	v_mfma_f32_16x16x32_bf16 v[88:91], v[224:227], v[200:203], v[88:91]
	v_mfma_f32_16x16x32_bf16 v[80:83], v[232:235], v[200:203], v[80:83]
	v_mfma_f32_16x16x32_bf16 v[104:107], v[224:227], v[208:211], v[104:107]
	v_mfma_f32_16x16x32_bf16 v[96:99], v[232:235], v[208:211], v[96:99]
	v_mfma_f32_16x16x32_bf16 v[120:123], v[224:227], v[216:219], v[120:123]
	v_mfma_f32_16x16x32_bf16 v[124:127], v[232:235], v[216:219], v[124:127]
	s_barrier
	s_setprio 0
	s_add_i32 s59, 0, 0x18000
	v_add_u32_e32 v183, s59, v157
	ds_read_b128 v[128:131], v183
	ds_read_b128 v[132:135], v183 offset:1024
	ds_read_b128 v[174:177], v183 offset:2048
	ds_read_b128 v[184:187], v183 offset:3072
	s_add_u32 s30, s30, 0x4000
	s_addc_u32 s31, s31, 0
	s_mov_b32 m0, s36
	v_lshl_add_u64 v[220:221], s[30:31], 0, v[136:137]
	ds_read_b128 v[188:191], v181 offset:32768
	ds_read_b128 v[192:195], v181 offset:33792
	ds_read_b128 v[196:199], v181 offset:34816
	ds_read_b128 v[200:203], v181 offset:35840
	ds_read_b128 v[204:207], v181 offset:36864
	ds_read_b128 v[208:211], v181 offset:37888
	ds_read_b128 v[212:215], v181 offset:38912
	ds_read_b128 v[216:219], v181 offset:39936
	global_load_lds_dwordx4 v[220:221], off
	v_lshl_add_u64 v[220:221], s[30:31], 0, v[140:141]
	s_mov_b32 m0, s37
	s_nop 0
	global_load_lds_dwordx4 v[220:221], off
	s_waitcnt lgkmcnt(8)
	s_setprio 1
	s_barrier
	s_waitcnt lgkmcnt(0)
	v_mfma_f32_16x16x32_bf16 v[0:3], v[128:131], v[188:191], v[0:3]
	v_mfma_f32_16x16x32_bf16 v[4:7], v[174:177], v[188:191], v[4:7]
	v_mfma_f32_16x16x32_bf16 v[44:47], v[128:131], v[196:199], v[44:47]
	v_mfma_f32_16x16x32_bf16 v[36:39], v[174:177], v[196:199], v[36:39]
	v_mfma_f32_16x16x32_bf16 v[52:55], v[128:131], v[204:207], v[52:55]
	v_mfma_f32_16x16x32_bf16 v[48:51], v[174:177], v[204:207], v[48:51]
	v_mfma_f32_16x16x32_bf16 v[92:95], v[128:131], v[212:215], v[92:95]
	v_mfma_f32_16x16x32_bf16 v[84:87], v[174:177], v[212:215], v[84:87]
	v_mfma_f32_16x16x32_bf16 v[0:3], v[132:135], v[192:195], v[0:3]
	v_mfma_f32_16x16x32_bf16 v[4:7], v[184:187], v[192:195], v[4:7]
	v_mfma_f32_16x16x32_bf16 v[44:47], v[132:135], v[200:203], v[44:47]
	v_mfma_f32_16x16x32_bf16 v[36:39], v[184:187], v[200:203], v[36:39]
	v_mfma_f32_16x16x32_bf16 v[52:55], v[132:135], v[208:211], v[52:55]
	v_mfma_f32_16x16x32_bf16 v[48:51], v[184:187], v[208:211], v[48:51]
	v_mfma_f32_16x16x32_bf16 v[92:95], v[132:135], v[216:219], v[92:95]
	v_mfma_f32_16x16x32_bf16 v[84:87], v[184:187], v[216:219], v[84:87]
	s_barrier
	s_setprio 0
	s_add_i32 s30, 0, 0x1c000
	s_add_i32 s31, s59, s33
	v_add_u32_e32 v183, s30, v157
	v_lshl_add_u64 v[178:179], v[178:179], 0, s[4:5]
	s_mov_b32 m0, s31
	ds_read_b128 v[220:223], v183
	ds_read_b128 v[224:227], v183 offset:1024
	ds_read_b128 v[228:231], v183 offset:2048
	ds_read_b128 v[232:235], v183 offset:3072
	global_load_lds_dwordx4 v[178:179], off
	v_lshl_add_u64 v[178:179], v[236:237], 0, s[4:5]
	s_add_i32 m0, s31, 0x2000
	s_nop 0
	global_load_lds_dwordx4 v[178:179], off
	s_setprio 1
	s_barrier
	s_waitcnt lgkmcnt(0)
	v_mfma_f32_16x16x32_bf16 v[12:15], v[220:223], v[188:191], v[12:15]
	v_mfma_f32_16x16x32_bf16 v[8:11], v[228:231], v[188:191], v[8:11]
	v_mfma_f32_16x16x32_bf16 v[24:27], v[220:223], v[196:199], v[24:27]
	v_mfma_f32_16x16x32_bf16 v[16:19], v[228:231], v[196:199], v[16:19]
	v_mfma_f32_16x16x32_bf16 v[40:43], v[220:223], v[204:207], v[40:43]
	v_mfma_f32_16x16x32_bf16 v[32:35], v[228:231], v[204:207], v[32:35]
	v_mfma_f32_16x16x32_bf16 v[56:59], v[220:223], v[212:215], v[56:59]
	v_mfma_f32_16x16x32_bf16 v[60:63], v[228:231], v[212:215], v[60:63]
	v_mfma_f32_16x16x32_bf16 v[12:15], v[224:227], v[192:195], v[12:15]
	v_mfma_f32_16x16x32_bf16 v[8:11], v[232:235], v[192:195], v[8:11]
	v_mfma_f32_16x16x32_bf16 v[24:27], v[224:227], v[200:203], v[24:27]
	v_mfma_f32_16x16x32_bf16 v[16:19], v[232:235], v[200:203], v[16:19]
	v_mfma_f32_16x16x32_bf16 v[40:43], v[224:227], v[208:211], v[40:43]
	v_mfma_f32_16x16x32_bf16 v[32:35], v[232:235], v[208:211], v[32:35]
	v_mfma_f32_16x16x32_bf16 v[56:59], v[224:227], v[216:219], v[56:59]
	v_mfma_f32_16x16x32_bf16 v[60:63], v[232:235], v[216:219], v[60:63]
	s_barrier
	s_setprio 0
	s_mov_b32 m0, s39
	v_lshl_add_u64 v[178:179], s[28:29], 0, v[136:137]
	ds_read_b128 v[188:191], v181 offset:49152
	ds_read_b128 v[192:195], v181 offset:50176
	ds_read_b128 v[196:199], v181 offset:51200
	ds_read_b128 v[200:203], v181 offset:52224
	ds_read_b128 v[204:207], v181 offset:53248
	ds_read_b128 v[208:211], v181 offset:54272
	ds_read_b128 v[212:215], v181 offset:55296
	ds_read_b128 v[216:219], v181 offset:56320
	global_load_lds_dwordx4 v[178:179], off
	v_lshl_add_u64 v[178:179], s[28:29], 0, v[140:141]
	s_mov_b32 m0, s40
	s_nop 0
	global_load_lds_dwordx4 v[178:179], off
	s_setprio 1
	s_barrier
; __device__ __forceinline__ float bflo(unsigned w) { return __uint_as_float(w << 16); }
; __device__ __forceinline__ float bfhi(unsigned w) { return __uint_as_float(w & 0xffff0000u); }
; #define PG8_STAGE(bufoff, gbase, voff) do { _Pragma("unroll") for (int _i = 0; _i < 2; ++_i) \
;         __builtin_amdgcn_global_load_lds((const unsigned*)((const char*)(gbase) + (voff)[_i]), (LAS unsigned*)(lds + (bufoff) + ldsw + _i * 8192), 16, 0, 0); } while (0)
; #define PG8_LDA(dst, b, h) do { _Pragma("unroll") for (int m = 0; m < 4; ++m) _Pragma("unroll") for (int k = 0; k < 2; ++k) dst[m][k] = *(const LAS bf16x8*)(lds + PG8_SA(b, h) + aoff + m * 2048 + k * 1024); } while (0)
; #define PG8_MMA(ai, bj, At, Bt) do { __builtin_amdgcn_s_setprio(1); _Pragma("unroll") for (int m = 0; m < 4; ++m) _Pragma("unroll") for (int n = 0; n < 2; ++n) _Pragma("unroll") for (int k = 0; k < 2; ++k) \
;         acc[ai][bj][m][n] = __builtin_amdgcn_mfma_f32_16x16x32_bf16(Bt[n][k], At[m][k], acc[ai][bj][m][n], 0, 0, 0); __builtin_amdgcn_s_setprio(0); } while (0)
; #define PG8_WAIT_V(n) asm volatile("s_waitcnt vmcnt(" #n ")" ::: "memory")
; #define PG8_WAIT_L(n) asm volatile("s_waitcnt lgkmcnt(" #n ")" ::: "memory")
; #define PG8_BAR __builtin_amdgcn_s_barrier()
; #define PG8_SCHED __builtin_amdgcn_sched_barrier(0)
; template <class Epi, class Sched, bool ATILE = false>
; __device__ __forceinline__ void gemm_phase(LAS unsigned char* lds, const Gemm g, const Sched& S, const Epi& E) {
;     ...
;             PG8_BAR; PG8_WAIT_L(0); PG8_MMA(0, 1, At, B1); PG8_BAR;
;             PG8_LDA(At, 1, 1); PG8_STAGE(PG8_SA(1, 0), a3, voffA);
;             PG8_BAR; PG8_WAIT_L(0); PG8_MMA(1, 0, At, B0); PG8_BAR; PG8_SCHED;
;             PG8_STAGE(PG8_SB(1, 1), b3 + hstepB, voffB);
;             PG8_WAIT_V(6); PG8_BAR; PG8_MMA(1, 1, At, B1); PG8_BAR;
;     __device__ __forceinline__ void operator()(const f32x4 (&acc)[2][2][4][2], const Unit& u, int wr, int wc, int fr, int fq) const {
;     ...
;                     const f32x4 v0 = (f32x4){bflo(x.x), bfhi(x.x), bflo(x.y), bfhi(x.y)} + alpha * acc[ai][bj][m][0];
;                     const f32x4 v1 = (f32x4){bflo(x.z), bfhi(x.z), bflo(x.w), bfhi(x.w)} + alpha * acc[ai][bj][m][1];
	s_waitcnt lgkmcnt(0)
	v_mfma_f32_16x16x32_bf16 v[64:67], v[128:131], v[188:191], v[64:67]
	v_mfma_f32_16x16x32_bf16 v[108:111], v[128:131], v[196:199], v[108:111]
	v_mfma_f32_16x16x32_bf16 v[116:119], v[128:131], v[204:207], v[116:119]
	v_mfma_f32_16x16x32_bf16 v[20:23], v[128:131], v[212:215], v[20:23]
	v_mfma_f32_16x16x32_bf16 v[64:67], v[132:135], v[192:195], v[64:67]
	v_mfma_f32_16x16x32_bf16 v[68:71], v[174:177], v[188:191], v[68:71]
	v_mfma_f32_16x16x32_bf16 v[108:111], v[132:135], v[200:203], v[108:111]
	v_mfma_f32_16x16x32_bf16 v[100:103], v[174:177], v[196:199], v[100:103]
	v_mfma_f32_16x16x32_bf16 v[116:119], v[132:135], v[208:211], v[116:119]
	v_mfma_f32_16x16x32_bf16 v[112:115], v[174:177], v[204:207], v[112:115]
	v_mfma_f32_16x16x32_bf16 v[132:135], v[132:135], v[216:219], v[20:23]
	v_mfma_f32_16x16x32_bf16 v[20:23], v[174:177], v[212:215], v[28:31]
	v_mfma_f32_16x16x32_bf16 v[68:71], v[184:187], v[192:195], v[68:71]
	v_mfma_f32_16x16x32_bf16 v[100:103], v[184:187], v[200:203], v[100:103]
	v_mfma_f32_16x16x32_bf16 v[112:115], v[184:187], v[208:211], v[112:115]
	v_mfma_f32_16x16x32_bf16 v[128:131], v[184:187], v[216:219], v[20:23]
	s_barrier
	s_setprio 0
	s_add_u32 s26, s26, 0x158080
	s_addc_u32 s27, s27, 0
	s_add_i32 s28, s30, s33
	v_lshl_add_u64 v[20:21], s[26:27], 0, v[138:139]
	s_mov_b32 m0, s28
	s_nop 0
	global_load_lds_dwordx4 v[20:21], off
	v_lshl_add_u64 v[20:21], s[26:27], 0, v[142:143]
	s_add_i32 m0, s28, 0x2000
	s_nop 0
	global_load_lds_dwordx4 v[20:21], off
	s_waitcnt vmcnt(6)
	s_setprio 1
	s_barrier
	v_mfma_f32_16x16x32_bf16 v[20:23], v[220:223], v[188:191], v[76:79]
	v_mfma_f32_16x16x32_bf16 v[76:79], v[224:227], v[192:195], v[20:23]
	v_mfma_f32_16x16x32_bf16 v[20:23], v[228:231], v[188:191], v[72:75]
	v_mfma_f32_16x16x32_bf16 v[72:75], v[232:235], v[192:195], v[20:23]
	v_mfma_f32_16x16x32_bf16 v[20:23], v[220:223], v[196:199], v[88:91]
	v_mfma_f32_16x16x32_bf16 v[88:91], v[224:227], v[200:203], v[20:23]
	v_mfma_f32_16x16x32_bf16 v[20:23], v[228:231], v[196:199], v[80:83]
	v_mfma_f32_16x16x32_bf16 v[80:83], v[232:235], v[200:203], v[20:23]
	v_mfma_f32_16x16x32_bf16 v[20:23], v[220:223], v[204:207], v[104:107]
	v_mfma_f32_16x16x32_bf16 v[104:107], v[224:227], v[208:211], v[20:23]
	v_mfma_f32_16x16x32_bf16 v[20:23], v[228:231], v[204:207], v[96:99]
	v_mfma_f32_16x16x32_bf16 v[96:99], v[232:235], v[208:211], v[20:23]
	v_mfma_f32_16x16x32_bf16 v[20:23], v[220:223], v[212:215], v[120:123]
	v_mfma_f32_16x16x32_bf16 v[120:123], v[224:227], v[216:219], v[20:23]
	v_mfma_f32_16x16x32_bf16 v[20:23], v[228:231], v[212:215], v[124:127]
	v_mfma_f32_16x16x32_bf16 v[124:127], v[232:235], v[216:219], v[20:23]
	s_barrier
	s_setprio 0
	s_add_u32 s56, s56, 0x100
	s_addc_u32 s57, s57, 0
	s_add_u32 s24, s24, 0x10000
	s_addc_u32 s25, s25, 0
	s_cmp_ge_i32 s58, s55
	s_mov_b32 s26, s58
	s_cbranch_scc0 .LBB0_1898
	v_pk_mul_f32 v[2:3], v[2:3], 0.5 op_sel_hi:[1,0]
	v_pk_mul_f32 v[0:1], v[0:1], 0.5 op_sel_hi:[1,0]
	v_pk_mul_f32 v[6:7], v[6:7], 0.5 op_sel_hi:[1,0]
	v_pk_mul_f32 v[4:5], v[4:5], 0.5 op_sel_hi:[1,0]
	v_pk_mul_f32 v[22:23], v[14:15], 0.5 op_sel_hi:[1,0]
	v_pk_mul_f32 v[20:21], v[12:13], 0.5 op_sel_hi:[1,0]
	v_pk_mul_f32 v[30:31], v[10:11], 0.5 op_sel_hi:[1,0]
	v_pk_mul_f32 v[28:29], v[8:9], 0.5 op_sel_hi:[1,0]
	v_pk_mul_f32 v[10:11], v[46:47], 0.5 op_sel_hi:[1,0]
	v_pk_mul_f32 v[8:9], v[44:45], 0.5 op_sel_hi:[1,0]
	v_pk_mul_f32 v[14:15], v[38:39], 0.5 op_sel_hi:[1,0]
	v_pk_mul_f32 v[12:13], v[36:37], 0.5 op_sel_hi:[1,0]
	v_pk_mul_f32 v[38:39], v[26:27], 0.5 op_sel_hi:[1,0]
	v_pk_mul_f32 v[36:37], v[24:25], 0.5 op_sel_hi:[1,0]
	v_pk_mul_f32 v[46:47], v[18:19], 0.5 op_sel_hi:[1,0]
	v_pk_mul_f32 v[44:45], v[16:17], 0.5 op_sel_hi:[1,0]
	v_pk_mul_f32 v[18:19], v[54:55], 0.5 op_sel_hi:[1,0]
	v_pk_mul_f32 v[16:17], v[52:53], 0.5 op_sel_hi:[1,0]
	v_pk_mul_f32 v[26:27], v[50:51], 0.5 op_sel_hi:[1,0]
	v_pk_mul_f32 v[24:25], v[48:49], 0.5 op_sel_hi:[1,0]
	v_pk_mul_f32 v[50:51], v[42:43], 0.5 op_sel_hi:[1,0]
	v_pk_mul_f32 v[48:49], v[40:41], 0.5 op_sel_hi:[1,0]
	v_pk_mul_f32 v[54:55], v[34:35], 0.5 op_sel_hi:[1,0]
	v_pk_mul_f32 v[52:53], v[32:33], 0.5 op_sel_hi:[1,0]
	v_pk_mul_f32 v[34:35], v[94:95], 0.5 op_sel_hi:[1,0]
	v_pk_mul_f32 v[32:33], v[92:93], 0.5 op_sel_hi:[1,0]
	v_pk_mul_f32 v[42:43], v[86:87], 0.5 op_sel_hi:[1,0]
	v_pk_mul_f32 v[40:41], v[84:85], 0.5 op_sel_hi:[1,0]
	v_pk_mul_f32 v[58:59], v[58:59], 0.5 op_sel_hi:[1,0]
	v_pk_mul_f32 v[56:57], v[56:57], 0.5 op_sel_hi:[1,0]
	v_pk_mul_f32 v[62:63], v[62:63], 0.5 op_sel_hi:[1,0]
	v_pk_mul_f32 v[60:61], v[60:61], 0.5 op_sel_hi:[1,0]
	v_pk_mul_f32 v[66:67], v[66:67], 0.5 op_sel_hi:[1,0]
	v_pk_mul_f32 v[64:65], v[64:65], 0.5 op_sel_hi:[1,0]
	v_pk_mul_f32 v[70:71], v[70:71], 0.5 op_sel_hi:[1,0]
	v_pk_mul_f32 v[68:69], v[68:69], 0.5 op_sel_hi:[1,0]
	v_pk_mul_f32 v[86:87], v[78:79], 0.5 op_sel_hi:[1,0]
	v_pk_mul_f32 v[84:85], v[76:77], 0.5 op_sel_hi:[1,0]
	v_pk_mul_f32 v[94:95], v[74:75], 0.5 op_sel_hi:[1,0]
	v_pk_mul_f32 v[92:93], v[72:73], 0.5 op_sel_hi:[1,0]
	v_pk_mul_f32 v[74:75], v[110:111], 0.5 op_sel_hi:[1,0]
	v_pk_mul_f32 v[72:73], v[108:109], 0.5 op_sel_hi:[1,0]
	v_pk_mul_f32 v[78:79], v[102:103], 0.5 op_sel_hi:[1,0]
	v_pk_mul_f32 v[76:77], v[100:101], 0.5 op_sel_hi:[1,0]
	v_pk_mul_f32 v[102:103], v[90:91], 0.5 op_sel_hi:[1,0]
	v_pk_mul_f32 v[100:101], v[88:89], 0.5 op_sel_hi:[1,0]
	v_pk_mul_f32 v[110:111], v[82:83], 0.5 op_sel_hi:[1,0]
	v_pk_mul_f32 v[108:109], v[80:81], 0.5 op_sel_hi:[1,0]
	v_pk_mul_f32 v[82:83], v[118:119], 0.5 op_sel_hi:[1,0]
	v_pk_mul_f32 v[80:81], v[116:117], 0.5 op_sel_hi:[1,0]
	v_pk_mul_f32 v[90:91], v[114:115], 0.5 op_sel_hi:[1,0]
	v_pk_mul_f32 v[88:89], v[112:113], 0.5 op_sel_hi:[1,0]
	v_pk_mul_f32 v[114:115], v[106:107], 0.5 op_sel_hi:[1,0]
	v_pk_mul_f32 v[112:113], v[104:105], 0.5 op_sel_hi:[1,0]
	v_pk_mul_f32 v[118:119], v[98:99], 0.5 op_sel_hi:[1,0]
	v_pk_mul_f32 v[116:117], v[96:97], 0.5 op_sel_hi:[1,0]
	v_pk_mul_f32 v[98:99], v[134:135], 0.5 op_sel_hi:[1,0]
	v_pk_mul_f32 v[96:97], v[132:133], 0.5 op_sel_hi:[1,0]
	v_pk_mul_f32 v[106:107], v[130:131], 0.5 op_sel_hi:[1,0]
	v_pk_mul_f32 v[104:105], v[128:129], 0.5 op_sel_hi:[1,0]
	v_pk_mul_f32 v[122:123], v[122:123], 0.5 op_sel_hi:[1,0]
	v_pk_mul_f32 v[120:121], v[120:121], 0.5 op_sel_hi:[1,0]
	v_pk_mul_f32 v[126:127], v[126:127], 0.5 op_sel_hi:[1,0]
	v_pk_mul_f32 v[124:125], v[124:125], 0.5 op_sel_hi:[1,0]
	s_branch .LBB0_1903
